# peeled first K-iteration of every GEMM tile (srcC=0), removes 128 v_mov accumulator zeroing per tile
# speedup vs baseline: 1.0029x; 1.0029x over previous
.LBB0_490:
	s_ashr_i32 s11, s10, 31
	s_lshl_b64 s[12:13], s[10:11], 20
	v_readlane_b32 s14, v253, 25
	v_readlane_b32 s15, v253, 26
	s_add_u32 s12, s14, s12
	s_addc_u32 s13, s15, s13
	s_and_b64 s[14:15], s[34:35], exec
	s_cselect_b32 s11, s13, s17
	s_cselect_b32 s49, s12, s16
	s_ashr_i32 s9, s8, 31
	s_lshl_b64 s[14:15], s[8:9], 20
	s_add_u32 s14, s25, s14
	s_addc_u32 s15, s36, s15
	s_and_b64 s[20:21], s[34:35], exec
	s_cselect_b32 s9, s15, s19
	s_cselect_b32 s50, s14, s18
	s_add_u32 s16, s16, 0x80080
	s_addc_u32 s17, s17, 0
	s_add_u32 s51, s18, 0x100
	s_addc_u32 s52, s19, 0
	s_mov_b32 s53, -2
	s_add_u32 s18, s16, 0xfff80080
	s_addc_u32 s19, s17, -1
	s_add_i32 s54, 0, 0x10000
	s_cmp_eq_u32 s53, 28
	s_cselect_b32 s21, s11, s19
	s_cselect_b32 s20, s49, s18
	s_cselect_b32 s19, s9, s52
	s_cselect_b32 s18, s50, s51
	s_add_i32 s56, 0, 0x14000
	v_add_u32_e32 v156, s54, v141
	v_add_u32_e32 v172, s56, v141
	ds_read_b128 v[144:147], v156
	ds_read_b128 v[148:151], v156 offset:1024
	ds_read_b128 v[152:155], v156 offset:2048
	ds_read_b128 v[156:159], v156 offset:3072
	ds_read_b128 v[160:163], v172
	ds_read_b128 v[164:167], v172 offset:1024
	ds_read_b128 v[168:171], v172 offset:2048
	ds_read_b128 v[172:175], v172 offset:3072
	v_lshl_add_u64 v[208:209], s[16:17], 0, v[136:137]
	s_add_i32 m0, s39, 0xc000
	ds_read_b128 v[176:179], v143
	ds_read_b128 v[180:183], v143 offset:1024
	ds_read_b128 v[184:187], v143 offset:2048
	ds_read_b128 v[188:191], v143 offset:3072
	ds_read_b128 v[192:195], v143 offset:4096
	ds_read_b128 v[196:199], v143 offset:5120
	ds_read_b128 v[200:203], v143 offset:6144
	ds_read_b128 v[204:207], v143 offset:7168
	global_load_lds_dwordx4 v[208:209], off
	v_lshl_add_u64 v[208:209], s[16:17], 0, v[138:139]
	s_add_i32 m0, s39, 0xe000
	s_nop 0
	global_load_lds_dwordx4 v[208:209], off
	s_waitcnt vmcnt(8)
	s_waitcnt lgkmcnt(0)
	s_barrier
	s_setprio 1
	s_waitcnt lgkmcnt(0)
	v_mfma_f32_16x16x32_bf16 v[126:129], v[144:147], v[176:179], 0
	v_mfma_f32_16x16x32_bf16 v[122:125], v[152:155], v[176:179], 0
	v_mfma_f32_16x16x32_bf16 v[118:121], v[144:147], v[184:187], 0
	v_mfma_f32_16x16x32_bf16 v[114:117], v[152:155], v[184:187], 0
	v_mfma_f32_16x16x32_bf16 v[102:105], v[144:147], v[192:195], 0
	v_mfma_f32_16x16x32_bf16 v[98:101], v[152:155], v[192:195], 0
	v_mfma_f32_16x16x32_bf16 v[86:89], v[144:147], v[200:203], 0
	v_mfma_f32_16x16x32_bf16 v[82:85], v[152:155], v[200:203], 0
	v_mfma_f32_16x16x32_bf16 v[126:129], v[148:151], v[180:183], v[126:129]
	v_mfma_f32_16x16x32_bf16 v[122:125], v[156:159], v[180:183], v[122:125]
	v_mfma_f32_16x16x32_bf16 v[118:121], v[148:151], v[188:191], v[118:121]
	v_mfma_f32_16x16x32_bf16 v[114:117], v[156:159], v[188:191], v[114:117]
	v_mfma_f32_16x16x32_bf16 v[102:105], v[148:151], v[196:199], v[102:105]
	v_mfma_f32_16x16x32_bf16 v[98:101], v[156:159], v[196:199], v[98:101]
	v_mfma_f32_16x16x32_bf16 v[86:89], v[148:151], v[204:207], v[86:89]
	v_mfma_f32_16x16x32_bf16 v[82:85], v[156:159], v[204:207], v[82:85]
	s_setprio 0
	s_setprio 1
	v_mfma_f32_16x16x32_bf16 v[110:113], v[160:163], v[176:179], 0
	v_mfma_f32_16x16x32_bf16 v[106:109], v[168:171], v[176:179], 0
	v_mfma_f32_16x16x32_bf16 v[94:97], v[160:163], v[184:187], 0
	v_mfma_f32_16x16x32_bf16 v[90:93], v[168:171], v[184:187], 0
	v_mfma_f32_16x16x32_bf16 v[78:81], v[160:163], v[192:195], 0
	v_mfma_f32_16x16x32_bf16 v[74:77], v[168:171], v[192:195], 0
	v_mfma_f32_16x16x32_bf16 v[70:73], v[160:163], v[200:203], 0
	v_mfma_f32_16x16x32_bf16 v[66:69], v[168:171], v[200:203], 0
	v_mfma_f32_16x16x32_bf16 v[110:113], v[164:167], v[180:183], v[110:113]
	v_mfma_f32_16x16x32_bf16 v[106:109], v[172:175], v[180:183], v[106:109]
	v_mfma_f32_16x16x32_bf16 v[94:97], v[164:167], v[188:191], v[94:97]
	v_mfma_f32_16x16x32_bf16 v[90:93], v[172:175], v[188:191], v[90:93]
	v_mfma_f32_16x16x32_bf16 v[78:81], v[164:167], v[196:199], v[78:81]
	v_mfma_f32_16x16x32_bf16 v[74:77], v[172:175], v[196:199], v[74:77]
	v_mfma_f32_16x16x32_bf16 v[70:73], v[164:167], v[204:207], v[70:73]
	v_mfma_f32_16x16x32_bf16 v[66:69], v[172:175], v[204:207], v[66:69]
	s_setprio 0
	s_barrier
	s_add_i32 s54, s54, s37
	v_lshl_add_u64 v[208:209], s[18:19], 0, v[0:1]
	s_mov_b32 m0, s54
	ds_read_b128 v[176:179], v143 offset:16384
	ds_read_b128 v[180:183], v143 offset:17408
	ds_read_b128 v[184:187], v143 offset:18432
	ds_read_b128 v[188:191], v143 offset:19456
	ds_read_b128 v[192:195], v143 offset:20480
	ds_read_b128 v[196:199], v143 offset:21504
	ds_read_b128 v[200:203], v143 offset:22528
	ds_read_b128 v[204:207], v143 offset:23552
	global_load_lds_dwordx4 v[208:209], off
	s_add_i32 m0, s54, 0x2000
	s_add_u32 s54, s18, 0x80000
	v_lshl_add_u64 v[220:221], s[18:19], 0, v[130:131]
	s_addc_u32 s55, s19, 0
	s_add_i32 s56, s56, s37
	global_load_lds_dwordx4 v[220:221], off
	v_lshl_add_u64 v[222:223], s[54:55], 0, v[0:1]
	s_mov_b32 m0, s56
	v_lshl_add_u64 v[224:225], s[20:21], 0, v[132:133]
	global_load_lds_dwordx4 v[222:223], off
	v_lshl_add_u64 v[222:223], s[54:55], 0, v[130:131]
	s_add_i32 m0, s56, 0x2000
	s_nop 0
	global_load_lds_dwordx4 v[222:223], off
	v_lshl_add_u64 v[222:223], s[20:21], 0, v[134:135]
	s_mov_b32 m0, s39
	s_nop 0
	global_load_lds_dwordx4 v[222:223], off
	s_mov_b32 m0, s40
	s_nop 0
	global_load_lds_dwordx4 v[224:225], off
	s_waitcnt vmcnt(8)
	s_waitcnt lgkmcnt(0)
	s_barrier
	s_setprio 1
	s_waitcnt lgkmcnt(0)
	v_mfma_f32_16x16x32_bf16 v[62:65], v[144:147], v[176:179], 0
	v_mfma_f32_16x16x32_bf16 v[58:61], v[152:155], v[176:179], 0
	v_mfma_f32_16x16x32_bf16 v[54:57], v[144:147], v[184:187], 0
	v_mfma_f32_16x16x32_bf16 v[50:53], v[152:155], v[184:187], 0
	v_mfma_f32_16x16x32_bf16 v[38:41], v[144:147], v[192:195], 0
	v_mfma_f32_16x16x32_bf16 v[34:37], v[152:155], v[192:195], 0
	v_mfma_f32_16x16x32_bf16 v[22:25], v[144:147], v[200:203], 0
	v_mfma_f32_16x16x32_bf16 v[18:21], v[152:155], v[200:203], 0
	v_mfma_f32_16x16x32_bf16 v[62:65], v[148:151], v[180:183], v[62:65]
	v_mfma_f32_16x16x32_bf16 v[58:61], v[156:159], v[180:183], v[58:61]
	v_mfma_f32_16x16x32_bf16 v[54:57], v[148:151], v[188:191], v[54:57]
	v_mfma_f32_16x16x32_bf16 v[50:53], v[156:159], v[188:191], v[50:53]
	v_mfma_f32_16x16x32_bf16 v[38:41], v[148:151], v[196:199], v[38:41]
	v_mfma_f32_16x16x32_bf16 v[34:37], v[156:159], v[196:199], v[34:37]
	v_mfma_f32_16x16x32_bf16 v[22:25], v[148:151], v[204:207], v[22:25]
	v_mfma_f32_16x16x32_bf16 v[18:21], v[156:159], v[204:207], v[18:21]
	s_setprio 0
	s_setprio 1
	v_mfma_f32_16x16x32_bf16 v[46:49], v[160:163], v[176:179], 0
	v_mfma_f32_16x16x32_bf16 v[42:45], v[168:171], v[176:179], 0
	v_mfma_f32_16x16x32_bf16 v[30:33], v[160:163], v[184:187], 0
	v_mfma_f32_16x16x32_bf16 v[26:29], v[168:171], v[184:187], 0
	v_mfma_f32_16x16x32_bf16 v[14:17], v[160:163], v[192:195], 0
	v_mfma_f32_16x16x32_bf16 v[10:13], v[168:171], v[192:195], 0
	v_mfma_f32_16x16x32_bf16 v[6:9], v[160:163], v[200:203], 0
	v_mfma_f32_16x16x32_bf16 v[2:5], v[168:171], v[200:203], 0
	v_mfma_f32_16x16x32_bf16 v[46:49], v[164:167], v[180:183], v[46:49]
	v_mfma_f32_16x16x32_bf16 v[42:45], v[172:175], v[180:183], v[42:45]
	v_mfma_f32_16x16x32_bf16 v[30:33], v[164:167], v[188:191], v[30:33]
	v_mfma_f32_16x16x32_bf16 v[26:29], v[172:175], v[188:191], v[26:29]
	v_mfma_f32_16x16x32_bf16 v[14:17], v[164:167], v[196:199], v[14:17]
	v_mfma_f32_16x16x32_bf16 v[10:13], v[172:175], v[196:199], v[10:13]
	v_mfma_f32_16x16x32_bf16 v[6:9], v[164:167], v[204:207], v[6:9]
	v_mfma_f32_16x16x32_bf16 v[2:5], v[172:175], v[204:207], v[2:5]
	s_setprio 0
	s_barrier
	s_add_i32 s54, 0, 0x18000
	s_add_i32 s55, 0, 0x1c000
	v_add_u32_e32 v156, s54, v141
	v_add_u32_e32 v172, s55, v141
	ds_read_b128 v[144:147], v156
	ds_read_b128 v[148:151], v156 offset:1024
	ds_read_b128 v[152:155], v156 offset:2048
	ds_read_b128 v[156:159], v156 offset:3072
	ds_read_b128 v[160:163], v172
	ds_read_b128 v[164:167], v172 offset:1024
	ds_read_b128 v[168:171], v172 offset:2048
	ds_read_b128 v[172:175], v172 offset:3072
	s_add_u32 s20, s20, 0x80000
	s_addc_u32 s21, s21, 0
	s_mov_b32 m0, s41
	v_lshl_add_u64 v[226:227], s[20:21], 0, v[134:135]
	ds_read_b128 v[176:179], v143 offset:32768
	ds_read_b128 v[180:183], v143 offset:33792
	ds_read_b128 v[184:187], v143 offset:34816
	ds_read_b128 v[188:191], v143 offset:35840
	ds_read_b128 v[192:195], v143 offset:36864
	ds_read_b128 v[196:199], v143 offset:37888
	ds_read_b128 v[200:203], v143 offset:38912
	ds_read_b128 v[204:207], v143 offset:39936
	global_load_lds_dwordx4 v[226:227], off
	v_lshl_add_u64 v[226:227], s[20:21], 0, v[132:133]
	s_mov_b32 m0, s44
	s_nop 0
	global_load_lds_dwordx4 v[226:227], off
	s_waitcnt vmcnt(8)
	s_waitcnt lgkmcnt(0)
	s_barrier
	s_setprio 1
	s_waitcnt lgkmcnt(0)
	v_mfma_f32_16x16x32_bf16 v[126:129], v[144:147], v[176:179], v[126:129]
	v_mfma_f32_16x16x32_bf16 v[122:125], v[152:155], v[176:179], v[122:125]
	v_mfma_f32_16x16x32_bf16 v[118:121], v[144:147], v[184:187], v[118:121]
	v_mfma_f32_16x16x32_bf16 v[114:117], v[152:155], v[184:187], v[114:117]
	v_mfma_f32_16x16x32_bf16 v[102:105], v[144:147], v[192:195], v[102:105]
	v_mfma_f32_16x16x32_bf16 v[98:101], v[152:155], v[192:195], v[98:101]
	v_mfma_f32_16x16x32_bf16 v[86:89], v[144:147], v[200:203], v[86:89]
	v_mfma_f32_16x16x32_bf16 v[82:85], v[152:155], v[200:203], v[82:85]
	v_mfma_f32_16x16x32_bf16 v[126:129], v[148:151], v[180:183], v[126:129]
	v_mfma_f32_16x16x32_bf16 v[122:125], v[156:159], v[180:183], v[122:125]
	v_mfma_f32_16x16x32_bf16 v[118:121], v[148:151], v[188:191], v[118:121]
	v_mfma_f32_16x16x32_bf16 v[114:117], v[156:159], v[188:191], v[114:117]
	v_mfma_f32_16x16x32_bf16 v[102:105], v[148:151], v[196:199], v[102:105]
	v_mfma_f32_16x16x32_bf16 v[98:101], v[156:159], v[196:199], v[98:101]
	v_mfma_f32_16x16x32_bf16 v[86:89], v[148:151], v[204:207], v[86:89]
	v_mfma_f32_16x16x32_bf16 v[82:85], v[156:159], v[204:207], v[82:85]
	s_setprio 0
	s_setprio 1
	v_mfma_f32_16x16x32_bf16 v[110:113], v[160:163], v[176:179], v[110:113]
	v_mfma_f32_16x16x32_bf16 v[106:109], v[168:171], v[176:179], v[106:109]
	v_mfma_f32_16x16x32_bf16 v[94:97], v[160:163], v[184:187], v[94:97]
	v_mfma_f32_16x16x32_bf16 v[90:93], v[168:171], v[184:187], v[90:93]
	v_mfma_f32_16x16x32_bf16 v[78:81], v[160:163], v[192:195], v[78:81]
	v_mfma_f32_16x16x32_bf16 v[74:77], v[168:171], v[192:195], v[74:77]
	v_mfma_f32_16x16x32_bf16 v[70:73], v[160:163], v[200:203], v[70:73]
	v_mfma_f32_16x16x32_bf16 v[66:69], v[168:171], v[200:203], v[66:69]
	v_mfma_f32_16x16x32_bf16 v[110:113], v[164:167], v[180:183], v[110:113]
	v_mfma_f32_16x16x32_bf16 v[106:109], v[172:175], v[180:183], v[106:109]
	v_mfma_f32_16x16x32_bf16 v[94:97], v[164:167], v[188:191], v[94:97]
	v_mfma_f32_16x16x32_bf16 v[90:93], v[172:175], v[188:191], v[90:93]
	v_mfma_f32_16x16x32_bf16 v[78:81], v[164:167], v[196:199], v[78:81]
	v_mfma_f32_16x16x32_bf16 v[74:77], v[172:175], v[196:199], v[74:77]
	v_mfma_f32_16x16x32_bf16 v[70:73], v[164:167], v[204:207], v[70:73]
	v_mfma_f32_16x16x32_bf16 v[66:69], v[172:175], v[204:207], v[66:69]
	s_setprio 0
	s_barrier
	s_add_i32 s20, s54, s37
	v_lshl_add_u64 v[208:209], v[208:209], 0, s[2:3]
	s_mov_b32 m0, s20
	ds_read_b128 v[176:179], v143 offset:49152
	ds_read_b128 v[180:183], v143 offset:50176
	ds_read_b128 v[184:187], v143 offset:51200
	ds_read_b128 v[188:191], v143 offset:52224
	ds_read_b128 v[192:195], v143 offset:53248
	ds_read_b128 v[196:199], v143 offset:54272
	ds_read_b128 v[200:203], v143 offset:55296
	ds_read_b128 v[204:207], v143 offset:56320
	global_load_lds_dwordx4 v[208:209], off
	s_add_i32 m0, s20, 0x2000
	s_add_u32 s18, s18, 0x80080
	v_lshl_add_u64 v[208:209], v[220:221], 0, s[2:3]
	s_addc_u32 s19, s19, 0
	s_add_i32 s20, s55, s37
	global_load_lds_dwordx4 v[208:209], off
	v_lshl_add_u64 v[208:209], s[18:19], 0, v[0:1]
	s_mov_b32 m0, s20
	s_nop 0
	global_load_lds_dwordx4 v[208:209], off
	v_lshl_add_u64 v[208:209], s[18:19], 0, v[130:131]
	s_add_i32 m0, s20, 0x2000
	s_nop 0
	global_load_lds_dwordx4 v[208:209], off
	v_lshl_add_u64 v[208:209], v[222:223], 0, s[2:3]
	s_mov_b32 m0, s45
	s_nop 0
	global_load_lds_dwordx4 v[208:209], off
	v_lshl_add_u64 v[208:209], v[224:225], 0, s[2:3]
	s_mov_b32 m0, s46
	s_nop 0
	global_load_lds_dwordx4 v[208:209], off
	s_waitcnt vmcnt(8)
	s_waitcnt lgkmcnt(0)
	s_barrier
	s_setprio 1
	s_waitcnt lgkmcnt(0)
	v_mfma_f32_16x16x32_bf16 v[62:65], v[144:147], v[176:179], v[62:65]
	v_mfma_f32_16x16x32_bf16 v[58:61], v[152:155], v[176:179], v[58:61]
	v_mfma_f32_16x16x32_bf16 v[54:57], v[144:147], v[184:187], v[54:57]
	v_mfma_f32_16x16x32_bf16 v[50:53], v[152:155], v[184:187], v[50:53]
	v_mfma_f32_16x16x32_bf16 v[38:41], v[144:147], v[192:195], v[38:41]
	v_mfma_f32_16x16x32_bf16 v[34:37], v[152:155], v[192:195], v[34:37]
	v_mfma_f32_16x16x32_bf16 v[22:25], v[144:147], v[200:203], v[22:25]
	v_mfma_f32_16x16x32_bf16 v[18:21], v[152:155], v[200:203], v[18:21]
	v_mfma_f32_16x16x32_bf16 v[62:65], v[148:151], v[180:183], v[62:65]
	v_mfma_f32_16x16x32_bf16 v[58:61], v[156:159], v[180:183], v[58:61]
	v_mfma_f32_16x16x32_bf16 v[54:57], v[148:151], v[188:191], v[54:57]
	v_mfma_f32_16x16x32_bf16 v[50:53], v[156:159], v[188:191], v[50:53]
	v_mfma_f32_16x16x32_bf16 v[38:41], v[148:151], v[196:199], v[38:41]
	v_mfma_f32_16x16x32_bf16 v[34:37], v[156:159], v[196:199], v[34:37]
	v_mfma_f32_16x16x32_bf16 v[22:25], v[148:151], v[204:207], v[22:25]
	v_mfma_f32_16x16x32_bf16 v[18:21], v[156:159], v[204:207], v[18:21]
	s_setprio 0
	s_setprio 1
	v_mfma_f32_16x16x32_bf16 v[46:49], v[160:163], v[176:179], v[46:49]
	v_mfma_f32_16x16x32_bf16 v[42:45], v[168:171], v[176:179], v[42:45]
	v_mfma_f32_16x16x32_bf16 v[30:33], v[160:163], v[184:187], v[30:33]
	v_mfma_f32_16x16x32_bf16 v[26:29], v[168:171], v[184:187], v[26:29]
	v_mfma_f32_16x16x32_bf16 v[14:17], v[160:163], v[192:195], v[14:17]
	v_mfma_f32_16x16x32_bf16 v[10:13], v[168:171], v[192:195], v[10:13]
	v_mfma_f32_16x16x32_bf16 v[6:9], v[160:163], v[200:203], v[6:9]
	v_mfma_f32_16x16x32_bf16 v[2:5], v[168:171], v[200:203], v[2:5]
	v_mfma_f32_16x16x32_bf16 v[46:49], v[164:167], v[180:183], v[46:49]
	v_mfma_f32_16x16x32_bf16 v[42:45], v[172:175], v[180:183], v[42:45]
	v_mfma_f32_16x16x32_bf16 v[30:33], v[164:167], v[188:191], v[30:33]
	v_mfma_f32_16x16x32_bf16 v[26:29], v[172:175], v[188:191], v[26:29]
	v_mfma_f32_16x16x32_bf16 v[14:17], v[164:167], v[196:199], v[14:17]
	v_mfma_f32_16x16x32_bf16 v[10:13], v[172:175], v[196:199], v[10:13]
	v_mfma_f32_16x16x32_bf16 v[6:9], v[164:167], v[204:207], v[6:9]
	v_mfma_f32_16x16x32_bf16 v[2:5], v[172:175], v[204:207], v[2:5]
	s_setprio 0
	s_barrier
	s_add_i32 s53, s53, 2
	s_add_u32 s16, s16, 0x100
	s_addc_u32 s17, s17, 0
	s_add_u32 s51, s51, 0x100
	s_addc_u32 s52, s52, 0
	s_cmp_gt_u32 s53, 29
	s_cbranch_scc1 .Lpeel_done_0
.LBB0_491:
	s_add_u32 s18, s16, 0xfff80080
	s_addc_u32 s19, s17, -1
	s_add_i32 s54, 0, 0x10000
	s_cmp_eq_u32 s53, 28
	s_cselect_b32 s21, s11, s19
	s_cselect_b32 s20, s49, s18
	s_cselect_b32 s19, s9, s52
	s_cselect_b32 s18, s50, s51
	s_add_i32 s56, 0, 0x14000
	v_add_u32_e32 v156, s54, v141
	v_add_u32_e32 v172, s56, v141
	ds_read_b128 v[144:147], v156
	ds_read_b128 v[148:151], v156 offset:1024
	ds_read_b128 v[152:155], v156 offset:2048
	ds_read_b128 v[156:159], v156 offset:3072
	ds_read_b128 v[160:163], v172
	ds_read_b128 v[164:167], v172 offset:1024
	ds_read_b128 v[168:171], v172 offset:2048
	ds_read_b128 v[172:175], v172 offset:3072
	v_lshl_add_u64 v[208:209], s[16:17], 0, v[136:137]
	s_add_i32 m0, s39, 0xc000
	ds_read_b128 v[176:179], v143
	ds_read_b128 v[180:183], v143 offset:1024
	ds_read_b128 v[184:187], v143 offset:2048
	ds_read_b128 v[188:191], v143 offset:3072
	ds_read_b128 v[192:195], v143 offset:4096
	ds_read_b128 v[196:199], v143 offset:5120
	ds_read_b128 v[200:203], v143 offset:6144
	ds_read_b128 v[204:207], v143 offset:7168
	global_load_lds_dwordx4 v[208:209], off
	v_lshl_add_u64 v[208:209], s[16:17], 0, v[138:139]
	s_add_i32 m0, s39, 0xe000
	s_nop 0
	global_load_lds_dwordx4 v[208:209], off
	s_waitcnt vmcnt(8)
	s_waitcnt lgkmcnt(0)
	s_barrier
	s_setprio 1
	s_waitcnt lgkmcnt(0)
	v_mfma_f32_16x16x32_bf16 v[126:129], v[144:147], v[176:179], v[126:129]
	v_mfma_f32_16x16x32_bf16 v[122:125], v[152:155], v[176:179], v[122:125]
	v_mfma_f32_16x16x32_bf16 v[118:121], v[144:147], v[184:187], v[118:121]
	v_mfma_f32_16x16x32_bf16 v[114:117], v[152:155], v[184:187], v[114:117]
	v_mfma_f32_16x16x32_bf16 v[102:105], v[144:147], v[192:195], v[102:105]
	v_mfma_f32_16x16x32_bf16 v[98:101], v[152:155], v[192:195], v[98:101]
	v_mfma_f32_16x16x32_bf16 v[86:89], v[144:147], v[200:203], v[86:89]
	v_mfma_f32_16x16x32_bf16 v[82:85], v[152:155], v[200:203], v[82:85]
	v_mfma_f32_16x16x32_bf16 v[126:129], v[148:151], v[180:183], v[126:129]
	v_mfma_f32_16x16x32_bf16 v[122:125], v[156:159], v[180:183], v[122:125]
	v_mfma_f32_16x16x32_bf16 v[118:121], v[148:151], v[188:191], v[118:121]
	v_mfma_f32_16x16x32_bf16 v[114:117], v[156:159], v[188:191], v[114:117]
	v_mfma_f32_16x16x32_bf16 v[102:105], v[148:151], v[196:199], v[102:105]
	v_mfma_f32_16x16x32_bf16 v[98:101], v[156:159], v[196:199], v[98:101]
	v_mfma_f32_16x16x32_bf16 v[86:89], v[148:151], v[204:207], v[86:89]
	v_mfma_f32_16x16x32_bf16 v[82:85], v[156:159], v[204:207], v[82:85]
	s_setprio 0
	s_setprio 1
	v_mfma_f32_16x16x32_bf16 v[110:113], v[160:163], v[176:179], v[110:113]
	v_mfma_f32_16x16x32_bf16 v[106:109], v[168:171], v[176:179], v[106:109]
	v_mfma_f32_16x16x32_bf16 v[94:97], v[160:163], v[184:187], v[94:97]
	v_mfma_f32_16x16x32_bf16 v[90:93], v[168:171], v[184:187], v[90:93]
	v_mfma_f32_16x16x32_bf16 v[78:81], v[160:163], v[192:195], v[78:81]
	v_mfma_f32_16x16x32_bf16 v[74:77], v[168:171], v[192:195], v[74:77]
	v_mfma_f32_16x16x32_bf16 v[70:73], v[160:163], v[200:203], v[70:73]
	v_mfma_f32_16x16x32_bf16 v[66:69], v[168:171], v[200:203], v[66:69]
	v_mfma_f32_16x16x32_bf16 v[110:113], v[164:167], v[180:183], v[110:113]
	v_mfma_f32_16x16x32_bf16 v[106:109], v[172:175], v[180:183], v[106:109]
	v_mfma_f32_16x16x32_bf16 v[94:97], v[164:167], v[188:191], v[94:97]
	v_mfma_f32_16x16x32_bf16 v[90:93], v[172:175], v[188:191], v[90:93]
	v_mfma_f32_16x16x32_bf16 v[78:81], v[164:167], v[196:199], v[78:81]
	v_mfma_f32_16x16x32_bf16 v[74:77], v[172:175], v[196:199], v[74:77]
	v_mfma_f32_16x16x32_bf16 v[70:73], v[164:167], v[204:207], v[70:73]
	v_mfma_f32_16x16x32_bf16 v[66:69], v[172:175], v[204:207], v[66:69]
	s_setprio 0
	s_barrier
	s_add_i32 s54, s54, s37
	v_lshl_add_u64 v[208:209], s[18:19], 0, v[0:1]
	s_mov_b32 m0, s54
	ds_read_b128 v[176:179], v143 offset:16384
	ds_read_b128 v[180:183], v143 offset:17408
	ds_read_b128 v[184:187], v143 offset:18432
	ds_read_b128 v[188:191], v143 offset:19456
	ds_read_b128 v[192:195], v143 offset:20480
	ds_read_b128 v[196:199], v143 offset:21504
	ds_read_b128 v[200:203], v143 offset:22528
	ds_read_b128 v[204:207], v143 offset:23552
	global_load_lds_dwordx4 v[208:209], off
	s_add_i32 m0, s54, 0x2000
	s_add_u32 s54, s18, 0x80000
	v_lshl_add_u64 v[220:221], s[18:19], 0, v[130:131]
	s_addc_u32 s55, s19, 0
	s_add_i32 s56, s56, s37
	global_load_lds_dwordx4 v[220:221], off
	v_lshl_add_u64 v[222:223], s[54:55], 0, v[0:1]
	s_mov_b32 m0, s56
	v_lshl_add_u64 v[224:225], s[20:21], 0, v[132:133]
	global_load_lds_dwordx4 v[222:223], off
	v_lshl_add_u64 v[222:223], s[54:55], 0, v[130:131]
	s_add_i32 m0, s56, 0x2000
	s_nop 0
	global_load_lds_dwordx4 v[222:223], off
	v_lshl_add_u64 v[222:223], s[20:21], 0, v[134:135]
	s_mov_b32 m0, s39
	s_nop 0
	global_load_lds_dwordx4 v[222:223], off
	s_mov_b32 m0, s40
	s_nop 0
	global_load_lds_dwordx4 v[224:225], off
	s_waitcnt vmcnt(8)
	s_waitcnt lgkmcnt(0)
	s_barrier
	s_setprio 1
	s_waitcnt lgkmcnt(0)
	v_mfma_f32_16x16x32_bf16 v[62:65], v[144:147], v[176:179], v[62:65]
	v_mfma_f32_16x16x32_bf16 v[58:61], v[152:155], v[176:179], v[58:61]
	v_mfma_f32_16x16x32_bf16 v[54:57], v[144:147], v[184:187], v[54:57]
	v_mfma_f32_16x16x32_bf16 v[50:53], v[152:155], v[184:187], v[50:53]
	v_mfma_f32_16x16x32_bf16 v[38:41], v[144:147], v[192:195], v[38:41]
	v_mfma_f32_16x16x32_bf16 v[34:37], v[152:155], v[192:195], v[34:37]
	v_mfma_f32_16x16x32_bf16 v[22:25], v[144:147], v[200:203], v[22:25]
	v_mfma_f32_16x16x32_bf16 v[18:21], v[152:155], v[200:203], v[18:21]
	v_mfma_f32_16x16x32_bf16 v[62:65], v[148:151], v[180:183], v[62:65]
	v_mfma_f32_16x16x32_bf16 v[58:61], v[156:159], v[180:183], v[58:61]
	v_mfma_f32_16x16x32_bf16 v[54:57], v[148:151], v[188:191], v[54:57]
	v_mfma_f32_16x16x32_bf16 v[50:53], v[156:159], v[188:191], v[50:53]
	v_mfma_f32_16x16x32_bf16 v[38:41], v[148:151], v[196:199], v[38:41]
	v_mfma_f32_16x16x32_bf16 v[34:37], v[156:159], v[196:199], v[34:37]
	v_mfma_f32_16x16x32_bf16 v[22:25], v[148:151], v[204:207], v[22:25]
	v_mfma_f32_16x16x32_bf16 v[18:21], v[156:159], v[204:207], v[18:21]
	s_setprio 0
	s_setprio 1
	v_mfma_f32_16x16x32_bf16 v[46:49], v[160:163], v[176:179], v[46:49]
	v_mfma_f32_16x16x32_bf16 v[42:45], v[168:171], v[176:179], v[42:45]
	v_mfma_f32_16x16x32_bf16 v[30:33], v[160:163], v[184:187], v[30:33]
	v_mfma_f32_16x16x32_bf16 v[26:29], v[168:171], v[184:187], v[26:29]
	v_mfma_f32_16x16x32_bf16 v[14:17], v[160:163], v[192:195], v[14:17]
	v_mfma_f32_16x16x32_bf16 v[10:13], v[168:171], v[192:195], v[10:13]
	v_mfma_f32_16x16x32_bf16 v[6:9], v[160:163], v[200:203], v[6:9]
	v_mfma_f32_16x16x32_bf16 v[2:5], v[168:171], v[200:203], v[2:5]
	v_mfma_f32_16x16x32_bf16 v[46:49], v[164:167], v[180:183], v[46:49]
	v_mfma_f32_16x16x32_bf16 v[42:45], v[172:175], v[180:183], v[42:45]
	v_mfma_f32_16x16x32_bf16 v[30:33], v[164:167], v[188:191], v[30:33]
	v_mfma_f32_16x16x32_bf16 v[26:29], v[172:175], v[188:191], v[26:29]
	v_mfma_f32_16x16x32_bf16 v[14:17], v[164:167], v[196:199], v[14:17]
	v_mfma_f32_16x16x32_bf16 v[10:13], v[172:175], v[196:199], v[10:13]
	v_mfma_f32_16x16x32_bf16 v[6:9], v[164:167], v[204:207], v[6:9]
	v_mfma_f32_16x16x32_bf16 v[2:5], v[172:175], v[204:207], v[2:5]
	s_setprio 0
	s_barrier
	s_add_i32 s54, 0, 0x18000
	s_add_i32 s55, 0, 0x1c000
	v_add_u32_e32 v156, s54, v141
	v_add_u32_e32 v172, s55, v141
	ds_read_b128 v[144:147], v156
	ds_read_b128 v[148:151], v156 offset:1024
	ds_read_b128 v[152:155], v156 offset:2048
	ds_read_b128 v[156:159], v156 offset:3072
	ds_read_b128 v[160:163], v172
	ds_read_b128 v[164:167], v172 offset:1024
	ds_read_b128 v[168:171], v172 offset:2048
	ds_read_b128 v[172:175], v172 offset:3072
	s_add_u32 s20, s20, 0x80000
	s_addc_u32 s21, s21, 0
	s_mov_b32 m0, s41
	v_lshl_add_u64 v[226:227], s[20:21], 0, v[134:135]
	ds_read_b128 v[176:179], v143 offset:32768
	ds_read_b128 v[180:183], v143 offset:33792
	ds_read_b128 v[184:187], v143 offset:34816
	ds_read_b128 v[188:191], v143 offset:35840
	ds_read_b128 v[192:195], v143 offset:36864
	ds_read_b128 v[196:199], v143 offset:37888
	ds_read_b128 v[200:203], v143 offset:38912
	ds_read_b128 v[204:207], v143 offset:39936
	global_load_lds_dwordx4 v[226:227], off
	v_lshl_add_u64 v[226:227], s[20:21], 0, v[132:133]
	s_mov_b32 m0, s44
	s_nop 0
	global_load_lds_dwordx4 v[226:227], off
	s_waitcnt vmcnt(8)
	s_waitcnt lgkmcnt(0)
	s_barrier
	s_setprio 1
	s_waitcnt lgkmcnt(0)
	v_mfma_f32_16x16x32_bf16 v[126:129], v[144:147], v[176:179], v[126:129]
	v_mfma_f32_16x16x32_bf16 v[122:125], v[152:155], v[176:179], v[122:125]
	v_mfma_f32_16x16x32_bf16 v[118:121], v[144:147], v[184:187], v[118:121]
	v_mfma_f32_16x16x32_bf16 v[114:117], v[152:155], v[184:187], v[114:117]
	v_mfma_f32_16x16x32_bf16 v[102:105], v[144:147], v[192:195], v[102:105]
	v_mfma_f32_16x16x32_bf16 v[98:101], v[152:155], v[192:195], v[98:101]
	v_mfma_f32_16x16x32_bf16 v[86:89], v[144:147], v[200:203], v[86:89]
	v_mfma_f32_16x16x32_bf16 v[82:85], v[152:155], v[200:203], v[82:85]
	v_mfma_f32_16x16x32_bf16 v[126:129], v[148:151], v[180:183], v[126:129]
	v_mfma_f32_16x16x32_bf16 v[122:125], v[156:159], v[180:183], v[122:125]
	v_mfma_f32_16x16x32_bf16 v[118:121], v[148:151], v[188:191], v[118:121]
	v_mfma_f32_16x16x32_bf16 v[114:117], v[156:159], v[188:191], v[114:117]
	v_mfma_f32_16x16x32_bf16 v[102:105], v[148:151], v[196:199], v[102:105]
	v_mfma_f32_16x16x32_bf16 v[98:101], v[156:159], v[196:199], v[98:101]
	v_mfma_f32_16x16x32_bf16 v[86:89], v[148:151], v[204:207], v[86:89]
	v_mfma_f32_16x16x32_bf16 v[82:85], v[156:159], v[204:207], v[82:85]
	s_setprio 0
	s_setprio 1
	v_mfma_f32_16x16x32_bf16 v[110:113], v[160:163], v[176:179], v[110:113]
	v_mfma_f32_16x16x32_bf16 v[106:109], v[168:171], v[176:179], v[106:109]
	v_mfma_f32_16x16x32_bf16 v[94:97], v[160:163], v[184:187], v[94:97]
	v_mfma_f32_16x16x32_bf16 v[90:93], v[168:171], v[184:187], v[90:93]
	v_mfma_f32_16x16x32_bf16 v[78:81], v[160:163], v[192:195], v[78:81]
	v_mfma_f32_16x16x32_bf16 v[74:77], v[168:171], v[192:195], v[74:77]
	v_mfma_f32_16x16x32_bf16 v[70:73], v[160:163], v[200:203], v[70:73]
	v_mfma_f32_16x16x32_bf16 v[66:69], v[168:171], v[200:203], v[66:69]
	v_mfma_f32_16x16x32_bf16 v[110:113], v[164:167], v[180:183], v[110:113]
	v_mfma_f32_16x16x32_bf16 v[106:109], v[172:175], v[180:183], v[106:109]
	v_mfma_f32_16x16x32_bf16 v[94:97], v[164:167], v[188:191], v[94:97]
	v_mfma_f32_16x16x32_bf16 v[90:93], v[172:175], v[188:191], v[90:93]
	v_mfma_f32_16x16x32_bf16 v[78:81], v[164:167], v[196:199], v[78:81]
	v_mfma_f32_16x16x32_bf16 v[74:77], v[172:175], v[196:199], v[74:77]
	v_mfma_f32_16x16x32_bf16 v[70:73], v[164:167], v[204:207], v[70:73]
	v_mfma_f32_16x16x32_bf16 v[66:69], v[172:175], v[204:207], v[66:69]
	s_setprio 0
	s_barrier
	s_add_i32 s20, s54, s37
	v_lshl_add_u64 v[208:209], v[208:209], 0, s[2:3]
	s_mov_b32 m0, s20
	ds_read_b128 v[176:179], v143 offset:49152
	ds_read_b128 v[180:183], v143 offset:50176
	ds_read_b128 v[184:187], v143 offset:51200
	ds_read_b128 v[188:191], v143 offset:52224
	ds_read_b128 v[192:195], v143 offset:53248
	ds_read_b128 v[196:199], v143 offset:54272
	ds_read_b128 v[200:203], v143 offset:55296
	ds_read_b128 v[204:207], v143 offset:56320
	global_load_lds_dwordx4 v[208:209], off
	s_add_i32 m0, s20, 0x2000
	s_add_u32 s18, s18, 0x80080
	v_lshl_add_u64 v[208:209], v[220:221], 0, s[2:3]
	s_addc_u32 s19, s19, 0
	s_add_i32 s20, s55, s37
	global_load_lds_dwordx4 v[208:209], off
	v_lshl_add_u64 v[208:209], s[18:19], 0, v[0:1]
	s_mov_b32 m0, s20
	s_nop 0
	global_load_lds_dwordx4 v[208:209], off
	v_lshl_add_u64 v[208:209], s[18:19], 0, v[130:131]
	s_add_i32 m0, s20, 0x2000
	s_nop 0
	global_load_lds_dwordx4 v[208:209], off
	v_lshl_add_u64 v[208:209], v[222:223], 0, s[2:3]
	s_mov_b32 m0, s45
	s_nop 0
	global_load_lds_dwordx4 v[208:209], off
	v_lshl_add_u64 v[208:209], v[224:225], 0, s[2:3]
	s_mov_b32 m0, s46
	s_nop 0
	global_load_lds_dwordx4 v[208:209], off
	s_waitcnt vmcnt(8)
	s_waitcnt lgkmcnt(0)
	s_barrier
	s_setprio 1
	s_waitcnt lgkmcnt(0)
	v_mfma_f32_16x16x32_bf16 v[62:65], v[144:147], v[176:179], v[62:65]
	v_mfma_f32_16x16x32_bf16 v[58:61], v[152:155], v[176:179], v[58:61]
	v_mfma_f32_16x16x32_bf16 v[54:57], v[144:147], v[184:187], v[54:57]
	v_mfma_f32_16x16x32_bf16 v[50:53], v[152:155], v[184:187], v[50:53]
	v_mfma_f32_16x16x32_bf16 v[38:41], v[144:147], v[192:195], v[38:41]
	v_mfma_f32_16x16x32_bf16 v[34:37], v[152:155], v[192:195], v[34:37]
	v_mfma_f32_16x16x32_bf16 v[22:25], v[144:147], v[200:203], v[22:25]
	v_mfma_f32_16x16x32_bf16 v[18:21], v[152:155], v[200:203], v[18:21]
	v_mfma_f32_16x16x32_bf16 v[62:65], v[148:151], v[180:183], v[62:65]
	v_mfma_f32_16x16x32_bf16 v[58:61], v[156:159], v[180:183], v[58:61]
	v_mfma_f32_16x16x32_bf16 v[54:57], v[148:151], v[188:191], v[54:57]
	v_mfma_f32_16x16x32_bf16 v[50:53], v[156:159], v[188:191], v[50:53]
	v_mfma_f32_16x16x32_bf16 v[38:41], v[148:151], v[196:199], v[38:41]
	v_mfma_f32_16x16x32_bf16 v[34:37], v[156:159], v[196:199], v[34:37]
	v_mfma_f32_16x16x32_bf16 v[22:25], v[148:151], v[204:207], v[22:25]
	v_mfma_f32_16x16x32_bf16 v[18:21], v[156:159], v[204:207], v[18:21]
	s_setprio 0
	s_setprio 1
	v_mfma_f32_16x16x32_bf16 v[46:49], v[160:163], v[176:179], v[46:49]
	v_mfma_f32_16x16x32_bf16 v[42:45], v[168:171], v[176:179], v[42:45]
	v_mfma_f32_16x16x32_bf16 v[30:33], v[160:163], v[184:187], v[30:33]
	v_mfma_f32_16x16x32_bf16 v[26:29], v[168:171], v[184:187], v[26:29]
	v_mfma_f32_16x16x32_bf16 v[14:17], v[160:163], v[192:195], v[14:17]
	v_mfma_f32_16x16x32_bf16 v[10:13], v[168:171], v[192:195], v[10:13]
	v_mfma_f32_16x16x32_bf16 v[6:9], v[160:163], v[200:203], v[6:9]
	v_mfma_f32_16x16x32_bf16 v[2:5], v[168:171], v[200:203], v[2:5]
	v_mfma_f32_16x16x32_bf16 v[46:49], v[164:167], v[180:183], v[46:49]
	v_mfma_f32_16x16x32_bf16 v[42:45], v[172:175], v[180:183], v[42:45]
	v_mfma_f32_16x16x32_bf16 v[30:33], v[164:167], v[188:191], v[30:33]
	v_mfma_f32_16x16x32_bf16 v[26:29], v[172:175], v[188:191], v[26:29]
	v_mfma_f32_16x16x32_bf16 v[14:17], v[164:167], v[196:199], v[14:17]
	v_mfma_f32_16x16x32_bf16 v[10:13], v[172:175], v[196:199], v[10:13]
	v_mfma_f32_16x16x32_bf16 v[6:9], v[164:167], v[204:207], v[6:9]
	v_mfma_f32_16x16x32_bf16 v[2:5], v[172:175], v[204:207], v[2:5]
	s_setprio 0
	s_barrier
	s_add_i32 s53, s53, 2
	s_add_u32 s16, s16, 0x100
	s_addc_u32 s17, s17, 0
	s_add_u32 s51, s51, 0x100
	s_addc_u32 s52, s52, 0
	s_cmp_gt_u32 s53, 29
	s_cbranch_scc0 .LBB0_491
.Lpeel_done_0:
	s_and_b64 vcc, exec, s[4:5]
	s_cbranch_vccz .LBB0_494
	s_barrier

.LBB0_882:
	s_add_u32 s38, s22, 0x80080
	s_addc_u32 s39, s23, 0
	s_add_u32 s15, s42, 0x100
	s_addc_u32 s21, s43, 0
	s_mov_b32 s22, 0
	s_add_i32 s41, s22, 2
	s_add_u32 s42, s38, 0xfff80080
	s_addc_u32 s23, s39, -1
	s_add_i32 s44, 0, 0x10000
	s_cmp_eq_u32 s63, s22
	s_cselect_b32 s23, s17, s23
	s_cselect_b32 s22, s16, s42
	v_add_u32_e32 v0, s44, v224
	s_cselect_b32 s43, s19, s21
	s_cselect_b32 s42, s18, s15
	s_add_i32 s45, 0, 0x14000
	ds_read_b128 v[30:33], v0
	ds_read_b128 v[134:137], v0 offset:1024
	ds_read_b128 v[138:141], v0 offset:2048
	ds_read_b128 v[142:145], v0 offset:3072
	v_add_u32_e32 v0, s45, v224
	ds_read_b128 v[146:149], v0
	ds_read_b128 v[150:153], v0 offset:1024
	ds_read_b128 v[154:157], v0 offset:2048
	ds_read_b128 v[158:161], v0 offset:3072
	v_lshl_add_u64 v[206:207], s[38:39], 0, v[202:203]
	s_add_i32 m0, s52, 0xc000
	ds_read_b128 v[162:165], v225
	ds_read_b128 v[166:169], v225 offset:1024
	ds_read_b128 v[170:173], v225 offset:2048
	ds_read_b128 v[174:177], v225 offset:3072
	ds_read_b128 v[178:181], v225 offset:4096
	ds_read_b128 v[182:185], v225 offset:5120
	ds_read_b128 v[186:189], v225 offset:6144
	ds_read_b128 v[190:193], v225 offset:7168
	global_load_lds_dwordx4 v[206:207], off
	v_lshl_add_u64 v[206:207], s[38:39], 0, v[204:205]
	s_add_i32 m0, s52, 0xe000
	s_nop 0
	global_load_lds_dwordx4 v[206:207], off
	s_waitcnt vmcnt(8)
	s_waitcnt lgkmcnt(0)
	s_barrier
	s_setprio 1
	s_waitcnt lgkmcnt(0)
	v_mfma_f32_16x16x32_bf16 v[26:29], v[30:33], v[162:165], 0
	v_mfma_f32_16x16x32_bf16 v[22:25], v[138:141], v[162:165], 0
	v_mfma_f32_16x16x32_bf16 v[62:65], v[30:33], v[170:173], 0
	v_mfma_f32_16x16x32_bf16 v[14:17], v[138:141], v[170:173], 0
	v_mfma_f32_16x16x32_bf16 v[58:61], v[30:33], v[178:181], 0
	v_mfma_f32_16x16x32_bf16 v[54:57], v[138:141], v[178:181], 0
	v_mfma_f32_16x16x32_bf16 v[94:97], v[30:33], v[186:189], 0
	v_mfma_f32_16x16x32_bf16 v[46:49], v[138:141], v[186:189], 0
	v_mfma_f32_16x16x32_bf16 v[26:29], v[134:137], v[166:169], v[26:29]
	v_mfma_f32_16x16x32_bf16 v[22:25], v[142:145], v[166:169], v[22:25]
	v_mfma_f32_16x16x32_bf16 v[62:65], v[134:137], v[174:177], v[62:65]
	v_mfma_f32_16x16x32_bf16 v[14:17], v[142:145], v[174:177], v[14:17]
	v_mfma_f32_16x16x32_bf16 v[58:61], v[134:137], v[182:185], v[58:61]
	v_mfma_f32_16x16x32_bf16 v[54:57], v[142:145], v[182:185], v[54:57]
	v_mfma_f32_16x16x32_bf16 v[94:97], v[134:137], v[190:193], v[94:97]
	v_mfma_f32_16x16x32_bf16 v[46:49], v[142:145], v[190:193], v[46:49]
	s_setprio 0
	s_setprio 1
	v_mfma_f32_16x16x32_bf16 v[18:21], v[146:149], v[162:165], 0
	v_mfma_f32_16x16x32_bf16 v[10:13], v[154:157], v[162:165], 0
	v_mfma_f32_16x16x32_bf16 v[2:5], v[146:149], v[170:173], 0
	v_mfma_f32_16x16x32_bf16 v[6:9], v[154:157], v[170:173], 0
	v_mfma_f32_16x16x32_bf16 v[50:53], v[146:149], v[178:181], 0
	v_mfma_f32_16x16x32_bf16 v[42:45], v[154:157], v[178:181], 0
	v_mfma_f32_16x16x32_bf16 v[34:37], v[146:149], v[186:189], 0
	v_mfma_f32_16x16x32_bf16 v[38:41], v[154:157], v[186:189], 0
	v_mfma_f32_16x16x32_bf16 v[18:21], v[150:153], v[166:169], v[18:21]
	v_mfma_f32_16x16x32_bf16 v[10:13], v[158:161], v[166:169], v[10:13]
	v_mfma_f32_16x16x32_bf16 v[2:5], v[150:153], v[174:177], v[2:5]
	v_mfma_f32_16x16x32_bf16 v[6:9], v[158:161], v[174:177], v[6:9]
	v_mfma_f32_16x16x32_bf16 v[50:53], v[150:153], v[182:185], v[50:53]
	v_mfma_f32_16x16x32_bf16 v[42:45], v[158:161], v[182:185], v[42:45]
	v_mfma_f32_16x16x32_bf16 v[34:37], v[150:153], v[190:193], v[34:37]
	v_mfma_f32_16x16x32_bf16 v[38:41], v[158:161], v[190:193], v[38:41]
	s_setprio 0
	s_barrier
	s_add_i32 s44, s44, s49
	v_lshl_add_u64 v[206:207], s[42:43], 0, v[196:197]
	s_mov_b32 m0, s44
	ds_read_b128 v[162:165], v225 offset:16384
	ds_read_b128 v[166:169], v225 offset:17408
	ds_read_b128 v[170:173], v225 offset:18432
	ds_read_b128 v[174:177], v225 offset:19456
	ds_read_b128 v[178:181], v225 offset:20480
	ds_read_b128 v[182:185], v225 offset:21504
	ds_read_b128 v[186:189], v225 offset:22528
	ds_read_b128 v[190:193], v225 offset:23552
	global_load_lds_dwordx4 v[206:207], off
	s_add_i32 m0, s44, 0x2000
	v_lshl_add_u64 v[208:209], s[42:43], 0, v[200:201]
	s_add_u32 s42, s42, s50
	s_addc_u32 s43, s43, 0
	s_add_i32 s44, s45, s49
	global_load_lds_dwordx4 v[208:209], off
	v_lshl_add_u64 v[220:221], s[42:43], 0, v[196:197]
	s_mov_b32 m0, s44
	v_lshl_add_u64 v[226:227], s[42:43], 0, v[200:201]
	global_load_lds_dwordx4 v[220:221], off
	s_add_i32 m0, s44, 0x2000
	v_lshl_add_u64 v[228:229], s[22:23], 0, v[194:195]
	global_load_lds_dwordx4 v[226:227], off
	s_mov_b32 m0, s52
	v_lshl_add_u64 v[230:231], s[22:23], 0, v[198:199]
	global_load_lds_dwordx4 v[228:229], off
	s_mov_b32 m0, s53
	s_nop 0
	global_load_lds_dwordx4 v[230:231], off
	s_waitcnt vmcnt(8)
	s_waitcnt lgkmcnt(0)
	s_barrier
	s_setprio 1
	s_waitcnt lgkmcnt(0)
	v_mfma_f32_16x16x32_bf16 v[90:93], v[30:33], v[162:165], 0
	v_mfma_f32_16x16x32_bf16 v[86:89], v[138:141], v[162:165], 0
	v_mfma_f32_16x16x32_bf16 v[130:133], v[30:33], v[170:173], 0
	v_mfma_f32_16x16x32_bf16 v[78:81], v[138:141], v[170:173], 0
	v_mfma_f32_16x16x32_bf16 v[126:129], v[30:33], v[178:181], 0
	v_mfma_f32_16x16x32_bf16 v[118:121], v[138:141], v[178:181], 0
	v_mfma_f32_16x16x32_bf16 v[110:113], v[138:141], v[186:189], 0
	v_mfma_f32_16x16x32_bf16 v[90:93], v[134:137], v[166:169], v[90:93]
	v_mfma_f32_16x16x32_bf16 v[86:89], v[142:145], v[166:169], v[86:89]
	v_mfma_f32_16x16x32_bf16 v[130:133], v[134:137], v[174:177], v[130:133]
	v_mfma_f32_16x16x32_bf16 v[78:81], v[142:145], v[174:177], v[78:81]
	v_mfma_f32_16x16x32_bf16 v[126:129], v[134:137], v[182:185], v[126:129]
	v_mfma_f32_16x16x32_bf16 v[118:121], v[142:145], v[182:185], v[118:121]
	v_mfma_f32_16x16x32_bf16 v[30:33], v[30:33], v[186:189], 0
	v_mfma_f32_16x16x32_bf16 v[110:113], v[142:145], v[190:193], v[110:113]
	v_mfma_f32_16x16x32_bf16 v[30:33], v[134:137], v[190:193], v[30:33]
	s_setprio 0
	s_setprio 1
	v_mfma_f32_16x16x32_bf16 v[82:85], v[146:149], v[162:165], 0
	v_mfma_f32_16x16x32_bf16 v[74:77], v[154:157], v[162:165], 0
	v_mfma_f32_16x16x32_bf16 v[66:69], v[146:149], v[170:173], 0
	v_mfma_f32_16x16x32_bf16 v[70:73], v[154:157], v[170:173], 0
	v_mfma_f32_16x16x32_bf16 v[114:117], v[146:149], v[178:181], 0
	v_mfma_f32_16x16x32_bf16 v[106:109], v[154:157], v[178:181], 0
	v_mfma_f32_16x16x32_bf16 v[98:101], v[146:149], v[186:189], 0
	v_mfma_f32_16x16x32_bf16 v[102:105], v[154:157], v[186:189], 0
	v_mfma_f32_16x16x32_bf16 v[82:85], v[150:153], v[166:169], v[82:85]
	v_mfma_f32_16x16x32_bf16 v[74:77], v[158:161], v[166:169], v[74:77]
	v_mfma_f32_16x16x32_bf16 v[66:69], v[150:153], v[174:177], v[66:69]
	v_mfma_f32_16x16x32_bf16 v[70:73], v[158:161], v[174:177], v[70:73]
	v_mfma_f32_16x16x32_bf16 v[114:117], v[150:153], v[182:185], v[114:117]
	v_mfma_f32_16x16x32_bf16 v[106:109], v[158:161], v[182:185], v[106:109]
	v_mfma_f32_16x16x32_bf16 v[98:101], v[150:153], v[190:193], v[98:101]
	v_mfma_f32_16x16x32_bf16 v[102:105], v[158:161], v[190:193], v[102:105]
	s_setprio 0
	s_barrier
	s_add_i32 s42, 0, 0x18000
	v_add_u32_e32 v0, s42, v224
	s_add_i32 s43, 0, 0x1c000
	ds_read_b128 v[122:125], v0
	ds_read_b128 v[134:137], v0 offset:1024
	ds_read_b128 v[138:141], v0 offset:2048
	ds_read_b128 v[142:145], v0 offset:3072
	v_add_u32_e32 v0, s43, v224
	ds_read_b128 v[146:149], v0
	ds_read_b128 v[150:153], v0 offset:1024
	ds_read_b128 v[154:157], v0 offset:2048
	ds_read_b128 v[158:161], v0 offset:3072
	s_add_u32 s22, s22, 0x80000
	s_addc_u32 s23, s23, 0
	s_mov_b32 m0, s54
	v_lshl_add_u64 v[232:233], s[22:23], 0, v[194:195]
	ds_read_b128 v[162:165], v225 offset:32768
	ds_read_b128 v[166:169], v225 offset:33792
	ds_read_b128 v[170:173], v225 offset:34816
	ds_read_b128 v[174:177], v225 offset:35840
	ds_read_b128 v[178:181], v225 offset:36864
	ds_read_b128 v[182:185], v225 offset:37888
	ds_read_b128 v[186:189], v225 offset:38912
	ds_read_b128 v[190:193], v225 offset:39936
	global_load_lds_dwordx4 v[232:233], off
	v_lshl_add_u64 v[232:233], s[22:23], 0, v[198:199]
	s_mov_b32 m0, s55
	s_nop 0
	global_load_lds_dwordx4 v[232:233], off
	s_waitcnt vmcnt(8)
	s_waitcnt lgkmcnt(0)
	s_barrier
	s_setprio 1
	s_waitcnt lgkmcnt(0)
	v_mfma_f32_16x16x32_bf16 v[26:29], v[122:125], v[162:165], v[26:29]
	v_mfma_f32_16x16x32_bf16 v[22:25], v[138:141], v[162:165], v[22:25]
	v_mfma_f32_16x16x32_bf16 v[62:65], v[122:125], v[170:173], v[62:65]
	v_mfma_f32_16x16x32_bf16 v[14:17], v[138:141], v[170:173], v[14:17]
	v_mfma_f32_16x16x32_bf16 v[58:61], v[122:125], v[178:181], v[58:61]
	v_mfma_f32_16x16x32_bf16 v[54:57], v[138:141], v[178:181], v[54:57]
	v_mfma_f32_16x16x32_bf16 v[94:97], v[122:125], v[186:189], v[94:97]
	v_mfma_f32_16x16x32_bf16 v[46:49], v[138:141], v[186:189], v[46:49]
	v_mfma_f32_16x16x32_bf16 v[26:29], v[134:137], v[166:169], v[26:29]
	v_mfma_f32_16x16x32_bf16 v[22:25], v[142:145], v[166:169], v[22:25]
	v_mfma_f32_16x16x32_bf16 v[62:65], v[134:137], v[174:177], v[62:65]
	v_mfma_f32_16x16x32_bf16 v[14:17], v[142:145], v[174:177], v[14:17]
	v_mfma_f32_16x16x32_bf16 v[58:61], v[134:137], v[182:185], v[58:61]
	v_mfma_f32_16x16x32_bf16 v[54:57], v[142:145], v[182:185], v[54:57]
	v_mfma_f32_16x16x32_bf16 v[94:97], v[134:137], v[190:193], v[94:97]
	v_mfma_f32_16x16x32_bf16 v[46:49], v[142:145], v[190:193], v[46:49]
	s_setprio 0
	s_setprio 1
	v_mfma_f32_16x16x32_bf16 v[18:21], v[146:149], v[162:165], v[18:21]
	v_mfma_f32_16x16x32_bf16 v[10:13], v[154:157], v[162:165], v[10:13]
	v_mfma_f32_16x16x32_bf16 v[2:5], v[146:149], v[170:173], v[2:5]
	v_mfma_f32_16x16x32_bf16 v[6:9], v[154:157], v[170:173], v[6:9]
	v_mfma_f32_16x16x32_bf16 v[50:53], v[146:149], v[178:181], v[50:53]
	v_mfma_f32_16x16x32_bf16 v[42:45], v[154:157], v[178:181], v[42:45]
	v_mfma_f32_16x16x32_bf16 v[34:37], v[146:149], v[186:189], v[34:37]
	v_mfma_f32_16x16x32_bf16 v[38:41], v[154:157], v[186:189], v[38:41]
	v_mfma_f32_16x16x32_bf16 v[18:21], v[150:153], v[166:169], v[18:21]
	v_mfma_f32_16x16x32_bf16 v[10:13], v[158:161], v[166:169], v[10:13]
	v_mfma_f32_16x16x32_bf16 v[2:5], v[150:153], v[174:177], v[2:5]
	v_mfma_f32_16x16x32_bf16 v[6:9], v[158:161], v[174:177], v[6:9]
	v_mfma_f32_16x16x32_bf16 v[50:53], v[150:153], v[182:185], v[50:53]
	v_mfma_f32_16x16x32_bf16 v[42:45], v[158:161], v[182:185], v[42:45]
	v_mfma_f32_16x16x32_bf16 v[34:37], v[150:153], v[190:193], v[34:37]
	v_mfma_f32_16x16x32_bf16 v[38:41], v[158:161], v[190:193], v[38:41]
	s_setprio 0
	s_barrier
	s_add_i32 s22, s42, s49
	v_lshl_add_u64 v[206:207], v[206:207], 0, s[2:3]
	s_mov_b32 m0, s22
	ds_read_b128 v[162:165], v225 offset:49152
	ds_read_b128 v[166:169], v225 offset:50176
	ds_read_b128 v[170:173], v225 offset:51200
	ds_read_b128 v[174:177], v225 offset:52224
	ds_read_b128 v[178:181], v225 offset:53248
	ds_read_b128 v[182:185], v225 offset:54272
	ds_read_b128 v[186:189], v225 offset:55296
	ds_read_b128 v[190:193], v225 offset:56320
	global_load_lds_dwordx4 v[206:207], off
	v_lshl_add_u64 v[206:207], v[208:209], 0, s[2:3]
	s_add_i32 m0, s22, 0x2000
	s_add_i32 s22, s43, s49
	global_load_lds_dwordx4 v[206:207], off
	v_lshl_add_u64 v[206:207], v[220:221], 0, s[2:3]
	s_mov_b32 m0, s22
	s_nop 0
	global_load_lds_dwordx4 v[206:207], off
	v_lshl_add_u64 v[206:207], v[226:227], 0, s[2:3]
	s_add_i32 m0, s22, 0x2000
	s_nop 0
	global_load_lds_dwordx4 v[206:207], off
	v_lshl_add_u64 v[206:207], v[228:229], 0, s[2:3]
	s_mov_b32 m0, s61
	s_nop 0
	global_load_lds_dwordx4 v[206:207], off
	v_lshl_add_u64 v[206:207], v[230:231], 0, s[2:3]
	s_mov_b32 m0, s62
	s_nop 0
	global_load_lds_dwordx4 v[206:207], off
	s_waitcnt vmcnt(8)
	s_waitcnt lgkmcnt(0)
	s_barrier
	s_setprio 1
	s_waitcnt lgkmcnt(0)
	v_mfma_f32_16x16x32_bf16 v[30:33], v[122:125], v[186:189], v[30:33]
	v_mfma_f32_16x16x32_bf16 v[90:93], v[122:125], v[162:165], v[90:93]
	v_mfma_f32_16x16x32_bf16 v[86:89], v[138:141], v[162:165], v[86:89]
	v_mfma_f32_16x16x32_bf16 v[130:133], v[122:125], v[170:173], v[130:133]
	v_mfma_f32_16x16x32_bf16 v[78:81], v[138:141], v[170:173], v[78:81]
	v_mfma_f32_16x16x32_bf16 v[126:129], v[122:125], v[178:181], v[126:129]
	v_mfma_f32_16x16x32_bf16 v[118:121], v[138:141], v[178:181], v[118:121]
	v_mfma_f32_16x16x32_bf16 v[122:125], v[134:137], v[190:193], v[30:33]
	v_mfma_f32_16x16x32_bf16 v[30:33], v[138:141], v[186:189], v[110:113]
	v_mfma_f32_16x16x32_bf16 v[90:93], v[134:137], v[166:169], v[90:93]
	v_mfma_f32_16x16x32_bf16 v[86:89], v[142:145], v[166:169], v[86:89]
	v_mfma_f32_16x16x32_bf16 v[130:133], v[134:137], v[174:177], v[130:133]
	v_mfma_f32_16x16x32_bf16 v[78:81], v[142:145], v[174:177], v[78:81]
	v_mfma_f32_16x16x32_bf16 v[126:129], v[134:137], v[182:185], v[126:129]
	v_mfma_f32_16x16x32_bf16 v[118:121], v[142:145], v[182:185], v[118:121]
	v_mfma_f32_16x16x32_bf16 v[110:113], v[142:145], v[190:193], v[30:33]
	s_setprio 0
	s_setprio 1
	v_mfma_f32_16x16x32_bf16 v[30:33], v[146:149], v[162:165], v[82:85]
	v_mfma_f32_16x16x32_bf16 v[82:85], v[150:153], v[166:169], v[30:33]
	v_mfma_f32_16x16x32_bf16 v[30:33], v[154:157], v[162:165], v[74:77]
	v_mfma_f32_16x16x32_bf16 v[74:77], v[158:161], v[166:169], v[30:33]
	v_mfma_f32_16x16x32_bf16 v[30:33], v[146:149], v[170:173], v[66:69]
	v_mfma_f32_16x16x32_bf16 v[66:69], v[150:153], v[174:177], v[30:33]
	v_mfma_f32_16x16x32_bf16 v[30:33], v[154:157], v[170:173], v[70:73]
	v_mfma_f32_16x16x32_bf16 v[70:73], v[158:161], v[174:177], v[30:33]
	v_mfma_f32_16x16x32_bf16 v[30:33], v[146:149], v[178:181], v[114:117]
	v_mfma_f32_16x16x32_bf16 v[114:117], v[150:153], v[182:185], v[30:33]
	v_mfma_f32_16x16x32_bf16 v[30:33], v[154:157], v[178:181], v[106:109]
	v_mfma_f32_16x16x32_bf16 v[106:109], v[158:161], v[182:185], v[30:33]
	v_mfma_f32_16x16x32_bf16 v[30:33], v[146:149], v[186:189], v[98:101]
	v_mfma_f32_16x16x32_bf16 v[98:101], v[150:153], v[190:193], v[30:33]
	v_mfma_f32_16x16x32_bf16 v[30:33], v[154:157], v[186:189], v[102:105]
	v_mfma_f32_16x16x32_bf16 v[102:105], v[158:161], v[190:193], v[30:33]
	s_setprio 0
	s_barrier
	s_add_u32 s38, s38, 0x100
	s_addc_u32 s39, s39, 0
	s_add_u32 s15, s15, 0x100
	s_addc_u32 s21, s21, 0
	s_cmp_ge_u32 s41, s56
	s_mov_b32 s22, s41
	s_cbranch_scc1 .Lpeel_done_1
.LBB0_883:
	s_add_i32 s41, s22, 2
	s_add_u32 s42, s38, 0xfff80080
	s_addc_u32 s23, s39, -1
	s_add_i32 s44, 0, 0x10000
	s_cmp_eq_u32 s63, s22
	s_cselect_b32 s23, s17, s23
	s_cselect_b32 s22, s16, s42
	v_add_u32_e32 v0, s44, v224
	s_cselect_b32 s43, s19, s21
	s_cselect_b32 s42, s18, s15
	s_add_i32 s45, 0, 0x14000
	ds_read_b128 v[30:33], v0
	ds_read_b128 v[134:137], v0 offset:1024
	ds_read_b128 v[138:141], v0 offset:2048
	ds_read_b128 v[142:145], v0 offset:3072
	v_add_u32_e32 v0, s45, v224
	ds_read_b128 v[146:149], v0
	ds_read_b128 v[150:153], v0 offset:1024
	ds_read_b128 v[154:157], v0 offset:2048
	ds_read_b128 v[158:161], v0 offset:3072
	v_lshl_add_u64 v[206:207], s[38:39], 0, v[202:203]
	s_add_i32 m0, s52, 0xc000
	ds_read_b128 v[162:165], v225
	ds_read_b128 v[166:169], v225 offset:1024
	ds_read_b128 v[170:173], v225 offset:2048
	ds_read_b128 v[174:177], v225 offset:3072
	ds_read_b128 v[178:181], v225 offset:4096
	ds_read_b128 v[182:185], v225 offset:5120
	ds_read_b128 v[186:189], v225 offset:6144
	ds_read_b128 v[190:193], v225 offset:7168
	global_load_lds_dwordx4 v[206:207], off
	v_lshl_add_u64 v[206:207], s[38:39], 0, v[204:205]
	s_add_i32 m0, s52, 0xe000
	s_nop 0
	global_load_lds_dwordx4 v[206:207], off
	s_waitcnt vmcnt(8)
	s_waitcnt lgkmcnt(0)
	s_barrier
	s_setprio 1
	s_waitcnt lgkmcnt(0)
	v_mfma_f32_16x16x32_bf16 v[26:29], v[30:33], v[162:165], v[26:29]
	v_mfma_f32_16x16x32_bf16 v[22:25], v[138:141], v[162:165], v[22:25]
	v_mfma_f32_16x16x32_bf16 v[62:65], v[30:33], v[170:173], v[62:65]
	v_mfma_f32_16x16x32_bf16 v[14:17], v[138:141], v[170:173], v[14:17]
	v_mfma_f32_16x16x32_bf16 v[58:61], v[30:33], v[178:181], v[58:61]
	v_mfma_f32_16x16x32_bf16 v[54:57], v[138:141], v[178:181], v[54:57]
	v_mfma_f32_16x16x32_bf16 v[94:97], v[30:33], v[186:189], v[94:97]
	v_mfma_f32_16x16x32_bf16 v[46:49], v[138:141], v[186:189], v[46:49]
	v_mfma_f32_16x16x32_bf16 v[26:29], v[134:137], v[166:169], v[26:29]
	v_mfma_f32_16x16x32_bf16 v[22:25], v[142:145], v[166:169], v[22:25]
	v_mfma_f32_16x16x32_bf16 v[62:65], v[134:137], v[174:177], v[62:65]
	v_mfma_f32_16x16x32_bf16 v[14:17], v[142:145], v[174:177], v[14:17]
	v_mfma_f32_16x16x32_bf16 v[58:61], v[134:137], v[182:185], v[58:61]
	v_mfma_f32_16x16x32_bf16 v[54:57], v[142:145], v[182:185], v[54:57]
	v_mfma_f32_16x16x32_bf16 v[94:97], v[134:137], v[190:193], v[94:97]
	v_mfma_f32_16x16x32_bf16 v[46:49], v[142:145], v[190:193], v[46:49]
	s_setprio 0
	s_setprio 1
	v_mfma_f32_16x16x32_bf16 v[18:21], v[146:149], v[162:165], v[18:21]
	v_mfma_f32_16x16x32_bf16 v[10:13], v[154:157], v[162:165], v[10:13]
	v_mfma_f32_16x16x32_bf16 v[2:5], v[146:149], v[170:173], v[2:5]
	v_mfma_f32_16x16x32_bf16 v[6:9], v[154:157], v[170:173], v[6:9]
	v_mfma_f32_16x16x32_bf16 v[50:53], v[146:149], v[178:181], v[50:53]
	v_mfma_f32_16x16x32_bf16 v[42:45], v[154:157], v[178:181], v[42:45]
	v_mfma_f32_16x16x32_bf16 v[34:37], v[146:149], v[186:189], v[34:37]
	v_mfma_f32_16x16x32_bf16 v[38:41], v[154:157], v[186:189], v[38:41]
	v_mfma_f32_16x16x32_bf16 v[18:21], v[150:153], v[166:169], v[18:21]
	v_mfma_f32_16x16x32_bf16 v[10:13], v[158:161], v[166:169], v[10:13]
	v_mfma_f32_16x16x32_bf16 v[2:5], v[150:153], v[174:177], v[2:5]
	v_mfma_f32_16x16x32_bf16 v[6:9], v[158:161], v[174:177], v[6:9]
	v_mfma_f32_16x16x32_bf16 v[50:53], v[150:153], v[182:185], v[50:53]
	v_mfma_f32_16x16x32_bf16 v[42:45], v[158:161], v[182:185], v[42:45]
	v_mfma_f32_16x16x32_bf16 v[34:37], v[150:153], v[190:193], v[34:37]
	v_mfma_f32_16x16x32_bf16 v[38:41], v[158:161], v[190:193], v[38:41]
	s_setprio 0
	s_barrier
	s_add_i32 s44, s44, s49
	v_lshl_add_u64 v[206:207], s[42:43], 0, v[196:197]
	s_mov_b32 m0, s44
	ds_read_b128 v[162:165], v225 offset:16384
	ds_read_b128 v[166:169], v225 offset:17408
	ds_read_b128 v[170:173], v225 offset:18432
	ds_read_b128 v[174:177], v225 offset:19456
	ds_read_b128 v[178:181], v225 offset:20480
	ds_read_b128 v[182:185], v225 offset:21504
	ds_read_b128 v[186:189], v225 offset:22528
	ds_read_b128 v[190:193], v225 offset:23552
	global_load_lds_dwordx4 v[206:207], off
	s_add_i32 m0, s44, 0x2000
	v_lshl_add_u64 v[208:209], s[42:43], 0, v[200:201]
	s_add_u32 s42, s42, s50
	s_addc_u32 s43, s43, 0
	s_add_i32 s44, s45, s49
	global_load_lds_dwordx4 v[208:209], off
	v_lshl_add_u64 v[220:221], s[42:43], 0, v[196:197]
	s_mov_b32 m0, s44
	v_lshl_add_u64 v[226:227], s[42:43], 0, v[200:201]
	global_load_lds_dwordx4 v[220:221], off
	s_add_i32 m0, s44, 0x2000
	v_lshl_add_u64 v[228:229], s[22:23], 0, v[194:195]
	global_load_lds_dwordx4 v[226:227], off
	s_mov_b32 m0, s52
	v_lshl_add_u64 v[230:231], s[22:23], 0, v[198:199]
	global_load_lds_dwordx4 v[228:229], off
	s_mov_b32 m0, s53
	s_nop 0
	global_load_lds_dwordx4 v[230:231], off
	s_waitcnt vmcnt(8)
	s_waitcnt lgkmcnt(0)
	s_barrier
	s_setprio 1
	s_waitcnt lgkmcnt(0)
	v_mfma_f32_16x16x32_bf16 v[90:93], v[30:33], v[162:165], v[90:93]
	v_mfma_f32_16x16x32_bf16 v[86:89], v[138:141], v[162:165], v[86:89]
	v_mfma_f32_16x16x32_bf16 v[130:133], v[30:33], v[170:173], v[130:133]
	v_mfma_f32_16x16x32_bf16 v[78:81], v[138:141], v[170:173], v[78:81]
	v_mfma_f32_16x16x32_bf16 v[126:129], v[30:33], v[178:181], v[126:129]
	v_mfma_f32_16x16x32_bf16 v[118:121], v[138:141], v[178:181], v[118:121]
	v_mfma_f32_16x16x32_bf16 v[110:113], v[138:141], v[186:189], v[110:113]
	v_mfma_f32_16x16x32_bf16 v[90:93], v[134:137], v[166:169], v[90:93]
	v_mfma_f32_16x16x32_bf16 v[86:89], v[142:145], v[166:169], v[86:89]
	v_mfma_f32_16x16x32_bf16 v[130:133], v[134:137], v[174:177], v[130:133]
	v_mfma_f32_16x16x32_bf16 v[78:81], v[142:145], v[174:177], v[78:81]
	v_mfma_f32_16x16x32_bf16 v[126:129], v[134:137], v[182:185], v[126:129]
	v_mfma_f32_16x16x32_bf16 v[118:121], v[142:145], v[182:185], v[118:121]
	v_mfma_f32_16x16x32_bf16 v[30:33], v[30:33], v[186:189], v[122:125]
	v_mfma_f32_16x16x32_bf16 v[110:113], v[142:145], v[190:193], v[110:113]
	v_mfma_f32_16x16x32_bf16 v[30:33], v[134:137], v[190:193], v[30:33]
	s_setprio 0
	s_setprio 1
	v_mfma_f32_16x16x32_bf16 v[82:85], v[146:149], v[162:165], v[82:85]
	v_mfma_f32_16x16x32_bf16 v[74:77], v[154:157], v[162:165], v[74:77]
	v_mfma_f32_16x16x32_bf16 v[66:69], v[146:149], v[170:173], v[66:69]
	v_mfma_f32_16x16x32_bf16 v[70:73], v[154:157], v[170:173], v[70:73]
	v_mfma_f32_16x16x32_bf16 v[114:117], v[146:149], v[178:181], v[114:117]
	v_mfma_f32_16x16x32_bf16 v[106:109], v[154:157], v[178:181], v[106:109]
	v_mfma_f32_16x16x32_bf16 v[98:101], v[146:149], v[186:189], v[98:101]
	v_mfma_f32_16x16x32_bf16 v[102:105], v[154:157], v[186:189], v[102:105]
	v_mfma_f32_16x16x32_bf16 v[82:85], v[150:153], v[166:169], v[82:85]
	v_mfma_f32_16x16x32_bf16 v[74:77], v[158:161], v[166:169], v[74:77]
	v_mfma_f32_16x16x32_bf16 v[66:69], v[150:153], v[174:177], v[66:69]
	v_mfma_f32_16x16x32_bf16 v[70:73], v[158:161], v[174:177], v[70:73]
	v_mfma_f32_16x16x32_bf16 v[114:117], v[150:153], v[182:185], v[114:117]
	v_mfma_f32_16x16x32_bf16 v[106:109], v[158:161], v[182:185], v[106:109]
	v_mfma_f32_16x16x32_bf16 v[98:101], v[150:153], v[190:193], v[98:101]
	v_mfma_f32_16x16x32_bf16 v[102:105], v[158:161], v[190:193], v[102:105]
	s_setprio 0
	s_barrier
	s_add_i32 s42, 0, 0x18000
	v_add_u32_e32 v0, s42, v224
	s_add_i32 s43, 0, 0x1c000
	ds_read_b128 v[122:125], v0
	ds_read_b128 v[134:137], v0 offset:1024
	ds_read_b128 v[138:141], v0 offset:2048
	ds_read_b128 v[142:145], v0 offset:3072
	v_add_u32_e32 v0, s43, v224
	ds_read_b128 v[146:149], v0
	ds_read_b128 v[150:153], v0 offset:1024
	ds_read_b128 v[154:157], v0 offset:2048
	ds_read_b128 v[158:161], v0 offset:3072
	s_add_u32 s22, s22, 0x80000
	s_addc_u32 s23, s23, 0
	s_mov_b32 m0, s54
	v_lshl_add_u64 v[232:233], s[22:23], 0, v[194:195]
	ds_read_b128 v[162:165], v225 offset:32768
	ds_read_b128 v[166:169], v225 offset:33792
	ds_read_b128 v[170:173], v225 offset:34816
	ds_read_b128 v[174:177], v225 offset:35840
	ds_read_b128 v[178:181], v225 offset:36864
	ds_read_b128 v[182:185], v225 offset:37888
	ds_read_b128 v[186:189], v225 offset:38912
	ds_read_b128 v[190:193], v225 offset:39936
	global_load_lds_dwordx4 v[232:233], off
	v_lshl_add_u64 v[232:233], s[22:23], 0, v[198:199]
	s_mov_b32 m0, s55
	s_nop 0
	global_load_lds_dwordx4 v[232:233], off
	s_waitcnt vmcnt(8)
	s_waitcnt lgkmcnt(0)
	s_barrier
	s_setprio 1
	s_waitcnt lgkmcnt(0)
	v_mfma_f32_16x16x32_bf16 v[26:29], v[122:125], v[162:165], v[26:29]
	v_mfma_f32_16x16x32_bf16 v[22:25], v[138:141], v[162:165], v[22:25]
	v_mfma_f32_16x16x32_bf16 v[62:65], v[122:125], v[170:173], v[62:65]
	v_mfma_f32_16x16x32_bf16 v[14:17], v[138:141], v[170:173], v[14:17]
	v_mfma_f32_16x16x32_bf16 v[58:61], v[122:125], v[178:181], v[58:61]
	v_mfma_f32_16x16x32_bf16 v[54:57], v[138:141], v[178:181], v[54:57]
	v_mfma_f32_16x16x32_bf16 v[94:97], v[122:125], v[186:189], v[94:97]
	v_mfma_f32_16x16x32_bf16 v[46:49], v[138:141], v[186:189], v[46:49]
	v_mfma_f32_16x16x32_bf16 v[26:29], v[134:137], v[166:169], v[26:29]
	v_mfma_f32_16x16x32_bf16 v[22:25], v[142:145], v[166:169], v[22:25]
	v_mfma_f32_16x16x32_bf16 v[62:65], v[134:137], v[174:177], v[62:65]
	v_mfma_f32_16x16x32_bf16 v[14:17], v[142:145], v[174:177], v[14:17]
	v_mfma_f32_16x16x32_bf16 v[58:61], v[134:137], v[182:185], v[58:61]
	v_mfma_f32_16x16x32_bf16 v[54:57], v[142:145], v[182:185], v[54:57]
	v_mfma_f32_16x16x32_bf16 v[94:97], v[134:137], v[190:193], v[94:97]
	v_mfma_f32_16x16x32_bf16 v[46:49], v[142:145], v[190:193], v[46:49]
	s_setprio 0
	s_setprio 1
	v_mfma_f32_16x16x32_bf16 v[18:21], v[146:149], v[162:165], v[18:21]
	v_mfma_f32_16x16x32_bf16 v[10:13], v[154:157], v[162:165], v[10:13]
	v_mfma_f32_16x16x32_bf16 v[2:5], v[146:149], v[170:173], v[2:5]
	v_mfma_f32_16x16x32_bf16 v[6:9], v[154:157], v[170:173], v[6:9]
	v_mfma_f32_16x16x32_bf16 v[50:53], v[146:149], v[178:181], v[50:53]
	v_mfma_f32_16x16x32_bf16 v[42:45], v[154:157], v[178:181], v[42:45]
	v_mfma_f32_16x16x32_bf16 v[34:37], v[146:149], v[186:189], v[34:37]
	v_mfma_f32_16x16x32_bf16 v[38:41], v[154:157], v[186:189], v[38:41]
	v_mfma_f32_16x16x32_bf16 v[18:21], v[150:153], v[166:169], v[18:21]
	v_mfma_f32_16x16x32_bf16 v[10:13], v[158:161], v[166:169], v[10:13]
	v_mfma_f32_16x16x32_bf16 v[2:5], v[150:153], v[174:177], v[2:5]
	v_mfma_f32_16x16x32_bf16 v[6:9], v[158:161], v[174:177], v[6:9]
	v_mfma_f32_16x16x32_bf16 v[50:53], v[150:153], v[182:185], v[50:53]
	v_mfma_f32_16x16x32_bf16 v[42:45], v[158:161], v[182:185], v[42:45]
	v_mfma_f32_16x16x32_bf16 v[34:37], v[150:153], v[190:193], v[34:37]
	v_mfma_f32_16x16x32_bf16 v[38:41], v[158:161], v[190:193], v[38:41]
	s_setprio 0
	s_barrier
	s_add_i32 s22, s42, s49
	v_lshl_add_u64 v[206:207], v[206:207], 0, s[2:3]
	s_mov_b32 m0, s22
	ds_read_b128 v[162:165], v225 offset:49152
	ds_read_b128 v[166:169], v225 offset:50176
	ds_read_b128 v[170:173], v225 offset:51200
	ds_read_b128 v[174:177], v225 offset:52224
	ds_read_b128 v[178:181], v225 offset:53248
	ds_read_b128 v[182:185], v225 offset:54272
	ds_read_b128 v[186:189], v225 offset:55296
	ds_read_b128 v[190:193], v225 offset:56320
	global_load_lds_dwordx4 v[206:207], off
	v_lshl_add_u64 v[206:207], v[208:209], 0, s[2:3]
	s_add_i32 m0, s22, 0x2000
	s_add_i32 s22, s43, s49
	global_load_lds_dwordx4 v[206:207], off
	v_lshl_add_u64 v[206:207], v[220:221], 0, s[2:3]
	s_mov_b32 m0, s22
	s_nop 0
	global_load_lds_dwordx4 v[206:207], off
	v_lshl_add_u64 v[206:207], v[226:227], 0, s[2:3]
	s_add_i32 m0, s22, 0x2000
	s_nop 0
	global_load_lds_dwordx4 v[206:207], off
	v_lshl_add_u64 v[206:207], v[228:229], 0, s[2:3]
	s_mov_b32 m0, s61
	s_nop 0
	global_load_lds_dwordx4 v[206:207], off
	v_lshl_add_u64 v[206:207], v[230:231], 0, s[2:3]
	s_mov_b32 m0, s62
	s_nop 0
	global_load_lds_dwordx4 v[206:207], off
	s_waitcnt vmcnt(8)
	s_waitcnt lgkmcnt(0)
	s_barrier
	s_setprio 1
	s_waitcnt lgkmcnt(0)
	v_mfma_f32_16x16x32_bf16 v[30:33], v[122:125], v[186:189], v[30:33]
	v_mfma_f32_16x16x32_bf16 v[90:93], v[122:125], v[162:165], v[90:93]
	v_mfma_f32_16x16x32_bf16 v[86:89], v[138:141], v[162:165], v[86:89]
	v_mfma_f32_16x16x32_bf16 v[130:133], v[122:125], v[170:173], v[130:133]
	v_mfma_f32_16x16x32_bf16 v[78:81], v[138:141], v[170:173], v[78:81]
	v_mfma_f32_16x16x32_bf16 v[126:129], v[122:125], v[178:181], v[126:129]
	v_mfma_f32_16x16x32_bf16 v[118:121], v[138:141], v[178:181], v[118:121]
	v_mfma_f32_16x16x32_bf16 v[122:125], v[134:137], v[190:193], v[30:33]
	v_mfma_f32_16x16x32_bf16 v[30:33], v[138:141], v[186:189], v[110:113]
	v_mfma_f32_16x16x32_bf16 v[90:93], v[134:137], v[166:169], v[90:93]
	v_mfma_f32_16x16x32_bf16 v[86:89], v[142:145], v[166:169], v[86:89]
	v_mfma_f32_16x16x32_bf16 v[130:133], v[134:137], v[174:177], v[130:133]
	v_mfma_f32_16x16x32_bf16 v[78:81], v[142:145], v[174:177], v[78:81]
	v_mfma_f32_16x16x32_bf16 v[126:129], v[134:137], v[182:185], v[126:129]
	v_mfma_f32_16x16x32_bf16 v[118:121], v[142:145], v[182:185], v[118:121]
	v_mfma_f32_16x16x32_bf16 v[110:113], v[142:145], v[190:193], v[30:33]
	s_setprio 0
	s_setprio 1
	v_mfma_f32_16x16x32_bf16 v[30:33], v[146:149], v[162:165], v[82:85]
	v_mfma_f32_16x16x32_bf16 v[82:85], v[150:153], v[166:169], v[30:33]
	v_mfma_f32_16x16x32_bf16 v[30:33], v[154:157], v[162:165], v[74:77]
	v_mfma_f32_16x16x32_bf16 v[74:77], v[158:161], v[166:169], v[30:33]
	v_mfma_f32_16x16x32_bf16 v[30:33], v[146:149], v[170:173], v[66:69]
	v_mfma_f32_16x16x32_bf16 v[66:69], v[150:153], v[174:177], v[30:33]
	v_mfma_f32_16x16x32_bf16 v[30:33], v[154:157], v[170:173], v[70:73]
	v_mfma_f32_16x16x32_bf16 v[70:73], v[158:161], v[174:177], v[30:33]
	v_mfma_f32_16x16x32_bf16 v[30:33], v[146:149], v[178:181], v[114:117]
	v_mfma_f32_16x16x32_bf16 v[114:117], v[150:153], v[182:185], v[30:33]
	v_mfma_f32_16x16x32_bf16 v[30:33], v[154:157], v[178:181], v[106:109]
	v_mfma_f32_16x16x32_bf16 v[106:109], v[158:161], v[182:185], v[30:33]
	v_mfma_f32_16x16x32_bf16 v[30:33], v[146:149], v[186:189], v[98:101]
	v_mfma_f32_16x16x32_bf16 v[98:101], v[150:153], v[190:193], v[30:33]
	v_mfma_f32_16x16x32_bf16 v[30:33], v[154:157], v[186:189], v[102:105]
	v_mfma_f32_16x16x32_bf16 v[102:105], v[158:161], v[190:193], v[30:33]
	s_setprio 0
	s_barrier
	s_add_u32 s38, s38, 0x100
	s_addc_u32 s39, s39, 0
	s_add_u32 s15, s15, 0x100
	s_addc_u32 s21, s21, 0
	s_cmp_ge_u32 s41, s56
	s_mov_b32 s22, s41
	s_cbranch_scc0 .LBB0_883
.Lpeel_done_1:
	s_and_b64 vcc, exec, s[6:7]
	s_cbranch_vccz .LBB0_886
	s_barrier

.LBB0_989:
	s_add_u32 s36, s38, 0x80080
	s_addc_u32 s37, s39, 0
	s_add_u32 s5, s22, 0x100
	s_addc_u32 s13, s23, 0
	s_mov_b32 s15, -2
	s_add_u32 s17, s36, 0xfff80080
	s_addc_u32 s22, s37, -1
	s_add_i32 s48, 0, 0x10000
	s_cmp_eq_u32 s15, 4
	s_cselect_b32 s39, s19, s22
	s_cselect_b32 s38, s18, s17
	s_cselect_b32 s23, s21, s13
	s_cselect_b32 s22, s20, s5
	s_add_i32 s17, 0, 0x14000
	v_add_u32_e32 v156, s48, v140
	v_add_u32_e32 v172, s17, v140
	ds_read_b128 v[144:147], v156
	ds_read_b128 v[148:151], v156 offset:1024
	ds_read_b128 v[152:155], v156 offset:2048
	ds_read_b128 v[156:159], v156 offset:3072
	ds_read_b128 v[160:163], v172
	ds_read_b128 v[164:167], v172 offset:1024
	ds_read_b128 v[168:171], v172 offset:2048
	ds_read_b128 v[172:175], v172 offset:3072
	v_lshl_add_u64 v[208:209], s[36:37], 0, v[136:137]
	s_add_i32 m0, s7, 0xc000
	ds_read_b128 v[176:179], v143
	ds_read_b128 v[180:183], v143 offset:1024
	ds_read_b128 v[184:187], v143 offset:2048
	ds_read_b128 v[188:191], v143 offset:3072
	ds_read_b128 v[192:195], v143 offset:4096
	ds_read_b128 v[196:199], v143 offset:5120
	ds_read_b128 v[200:203], v143 offset:6144
	ds_read_b128 v[204:207], v143 offset:7168
	global_load_lds_dwordx4 v[208:209], off
	v_lshl_add_u64 v[208:209], s[36:37], 0, v[138:139]
	s_add_i32 m0, s7, 0xe000
	s_nop 0
	global_load_lds_dwordx4 v[208:209], off
	s_waitcnt vmcnt(8)
	s_waitcnt lgkmcnt(0)
	s_barrier
	s_setprio 1
	s_waitcnt lgkmcnt(0)
	v_mfma_f32_16x16x32_bf16 v[126:129], v[144:147], v[176:179], 0
	v_mfma_f32_16x16x32_bf16 v[122:125], v[152:155], v[176:179], 0
	v_mfma_f32_16x16x32_bf16 v[118:121], v[144:147], v[184:187], 0
	v_mfma_f32_16x16x32_bf16 v[114:117], v[152:155], v[184:187], 0
	v_mfma_f32_16x16x32_bf16 v[102:105], v[144:147], v[192:195], 0
	v_mfma_f32_16x16x32_bf16 v[98:101], v[152:155], v[192:195], 0
	v_mfma_f32_16x16x32_bf16 v[86:89], v[144:147], v[200:203], 0
	v_mfma_f32_16x16x32_bf16 v[82:85], v[152:155], v[200:203], 0
	v_mfma_f32_16x16x32_bf16 v[126:129], v[148:151], v[180:183], v[126:129]
	v_mfma_f32_16x16x32_bf16 v[122:125], v[156:159], v[180:183], v[122:125]
	v_mfma_f32_16x16x32_bf16 v[118:121], v[148:151], v[188:191], v[118:121]
	v_mfma_f32_16x16x32_bf16 v[114:117], v[156:159], v[188:191], v[114:117]
	v_mfma_f32_16x16x32_bf16 v[102:105], v[148:151], v[196:199], v[102:105]
	v_mfma_f32_16x16x32_bf16 v[98:101], v[156:159], v[196:199], v[98:101]
	v_mfma_f32_16x16x32_bf16 v[86:89], v[148:151], v[204:207], v[86:89]
	v_mfma_f32_16x16x32_bf16 v[82:85], v[156:159], v[204:207], v[82:85]
	s_setprio 0
	s_setprio 1
	v_mfma_f32_16x16x32_bf16 v[110:113], v[160:163], v[176:179], 0
	v_mfma_f32_16x16x32_bf16 v[106:109], v[168:171], v[176:179], 0
	v_mfma_f32_16x16x32_bf16 v[94:97], v[160:163], v[184:187], 0
	v_mfma_f32_16x16x32_bf16 v[90:93], v[168:171], v[184:187], 0
	v_mfma_f32_16x16x32_bf16 v[78:81], v[160:163], v[192:195], 0
	v_mfma_f32_16x16x32_bf16 v[74:77], v[168:171], v[192:195], 0
	v_mfma_f32_16x16x32_bf16 v[70:73], v[160:163], v[200:203], 0
	v_mfma_f32_16x16x32_bf16 v[66:69], v[168:171], v[200:203], 0
	v_mfma_f32_16x16x32_bf16 v[110:113], v[164:167], v[180:183], v[110:113]
	v_mfma_f32_16x16x32_bf16 v[106:109], v[172:175], v[180:183], v[106:109]
	v_mfma_f32_16x16x32_bf16 v[94:97], v[164:167], v[188:191], v[94:97]
	v_mfma_f32_16x16x32_bf16 v[90:93], v[172:175], v[188:191], v[90:93]
	v_mfma_f32_16x16x32_bf16 v[78:81], v[164:167], v[196:199], v[78:81]
	v_mfma_f32_16x16x32_bf16 v[74:77], v[172:175], v[196:199], v[74:77]
	v_mfma_f32_16x16x32_bf16 v[70:73], v[164:167], v[204:207], v[70:73]
	v_mfma_f32_16x16x32_bf16 v[66:69], v[172:175], v[204:207], v[66:69]
	s_setprio 0
	s_barrier
	s_add_i32 s48, s48, s40
	v_lshl_add_u64 v[208:209], s[22:23], 0, v[0:1]
	s_mov_b32 m0, s48
	ds_read_b128 v[176:179], v143 offset:16384
	ds_read_b128 v[180:183], v143 offset:17408
	ds_read_b128 v[184:187], v143 offset:18432
	ds_read_b128 v[188:191], v143 offset:19456
	ds_read_b128 v[192:195], v143 offset:20480
	ds_read_b128 v[196:199], v143 offset:21504
	ds_read_b128 v[200:203], v143 offset:22528
	ds_read_b128 v[204:207], v143 offset:23552
	global_load_lds_dwordx4 v[208:209], off
	s_add_i32 m0, s48, 0x2000
	s_add_u32 s48, s22, 0x80000
	v_lshl_add_u64 v[216:217], s[22:23], 0, v[130:131]
	s_addc_u32 s49, s23, 0
	s_add_i32 s17, s17, s40
	global_load_lds_dwordx4 v[216:217], off
	v_lshl_add_u64 v[220:221], s[48:49], 0, v[0:1]
	s_mov_b32 m0, s17
	v_lshl_add_u64 v[222:223], s[38:39], 0, v[132:133]
	global_load_lds_dwordx4 v[220:221], off
	v_lshl_add_u64 v[220:221], s[48:49], 0, v[130:131]
	s_add_i32 m0, s17, 0x2000
	s_nop 0
	global_load_lds_dwordx4 v[220:221], off
	v_lshl_add_u64 v[220:221], s[38:39], 0, v[134:135]
	s_mov_b32 m0, s7
	s_nop 0
	global_load_lds_dwordx4 v[220:221], off
	s_mov_b32 m0, s9
	s_nop 0
	global_load_lds_dwordx4 v[222:223], off
	s_waitcnt vmcnt(8)
	s_waitcnt lgkmcnt(0)
	s_barrier
	s_setprio 1
	s_waitcnt lgkmcnt(0)
	v_mfma_f32_16x16x32_bf16 v[62:65], v[144:147], v[176:179], 0
	v_mfma_f32_16x16x32_bf16 v[58:61], v[152:155], v[176:179], 0
	v_mfma_f32_16x16x32_bf16 v[54:57], v[144:147], v[184:187], 0
	v_mfma_f32_16x16x32_bf16 v[50:53], v[152:155], v[184:187], 0
	v_mfma_f32_16x16x32_bf16 v[38:41], v[144:147], v[192:195], 0
	v_mfma_f32_16x16x32_bf16 v[34:37], v[152:155], v[192:195], 0
	v_mfma_f32_16x16x32_bf16 v[22:25], v[144:147], v[200:203], 0
	v_mfma_f32_16x16x32_bf16 v[18:21], v[152:155], v[200:203], 0
	v_mfma_f32_16x16x32_bf16 v[62:65], v[148:151], v[180:183], v[62:65]
	v_mfma_f32_16x16x32_bf16 v[58:61], v[156:159], v[180:183], v[58:61]
	v_mfma_f32_16x16x32_bf16 v[54:57], v[148:151], v[188:191], v[54:57]
	v_mfma_f32_16x16x32_bf16 v[50:53], v[156:159], v[188:191], v[50:53]
	v_mfma_f32_16x16x32_bf16 v[38:41], v[148:151], v[196:199], v[38:41]
	v_mfma_f32_16x16x32_bf16 v[34:37], v[156:159], v[196:199], v[34:37]
	v_mfma_f32_16x16x32_bf16 v[22:25], v[148:151], v[204:207], v[22:25]
	v_mfma_f32_16x16x32_bf16 v[18:21], v[156:159], v[204:207], v[18:21]
	s_setprio 0
	s_setprio 1
	v_mfma_f32_16x16x32_bf16 v[46:49], v[160:163], v[176:179], 0
	v_mfma_f32_16x16x32_bf16 v[42:45], v[168:171], v[176:179], 0
	v_mfma_f32_16x16x32_bf16 v[30:33], v[160:163], v[184:187], 0
	v_mfma_f32_16x16x32_bf16 v[26:29], v[168:171], v[184:187], 0
	v_mfma_f32_16x16x32_bf16 v[14:17], v[160:163], v[192:195], 0
	v_mfma_f32_16x16x32_bf16 v[10:13], v[168:171], v[192:195], 0
	v_mfma_f32_16x16x32_bf16 v[6:9], v[160:163], v[200:203], 0
	v_mfma_f32_16x16x32_bf16 v[2:5], v[168:171], v[200:203], 0
	v_mfma_f32_16x16x32_bf16 v[46:49], v[164:167], v[180:183], v[46:49]
	v_mfma_f32_16x16x32_bf16 v[42:45], v[172:175], v[180:183], v[42:45]
	v_mfma_f32_16x16x32_bf16 v[30:33], v[164:167], v[188:191], v[30:33]
	v_mfma_f32_16x16x32_bf16 v[26:29], v[172:175], v[188:191], v[26:29]
	v_mfma_f32_16x16x32_bf16 v[14:17], v[164:167], v[196:199], v[14:17]
	v_mfma_f32_16x16x32_bf16 v[10:13], v[172:175], v[196:199], v[10:13]
	v_mfma_f32_16x16x32_bf16 v[6:9], v[164:167], v[204:207], v[6:9]
	v_mfma_f32_16x16x32_bf16 v[2:5], v[172:175], v[204:207], v[2:5]
	s_setprio 0
	s_barrier
	s_add_i32 s17, 0, 0x18000
	s_add_i32 s48, 0, 0x1c000
	v_add_u32_e32 v156, s17, v140
	v_add_u32_e32 v172, s48, v140
	ds_read_b128 v[144:147], v156
	ds_read_b128 v[148:151], v156 offset:1024
	ds_read_b128 v[152:155], v156 offset:2048
	ds_read_b128 v[156:159], v156 offset:3072
	ds_read_b128 v[160:163], v172
	ds_read_b128 v[164:167], v172 offset:1024
	ds_read_b128 v[168:171], v172 offset:2048
	ds_read_b128 v[172:175], v172 offset:3072
	s_add_u32 s38, s38, 0x80000
	s_addc_u32 s39, s39, 0
	s_mov_b32 m0, s42
	v_lshl_add_u64 v[224:225], s[38:39], 0, v[134:135]
	ds_read_b128 v[176:179], v143 offset:32768
	ds_read_b128 v[180:183], v143 offset:33792
	ds_read_b128 v[184:187], v143 offset:34816
	ds_read_b128 v[188:191], v143 offset:35840
	ds_read_b128 v[192:195], v143 offset:36864
	ds_read_b128 v[196:199], v143 offset:37888
	ds_read_b128 v[200:203], v143 offset:38912
	ds_read_b128 v[204:207], v143 offset:39936
	global_load_lds_dwordx4 v[224:225], off
	v_lshl_add_u64 v[224:225], s[38:39], 0, v[132:133]
	s_mov_b32 m0, s43
	s_nop 0
	global_load_lds_dwordx4 v[224:225], off
	s_waitcnt vmcnt(8)
	s_waitcnt lgkmcnt(0)
	s_barrier
	s_setprio 1
	s_waitcnt lgkmcnt(0)
	v_mfma_f32_16x16x32_bf16 v[126:129], v[144:147], v[176:179], v[126:129]
	v_mfma_f32_16x16x32_bf16 v[122:125], v[152:155], v[176:179], v[122:125]
	v_mfma_f32_16x16x32_bf16 v[118:121], v[144:147], v[184:187], v[118:121]
	v_mfma_f32_16x16x32_bf16 v[114:117], v[152:155], v[184:187], v[114:117]
	v_mfma_f32_16x16x32_bf16 v[102:105], v[144:147], v[192:195], v[102:105]
	v_mfma_f32_16x16x32_bf16 v[98:101], v[152:155], v[192:195], v[98:101]
	v_mfma_f32_16x16x32_bf16 v[86:89], v[144:147], v[200:203], v[86:89]
	v_mfma_f32_16x16x32_bf16 v[82:85], v[152:155], v[200:203], v[82:85]
	v_mfma_f32_16x16x32_bf16 v[126:129], v[148:151], v[180:183], v[126:129]
	v_mfma_f32_16x16x32_bf16 v[122:125], v[156:159], v[180:183], v[122:125]
	v_mfma_f32_16x16x32_bf16 v[118:121], v[148:151], v[188:191], v[118:121]
	v_mfma_f32_16x16x32_bf16 v[114:117], v[156:159], v[188:191], v[114:117]
	v_mfma_f32_16x16x32_bf16 v[102:105], v[148:151], v[196:199], v[102:105]
	v_mfma_f32_16x16x32_bf16 v[98:101], v[156:159], v[196:199], v[98:101]
	v_mfma_f32_16x16x32_bf16 v[86:89], v[148:151], v[204:207], v[86:89]
	v_mfma_f32_16x16x32_bf16 v[82:85], v[156:159], v[204:207], v[82:85]
	s_setprio 0
	s_setprio 1
	v_mfma_f32_16x16x32_bf16 v[110:113], v[160:163], v[176:179], v[110:113]
	v_mfma_f32_16x16x32_bf16 v[106:109], v[168:171], v[176:179], v[106:109]
	v_mfma_f32_16x16x32_bf16 v[94:97], v[160:163], v[184:187], v[94:97]
	v_mfma_f32_16x16x32_bf16 v[90:93], v[168:171], v[184:187], v[90:93]
	v_mfma_f32_16x16x32_bf16 v[78:81], v[160:163], v[192:195], v[78:81]
	v_mfma_f32_16x16x32_bf16 v[74:77], v[168:171], v[192:195], v[74:77]
	v_mfma_f32_16x16x32_bf16 v[70:73], v[160:163], v[200:203], v[70:73]
	v_mfma_f32_16x16x32_bf16 v[66:69], v[168:171], v[200:203], v[66:69]
	v_mfma_f32_16x16x32_bf16 v[110:113], v[164:167], v[180:183], v[110:113]
	v_mfma_f32_16x16x32_bf16 v[106:109], v[172:175], v[180:183], v[106:109]
	v_mfma_f32_16x16x32_bf16 v[94:97], v[164:167], v[188:191], v[94:97]
	v_mfma_f32_16x16x32_bf16 v[90:93], v[172:175], v[188:191], v[90:93]
	v_mfma_f32_16x16x32_bf16 v[78:81], v[164:167], v[196:199], v[78:81]
	v_mfma_f32_16x16x32_bf16 v[74:77], v[172:175], v[196:199], v[74:77]
	v_mfma_f32_16x16x32_bf16 v[70:73], v[164:167], v[204:207], v[70:73]
	v_mfma_f32_16x16x32_bf16 v[66:69], v[172:175], v[204:207], v[66:69]
	s_setprio 0
	s_barrier
	s_add_i32 s17, s17, s40
	v_lshl_add_u64 v[208:209], v[208:209], 0, s[2:3]
	s_mov_b32 m0, s17
	ds_read_b128 v[176:179], v143 offset:49152
	ds_read_b128 v[180:183], v143 offset:50176
	ds_read_b128 v[184:187], v143 offset:51200
	ds_read_b128 v[188:191], v143 offset:52224
	ds_read_b128 v[192:195], v143 offset:53248
	ds_read_b128 v[196:199], v143 offset:54272
	ds_read_b128 v[200:203], v143 offset:55296
	ds_read_b128 v[204:207], v143 offset:56320
	global_load_lds_dwordx4 v[208:209], off
	s_add_i32 m0, s17, 0x2000
	s_add_u32 s22, s22, 0x80080
	v_lshl_add_u64 v[208:209], v[216:217], 0, s[2:3]
	s_addc_u32 s23, s23, 0
	s_add_i32 s17, s48, s40
	global_load_lds_dwordx4 v[208:209], off
	v_lshl_add_u64 v[208:209], s[22:23], 0, v[0:1]
	s_mov_b32 m0, s17
	s_nop 0
	global_load_lds_dwordx4 v[208:209], off
	v_lshl_add_u64 v[208:209], s[22:23], 0, v[130:131]
	s_add_i32 m0, s17, 0x2000
	s_nop 0
	global_load_lds_dwordx4 v[208:209], off
	v_lshl_add_u64 v[208:209], v[220:221], 0, s[2:3]
	s_mov_b32 m0, s44
	s_nop 0
	global_load_lds_dwordx4 v[208:209], off
	v_lshl_add_u64 v[208:209], v[222:223], 0, s[2:3]
	s_mov_b32 m0, s45
	s_nop 0
	global_load_lds_dwordx4 v[208:209], off
	s_waitcnt vmcnt(8)
	s_waitcnt lgkmcnt(0)
	s_barrier
	s_setprio 1
	s_waitcnt lgkmcnt(0)
	v_mfma_f32_16x16x32_bf16 v[62:65], v[144:147], v[176:179], v[62:65]
	v_mfma_f32_16x16x32_bf16 v[58:61], v[152:155], v[176:179], v[58:61]
	v_mfma_f32_16x16x32_bf16 v[54:57], v[144:147], v[184:187], v[54:57]
	v_mfma_f32_16x16x32_bf16 v[50:53], v[152:155], v[184:187], v[50:53]
	v_mfma_f32_16x16x32_bf16 v[38:41], v[144:147], v[192:195], v[38:41]
	v_mfma_f32_16x16x32_bf16 v[34:37], v[152:155], v[192:195], v[34:37]
	v_mfma_f32_16x16x32_bf16 v[22:25], v[144:147], v[200:203], v[22:25]
	v_mfma_f32_16x16x32_bf16 v[18:21], v[152:155], v[200:203], v[18:21]
	v_mfma_f32_16x16x32_bf16 v[62:65], v[148:151], v[180:183], v[62:65]
	v_mfma_f32_16x16x32_bf16 v[58:61], v[156:159], v[180:183], v[58:61]
	v_mfma_f32_16x16x32_bf16 v[54:57], v[148:151], v[188:191], v[54:57]
	v_mfma_f32_16x16x32_bf16 v[50:53], v[156:159], v[188:191], v[50:53]
	v_mfma_f32_16x16x32_bf16 v[38:41], v[148:151], v[196:199], v[38:41]
	v_mfma_f32_16x16x32_bf16 v[34:37], v[156:159], v[196:199], v[34:37]
	v_mfma_f32_16x16x32_bf16 v[22:25], v[148:151], v[204:207], v[22:25]
	v_mfma_f32_16x16x32_bf16 v[18:21], v[156:159], v[204:207], v[18:21]
	s_setprio 0
	s_setprio 1
	v_mfma_f32_16x16x32_bf16 v[46:49], v[160:163], v[176:179], v[46:49]
	v_mfma_f32_16x16x32_bf16 v[42:45], v[168:171], v[176:179], v[42:45]
	v_mfma_f32_16x16x32_bf16 v[30:33], v[160:163], v[184:187], v[30:33]
	v_mfma_f32_16x16x32_bf16 v[26:29], v[168:171], v[184:187], v[26:29]
	v_mfma_f32_16x16x32_bf16 v[14:17], v[160:163], v[192:195], v[14:17]
	v_mfma_f32_16x16x32_bf16 v[10:13], v[168:171], v[192:195], v[10:13]
	v_mfma_f32_16x16x32_bf16 v[6:9], v[160:163], v[200:203], v[6:9]
	v_mfma_f32_16x16x32_bf16 v[2:5], v[168:171], v[200:203], v[2:5]
	v_mfma_f32_16x16x32_bf16 v[46:49], v[164:167], v[180:183], v[46:49]
	v_mfma_f32_16x16x32_bf16 v[42:45], v[172:175], v[180:183], v[42:45]
	v_mfma_f32_16x16x32_bf16 v[30:33], v[164:167], v[188:191], v[30:33]
	v_mfma_f32_16x16x32_bf16 v[26:29], v[172:175], v[188:191], v[26:29]
	v_mfma_f32_16x16x32_bf16 v[14:17], v[164:167], v[196:199], v[14:17]
	v_mfma_f32_16x16x32_bf16 v[10:13], v[172:175], v[196:199], v[10:13]
	v_mfma_f32_16x16x32_bf16 v[6:9], v[164:167], v[204:207], v[6:9]
	v_mfma_f32_16x16x32_bf16 v[2:5], v[172:175], v[204:207], v[2:5]
	s_setprio 0
	s_barrier
	s_add_i32 s15, s15, 2
	s_add_u32 s36, s36, 0x100
	s_addc_u32 s37, s37, 0
	s_add_u32 s5, s5, 0x100
	s_addc_u32 s13, s13, 0
	s_cmp_gt_u32 s15, 5
	s_cbranch_scc1 .Lpeel_done_2
.LBB0_990:
	s_add_u32 s17, s36, 0xfff80080
	s_addc_u32 s22, s37, -1
	s_add_i32 s48, 0, 0x10000
	s_cmp_eq_u32 s15, 4
	s_cselect_b32 s39, s19, s22
	s_cselect_b32 s38, s18, s17
	s_cselect_b32 s23, s21, s13
	s_cselect_b32 s22, s20, s5
	s_add_i32 s17, 0, 0x14000
	v_add_u32_e32 v156, s48, v140
	v_add_u32_e32 v172, s17, v140
	ds_read_b128 v[144:147], v156
	ds_read_b128 v[148:151], v156 offset:1024
	ds_read_b128 v[152:155], v156 offset:2048
	ds_read_b128 v[156:159], v156 offset:3072
	ds_read_b128 v[160:163], v172
	ds_read_b128 v[164:167], v172 offset:1024
	ds_read_b128 v[168:171], v172 offset:2048
	ds_read_b128 v[172:175], v172 offset:3072
	v_lshl_add_u64 v[208:209], s[36:37], 0, v[136:137]
	s_add_i32 m0, s7, 0xc000
	ds_read_b128 v[176:179], v143
	ds_read_b128 v[180:183], v143 offset:1024
	ds_read_b128 v[184:187], v143 offset:2048
	ds_read_b128 v[188:191], v143 offset:3072
	ds_read_b128 v[192:195], v143 offset:4096
	ds_read_b128 v[196:199], v143 offset:5120
	ds_read_b128 v[200:203], v143 offset:6144
	ds_read_b128 v[204:207], v143 offset:7168
	global_load_lds_dwordx4 v[208:209], off
	v_lshl_add_u64 v[208:209], s[36:37], 0, v[138:139]
	s_add_i32 m0, s7, 0xe000
	s_nop 0
	global_load_lds_dwordx4 v[208:209], off
	s_waitcnt vmcnt(8)
	s_waitcnt lgkmcnt(0)
	s_barrier
	s_setprio 1
	s_waitcnt lgkmcnt(0)
	v_mfma_f32_16x16x32_bf16 v[126:129], v[144:147], v[176:179], v[126:129]
	v_mfma_f32_16x16x32_bf16 v[122:125], v[152:155], v[176:179], v[122:125]
	v_mfma_f32_16x16x32_bf16 v[118:121], v[144:147], v[184:187], v[118:121]
	v_mfma_f32_16x16x32_bf16 v[114:117], v[152:155], v[184:187], v[114:117]
	v_mfma_f32_16x16x32_bf16 v[102:105], v[144:147], v[192:195], v[102:105]
	v_mfma_f32_16x16x32_bf16 v[98:101], v[152:155], v[192:195], v[98:101]
	v_mfma_f32_16x16x32_bf16 v[86:89], v[144:147], v[200:203], v[86:89]
	v_mfma_f32_16x16x32_bf16 v[82:85], v[152:155], v[200:203], v[82:85]
	v_mfma_f32_16x16x32_bf16 v[126:129], v[148:151], v[180:183], v[126:129]
	v_mfma_f32_16x16x32_bf16 v[122:125], v[156:159], v[180:183], v[122:125]
	v_mfma_f32_16x16x32_bf16 v[118:121], v[148:151], v[188:191], v[118:121]
	v_mfma_f32_16x16x32_bf16 v[114:117], v[156:159], v[188:191], v[114:117]
	v_mfma_f32_16x16x32_bf16 v[102:105], v[148:151], v[196:199], v[102:105]
	v_mfma_f32_16x16x32_bf16 v[98:101], v[156:159], v[196:199], v[98:101]
	v_mfma_f32_16x16x32_bf16 v[86:89], v[148:151], v[204:207], v[86:89]
	v_mfma_f32_16x16x32_bf16 v[82:85], v[156:159], v[204:207], v[82:85]
	s_setprio 0
	s_setprio 1
	v_mfma_f32_16x16x32_bf16 v[110:113], v[160:163], v[176:179], v[110:113]
	v_mfma_f32_16x16x32_bf16 v[106:109], v[168:171], v[176:179], v[106:109]
	v_mfma_f32_16x16x32_bf16 v[94:97], v[160:163], v[184:187], v[94:97]
	v_mfma_f32_16x16x32_bf16 v[90:93], v[168:171], v[184:187], v[90:93]
	v_mfma_f32_16x16x32_bf16 v[78:81], v[160:163], v[192:195], v[78:81]
	v_mfma_f32_16x16x32_bf16 v[74:77], v[168:171], v[192:195], v[74:77]
	v_mfma_f32_16x16x32_bf16 v[70:73], v[160:163], v[200:203], v[70:73]
	v_mfma_f32_16x16x32_bf16 v[66:69], v[168:171], v[200:203], v[66:69]
	v_mfma_f32_16x16x32_bf16 v[110:113], v[164:167], v[180:183], v[110:113]
	v_mfma_f32_16x16x32_bf16 v[106:109], v[172:175], v[180:183], v[106:109]
	v_mfma_f32_16x16x32_bf16 v[94:97], v[164:167], v[188:191], v[94:97]
	v_mfma_f32_16x16x32_bf16 v[90:93], v[172:175], v[188:191], v[90:93]
	v_mfma_f32_16x16x32_bf16 v[78:81], v[164:167], v[196:199], v[78:81]
	v_mfma_f32_16x16x32_bf16 v[74:77], v[172:175], v[196:199], v[74:77]
	v_mfma_f32_16x16x32_bf16 v[70:73], v[164:167], v[204:207], v[70:73]
	v_mfma_f32_16x16x32_bf16 v[66:69], v[172:175], v[204:207], v[66:69]
	s_setprio 0
	s_barrier
	s_add_i32 s48, s48, s40
	v_lshl_add_u64 v[208:209], s[22:23], 0, v[0:1]
	s_mov_b32 m0, s48
	ds_read_b128 v[176:179], v143 offset:16384
	ds_read_b128 v[180:183], v143 offset:17408
	ds_read_b128 v[184:187], v143 offset:18432
	ds_read_b128 v[188:191], v143 offset:19456
	ds_read_b128 v[192:195], v143 offset:20480
	ds_read_b128 v[196:199], v143 offset:21504
	ds_read_b128 v[200:203], v143 offset:22528
	ds_read_b128 v[204:207], v143 offset:23552
	global_load_lds_dwordx4 v[208:209], off
	s_add_i32 m0, s48, 0x2000
	s_add_u32 s48, s22, 0x80000
	v_lshl_add_u64 v[216:217], s[22:23], 0, v[130:131]
	s_addc_u32 s49, s23, 0
	s_add_i32 s17, s17, s40
	global_load_lds_dwordx4 v[216:217], off
	v_lshl_add_u64 v[220:221], s[48:49], 0, v[0:1]
	s_mov_b32 m0, s17
	v_lshl_add_u64 v[222:223], s[38:39], 0, v[132:133]
	global_load_lds_dwordx4 v[220:221], off
	v_lshl_add_u64 v[220:221], s[48:49], 0, v[130:131]
	s_add_i32 m0, s17, 0x2000
	s_nop 0
	global_load_lds_dwordx4 v[220:221], off
	v_lshl_add_u64 v[220:221], s[38:39], 0, v[134:135]
	s_mov_b32 m0, s7
	s_nop 0
	global_load_lds_dwordx4 v[220:221], off
	s_mov_b32 m0, s9
	s_nop 0
	global_load_lds_dwordx4 v[222:223], off
	s_waitcnt vmcnt(8)
	s_waitcnt lgkmcnt(0)
	s_barrier
	s_setprio 1
	s_waitcnt lgkmcnt(0)
	v_mfma_f32_16x16x32_bf16 v[62:65], v[144:147], v[176:179], v[62:65]
	v_mfma_f32_16x16x32_bf16 v[58:61], v[152:155], v[176:179], v[58:61]
	v_mfma_f32_16x16x32_bf16 v[54:57], v[144:147], v[184:187], v[54:57]
	v_mfma_f32_16x16x32_bf16 v[50:53], v[152:155], v[184:187], v[50:53]
	v_mfma_f32_16x16x32_bf16 v[38:41], v[144:147], v[192:195], v[38:41]
	v_mfma_f32_16x16x32_bf16 v[34:37], v[152:155], v[192:195], v[34:37]
	v_mfma_f32_16x16x32_bf16 v[22:25], v[144:147], v[200:203], v[22:25]
	v_mfma_f32_16x16x32_bf16 v[18:21], v[152:155], v[200:203], v[18:21]
	v_mfma_f32_16x16x32_bf16 v[62:65], v[148:151], v[180:183], v[62:65]
	v_mfma_f32_16x16x32_bf16 v[58:61], v[156:159], v[180:183], v[58:61]
	v_mfma_f32_16x16x32_bf16 v[54:57], v[148:151], v[188:191], v[54:57]
	v_mfma_f32_16x16x32_bf16 v[50:53], v[156:159], v[188:191], v[50:53]
	v_mfma_f32_16x16x32_bf16 v[38:41], v[148:151], v[196:199], v[38:41]
	v_mfma_f32_16x16x32_bf16 v[34:37], v[156:159], v[196:199], v[34:37]
	v_mfma_f32_16x16x32_bf16 v[22:25], v[148:151], v[204:207], v[22:25]
	v_mfma_f32_16x16x32_bf16 v[18:21], v[156:159], v[204:207], v[18:21]
	s_setprio 0
	s_setprio 1
	v_mfma_f32_16x16x32_bf16 v[46:49], v[160:163], v[176:179], v[46:49]
	v_mfma_f32_16x16x32_bf16 v[42:45], v[168:171], v[176:179], v[42:45]
	v_mfma_f32_16x16x32_bf16 v[30:33], v[160:163], v[184:187], v[30:33]
	v_mfma_f32_16x16x32_bf16 v[26:29], v[168:171], v[184:187], v[26:29]
	v_mfma_f32_16x16x32_bf16 v[14:17], v[160:163], v[192:195], v[14:17]
	v_mfma_f32_16x16x32_bf16 v[10:13], v[168:171], v[192:195], v[10:13]
	v_mfma_f32_16x16x32_bf16 v[6:9], v[160:163], v[200:203], v[6:9]
	v_mfma_f32_16x16x32_bf16 v[2:5], v[168:171], v[200:203], v[2:5]
	v_mfma_f32_16x16x32_bf16 v[46:49], v[164:167], v[180:183], v[46:49]
	v_mfma_f32_16x16x32_bf16 v[42:45], v[172:175], v[180:183], v[42:45]
	v_mfma_f32_16x16x32_bf16 v[30:33], v[164:167], v[188:191], v[30:33]
	v_mfma_f32_16x16x32_bf16 v[26:29], v[172:175], v[188:191], v[26:29]
	v_mfma_f32_16x16x32_bf16 v[14:17], v[164:167], v[196:199], v[14:17]
	v_mfma_f32_16x16x32_bf16 v[10:13], v[172:175], v[196:199], v[10:13]
	v_mfma_f32_16x16x32_bf16 v[6:9], v[164:167], v[204:207], v[6:9]
	v_mfma_f32_16x16x32_bf16 v[2:5], v[172:175], v[204:207], v[2:5]
	s_setprio 0
	s_barrier
	s_add_i32 s17, 0, 0x18000
	s_add_i32 s48, 0, 0x1c000
	v_add_u32_e32 v156, s17, v140
	v_add_u32_e32 v172, s48, v140
	ds_read_b128 v[144:147], v156
	ds_read_b128 v[148:151], v156 offset:1024
	ds_read_b128 v[152:155], v156 offset:2048
	ds_read_b128 v[156:159], v156 offset:3072
	ds_read_b128 v[160:163], v172
	ds_read_b128 v[164:167], v172 offset:1024
	ds_read_b128 v[168:171], v172 offset:2048
	ds_read_b128 v[172:175], v172 offset:3072
	s_add_u32 s38, s38, 0x80000
	s_addc_u32 s39, s39, 0
	s_mov_b32 m0, s42
	v_lshl_add_u64 v[224:225], s[38:39], 0, v[134:135]
	ds_read_b128 v[176:179], v143 offset:32768
	ds_read_b128 v[180:183], v143 offset:33792
	ds_read_b128 v[184:187], v143 offset:34816
	ds_read_b128 v[188:191], v143 offset:35840
	ds_read_b128 v[192:195], v143 offset:36864
	ds_read_b128 v[196:199], v143 offset:37888
	ds_read_b128 v[200:203], v143 offset:38912
	ds_read_b128 v[204:207], v143 offset:39936
	global_load_lds_dwordx4 v[224:225], off
	v_lshl_add_u64 v[224:225], s[38:39], 0, v[132:133]
	s_mov_b32 m0, s43
	s_nop 0
	global_load_lds_dwordx4 v[224:225], off
	s_waitcnt vmcnt(8)
	s_waitcnt lgkmcnt(0)
	s_barrier
	s_setprio 1
	s_waitcnt lgkmcnt(0)
	v_mfma_f32_16x16x32_bf16 v[126:129], v[144:147], v[176:179], v[126:129]
	v_mfma_f32_16x16x32_bf16 v[122:125], v[152:155], v[176:179], v[122:125]
	v_mfma_f32_16x16x32_bf16 v[118:121], v[144:147], v[184:187], v[118:121]
	v_mfma_f32_16x16x32_bf16 v[114:117], v[152:155], v[184:187], v[114:117]
	v_mfma_f32_16x16x32_bf16 v[102:105], v[144:147], v[192:195], v[102:105]
	v_mfma_f32_16x16x32_bf16 v[98:101], v[152:155], v[192:195], v[98:101]
	v_mfma_f32_16x16x32_bf16 v[86:89], v[144:147], v[200:203], v[86:89]
	v_mfma_f32_16x16x32_bf16 v[82:85], v[152:155], v[200:203], v[82:85]
	v_mfma_f32_16x16x32_bf16 v[126:129], v[148:151], v[180:183], v[126:129]
	v_mfma_f32_16x16x32_bf16 v[122:125], v[156:159], v[180:183], v[122:125]
	v_mfma_f32_16x16x32_bf16 v[118:121], v[148:151], v[188:191], v[118:121]
	v_mfma_f32_16x16x32_bf16 v[114:117], v[156:159], v[188:191], v[114:117]
	v_mfma_f32_16x16x32_bf16 v[102:105], v[148:151], v[196:199], v[102:105]
	v_mfma_f32_16x16x32_bf16 v[98:101], v[156:159], v[196:199], v[98:101]
	v_mfma_f32_16x16x32_bf16 v[86:89], v[148:151], v[204:207], v[86:89]
	v_mfma_f32_16x16x32_bf16 v[82:85], v[156:159], v[204:207], v[82:85]
	s_setprio 0
	s_setprio 1
	v_mfma_f32_16x16x32_bf16 v[110:113], v[160:163], v[176:179], v[110:113]
	v_mfma_f32_16x16x32_bf16 v[106:109], v[168:171], v[176:179], v[106:109]
	v_mfma_f32_16x16x32_bf16 v[94:97], v[160:163], v[184:187], v[94:97]
	v_mfma_f32_16x16x32_bf16 v[90:93], v[168:171], v[184:187], v[90:93]
	v_mfma_f32_16x16x32_bf16 v[78:81], v[160:163], v[192:195], v[78:81]
	v_mfma_f32_16x16x32_bf16 v[74:77], v[168:171], v[192:195], v[74:77]
	v_mfma_f32_16x16x32_bf16 v[70:73], v[160:163], v[200:203], v[70:73]
	v_mfma_f32_16x16x32_bf16 v[66:69], v[168:171], v[200:203], v[66:69]
	v_mfma_f32_16x16x32_bf16 v[110:113], v[164:167], v[180:183], v[110:113]
	v_mfma_f32_16x16x32_bf16 v[106:109], v[172:175], v[180:183], v[106:109]
	v_mfma_f32_16x16x32_bf16 v[94:97], v[164:167], v[188:191], v[94:97]
	v_mfma_f32_16x16x32_bf16 v[90:93], v[172:175], v[188:191], v[90:93]
	v_mfma_f32_16x16x32_bf16 v[78:81], v[164:167], v[196:199], v[78:81]
	v_mfma_f32_16x16x32_bf16 v[74:77], v[172:175], v[196:199], v[74:77]
	v_mfma_f32_16x16x32_bf16 v[70:73], v[164:167], v[204:207], v[70:73]
	v_mfma_f32_16x16x32_bf16 v[66:69], v[172:175], v[204:207], v[66:69]
	s_setprio 0
	s_barrier
	s_add_i32 s17, s17, s40
	v_lshl_add_u64 v[208:209], v[208:209], 0, s[2:3]
	s_mov_b32 m0, s17
	ds_read_b128 v[176:179], v143 offset:49152
	ds_read_b128 v[180:183], v143 offset:50176
	ds_read_b128 v[184:187], v143 offset:51200
	ds_read_b128 v[188:191], v143 offset:52224
	ds_read_b128 v[192:195], v143 offset:53248
	ds_read_b128 v[196:199], v143 offset:54272
	ds_read_b128 v[200:203], v143 offset:55296
	ds_read_b128 v[204:207], v143 offset:56320
	global_load_lds_dwordx4 v[208:209], off
	s_add_i32 m0, s17, 0x2000
	s_add_u32 s22, s22, 0x80080
	v_lshl_add_u64 v[208:209], v[216:217], 0, s[2:3]
	s_addc_u32 s23, s23, 0
	s_add_i32 s17, s48, s40
	global_load_lds_dwordx4 v[208:209], off
	v_lshl_add_u64 v[208:209], s[22:23], 0, v[0:1]
	s_mov_b32 m0, s17
	s_nop 0
	global_load_lds_dwordx4 v[208:209], off
	v_lshl_add_u64 v[208:209], s[22:23], 0, v[130:131]
	s_add_i32 m0, s17, 0x2000
	s_nop 0
	global_load_lds_dwordx4 v[208:209], off
	v_lshl_add_u64 v[208:209], v[220:221], 0, s[2:3]
	s_mov_b32 m0, s44
	s_nop 0
	global_load_lds_dwordx4 v[208:209], off
	v_lshl_add_u64 v[208:209], v[222:223], 0, s[2:3]
	s_mov_b32 m0, s45
	s_nop 0
	global_load_lds_dwordx4 v[208:209], off
	s_waitcnt vmcnt(8)
	s_waitcnt lgkmcnt(0)
	s_barrier
	s_setprio 1
	s_waitcnt lgkmcnt(0)
	v_mfma_f32_16x16x32_bf16 v[62:65], v[144:147], v[176:179], v[62:65]
	v_mfma_f32_16x16x32_bf16 v[58:61], v[152:155], v[176:179], v[58:61]
	v_mfma_f32_16x16x32_bf16 v[54:57], v[144:147], v[184:187], v[54:57]
	v_mfma_f32_16x16x32_bf16 v[50:53], v[152:155], v[184:187], v[50:53]
	v_mfma_f32_16x16x32_bf16 v[38:41], v[144:147], v[192:195], v[38:41]
	v_mfma_f32_16x16x32_bf16 v[34:37], v[152:155], v[192:195], v[34:37]
	v_mfma_f32_16x16x32_bf16 v[22:25], v[144:147], v[200:203], v[22:25]
	v_mfma_f32_16x16x32_bf16 v[18:21], v[152:155], v[200:203], v[18:21]
	v_mfma_f32_16x16x32_bf16 v[62:65], v[148:151], v[180:183], v[62:65]
	v_mfma_f32_16x16x32_bf16 v[58:61], v[156:159], v[180:183], v[58:61]
	v_mfma_f32_16x16x32_bf16 v[54:57], v[148:151], v[188:191], v[54:57]
	v_mfma_f32_16x16x32_bf16 v[50:53], v[156:159], v[188:191], v[50:53]
	v_mfma_f32_16x16x32_bf16 v[38:41], v[148:151], v[196:199], v[38:41]
	v_mfma_f32_16x16x32_bf16 v[34:37], v[156:159], v[196:199], v[34:37]
	v_mfma_f32_16x16x32_bf16 v[22:25], v[148:151], v[204:207], v[22:25]
	v_mfma_f32_16x16x32_bf16 v[18:21], v[156:159], v[204:207], v[18:21]
	s_setprio 0
	s_setprio 1
	v_mfma_f32_16x16x32_bf16 v[46:49], v[160:163], v[176:179], v[46:49]
	v_mfma_f32_16x16x32_bf16 v[42:45], v[168:171], v[176:179], v[42:45]
	v_mfma_f32_16x16x32_bf16 v[30:33], v[160:163], v[184:187], v[30:33]
	v_mfma_f32_16x16x32_bf16 v[26:29], v[168:171], v[184:187], v[26:29]
	v_mfma_f32_16x16x32_bf16 v[14:17], v[160:163], v[192:195], v[14:17]
	v_mfma_f32_16x16x32_bf16 v[10:13], v[168:171], v[192:195], v[10:13]
	v_mfma_f32_16x16x32_bf16 v[6:9], v[160:163], v[200:203], v[6:9]
	v_mfma_f32_16x16x32_bf16 v[2:5], v[168:171], v[200:203], v[2:5]
	v_mfma_f32_16x16x32_bf16 v[46:49], v[164:167], v[180:183], v[46:49]
	v_mfma_f32_16x16x32_bf16 v[42:45], v[172:175], v[180:183], v[42:45]
	v_mfma_f32_16x16x32_bf16 v[30:33], v[164:167], v[188:191], v[30:33]
	v_mfma_f32_16x16x32_bf16 v[26:29], v[172:175], v[188:191], v[26:29]
	v_mfma_f32_16x16x32_bf16 v[14:17], v[164:167], v[196:199], v[14:17]
	v_mfma_f32_16x16x32_bf16 v[10:13], v[172:175], v[196:199], v[10:13]
	v_mfma_f32_16x16x32_bf16 v[6:9], v[164:167], v[204:207], v[6:9]
	v_mfma_f32_16x16x32_bf16 v[2:5], v[172:175], v[204:207], v[2:5]
	s_setprio 0
	s_barrier
	s_add_i32 s15, s15, 2
	s_add_u32 s36, s36, 0x100
	s_addc_u32 s37, s37, 0
	s_add_u32 s5, s5, 0x100
	s_addc_u32 s13, s13, 0
	s_cmp_gt_u32 s15, 5
	s_cbranch_scc0 .LBB0_990
.Lpeel_done_2:
	s_and_b64 vcc, exec, s[10:11]
	s_cbranch_vccz .LBB0_993
	s_barrier

.LBB0_1200:
	s_ashr_i32 s7, s6, 31
	s_lshl_b64 s[12:13], s[6:7], 18
	s_add_u32 s12, s78, s12
	v_readlane_b32 s7, v254, 37
	s_addc_u32 s13, s7, s13
	s_and_b64 s[22:23], s[22:23], exec
	s_cselect_b32 s7, s13, s21
	s_cselect_b32 s9, s12, s20
	s_add_u32 s18, s18, 0x80080
	s_addc_u32 s19, s19, 0
	s_add_u32 s15, s20, 0x100
	s_addc_u32 s36, s21, 0
	s_mov_b32 s37, -2
	s_add_u32 s20, s18, 0xfff80080
	s_addc_u32 s21, s19, -1
	s_add_i32 s47, 0, 0x10000
	s_cmp_eq_u32 s37, 4
	s_cselect_b32 s23, s11, s21
	s_cselect_b32 s22, s10, s20
	s_cselect_b32 s21, s7, s36
	s_cselect_b32 s20, s9, s15
	s_add_i32 s50, 0, 0x14000
	v_add_u32_e32 v142, s47, v171
	v_add_u32_e32 v168, s50, v171
	ds_read_b128 v[130:133], v142
	ds_read_b128 v[134:137], v142 offset:1024
	ds_read_b128 v[138:141], v142 offset:2048
	ds_read_b128 v[142:145], v142 offset:3072
	ds_read_b128 v[156:159], v168
	ds_read_b128 v[160:163], v168 offset:1024
	ds_read_b128 v[164:167], v168 offset:2048
	ds_read_b128 v[174:177], v168 offset:3072
	v_lshl_add_u64 v[168:169], s[18:19], 0, v[152:153]
	s_add_i32 m0, s17, 0xc000
	ds_read_b128 v[178:181], v173
	ds_read_b128 v[182:185], v173 offset:1024
	ds_read_b128 v[186:189], v173 offset:2048
	ds_read_b128 v[190:193], v173 offset:3072
	ds_read_b128 v[194:197], v173 offset:4096
	ds_read_b128 v[198:201], v173 offset:5120
	ds_read_b128 v[202:205], v173 offset:6144
	ds_read_b128 v[206:209], v173 offset:7168
	global_load_lds_dwordx4 v[168:169], off
	v_lshl_add_u64 v[168:169], s[18:19], 0, v[154:155]
	s_add_i32 m0, s17, 0xe000
	s_nop 0
	global_load_lds_dwordx4 v[168:169], off
	s_waitcnt vmcnt(8)
	s_waitcnt lgkmcnt(0)
	s_barrier
	s_setprio 1
	s_waitcnt lgkmcnt(0)
	v_mfma_f32_16x16x32_bf16 v[126:129], v[130:133], v[178:181], 0
	v_mfma_f32_16x16x32_bf16 v[122:125], v[138:141], v[178:181], 0
	v_mfma_f32_16x16x32_bf16 v[118:121], v[130:133], v[186:189], 0
	v_mfma_f32_16x16x32_bf16 v[106:109], v[138:141], v[186:189], 0
	v_mfma_f32_16x16x32_bf16 v[98:101], v[130:133], v[194:197], 0
	v_mfma_f32_16x16x32_bf16 v[90:93], v[138:141], v[194:197], 0
	v_mfma_f32_16x16x32_bf16 v[82:85], v[130:133], v[202:205], 0
	v_mfma_f32_16x16x32_bf16 v[74:77], v[138:141], v[202:205], 0
	v_mfma_f32_16x16x32_bf16 v[126:129], v[134:137], v[182:185], v[126:129]
	v_mfma_f32_16x16x32_bf16 v[122:125], v[142:145], v[182:185], v[122:125]
	v_mfma_f32_16x16x32_bf16 v[118:121], v[134:137], v[190:193], v[118:121]
	v_mfma_f32_16x16x32_bf16 v[106:109], v[142:145], v[190:193], v[106:109]
	v_mfma_f32_16x16x32_bf16 v[98:101], v[134:137], v[198:201], v[98:101]
	v_mfma_f32_16x16x32_bf16 v[90:93], v[142:145], v[198:201], v[90:93]
	v_mfma_f32_16x16x32_bf16 v[82:85], v[134:137], v[206:209], v[82:85]
	v_mfma_f32_16x16x32_bf16 v[74:77], v[142:145], v[206:209], v[74:77]
	s_setprio 0
	s_setprio 1
	v_mfma_f32_16x16x32_bf16 v[114:117], v[156:159], v[178:181], 0
	v_mfma_f32_16x16x32_bf16 v[110:113], v[164:167], v[178:181], 0
	v_mfma_f32_16x16x32_bf16 v[102:105], v[156:159], v[186:189], 0
	v_mfma_f32_16x16x32_bf16 v[94:97], v[164:167], v[186:189], 0
	v_mfma_f32_16x16x32_bf16 v[86:89], v[156:159], v[194:197], 0
	v_mfma_f32_16x16x32_bf16 v[78:81], v[164:167], v[194:197], 0
	v_mfma_f32_16x16x32_bf16 v[70:73], v[156:159], v[202:205], 0
	v_mfma_f32_16x16x32_bf16 v[66:69], v[164:167], v[202:205], 0
	v_mfma_f32_16x16x32_bf16 v[114:117], v[160:163], v[182:185], v[114:117]
	v_mfma_f32_16x16x32_bf16 v[110:113], v[174:177], v[182:185], v[110:113]
	v_mfma_f32_16x16x32_bf16 v[102:105], v[160:163], v[190:193], v[102:105]
	v_mfma_f32_16x16x32_bf16 v[94:97], v[174:177], v[190:193], v[94:97]
	v_mfma_f32_16x16x32_bf16 v[86:89], v[160:163], v[198:201], v[86:89]
	v_mfma_f32_16x16x32_bf16 v[78:81], v[174:177], v[198:201], v[78:81]
	v_mfma_f32_16x16x32_bf16 v[70:73], v[160:163], v[206:209], v[70:73]
	v_mfma_f32_16x16x32_bf16 v[66:69], v[174:177], v[206:209], v[66:69]
	s_setprio 0
	s_barrier
	s_add_i32 s47, s47, s38
	v_lshl_add_u64 v[168:169], s[20:21], 0, v[0:1]
	s_mov_b32 m0, s47
	ds_read_b128 v[178:181], v173 offset:16384
	ds_read_b128 v[182:185], v173 offset:17408
	ds_read_b128 v[186:189], v173 offset:18432
	ds_read_b128 v[190:193], v173 offset:19456
	ds_read_b128 v[194:197], v173 offset:20480
	ds_read_b128 v[198:201], v173 offset:21504
	ds_read_b128 v[202:205], v173 offset:22528
	ds_read_b128 v[206:209], v173 offset:23552
	global_load_lds_dwordx4 v[168:169], off
	s_add_i32 m0, s47, 0x2000
	s_add_u32 s48, s20, 0x20000
	v_lshl_add_u64 v[216:217], s[20:21], 0, v[146:147]
	s_addc_u32 s49, s21, 0
	s_add_i32 s47, s50, s38
	global_load_lds_dwordx4 v[216:217], off
	v_lshl_add_u64 v[220:221], s[48:49], 0, v[0:1]
	s_mov_b32 m0, s47
	v_lshl_add_u64 v[222:223], s[22:23], 0, v[148:149]
	global_load_lds_dwordx4 v[220:221], off
	v_lshl_add_u64 v[220:221], s[48:49], 0, v[146:147]
	s_add_i32 m0, s47, 0x2000
	s_nop 0
	global_load_lds_dwordx4 v[220:221], off
	v_lshl_add_u64 v[220:221], s[22:23], 0, v[150:151]
	s_mov_b32 m0, s17
	s_nop 0
	global_load_lds_dwordx4 v[220:221], off
	s_mov_b32 m0, s40
	s_nop 0
	global_load_lds_dwordx4 v[222:223], off
	s_waitcnt vmcnt(8)
	s_waitcnt lgkmcnt(0)
	s_barrier
	s_setprio 1
	s_waitcnt lgkmcnt(0)
	v_mfma_f32_16x16x32_bf16 v[62:65], v[130:133], v[178:181], 0
	v_mfma_f32_16x16x32_bf16 v[58:61], v[138:141], v[178:181], 0
	v_mfma_f32_16x16x32_bf16 v[50:53], v[130:133], v[186:189], 0
	v_mfma_f32_16x16x32_bf16 v[42:45], v[138:141], v[186:189], 0
	v_mfma_f32_16x16x32_bf16 v[34:37], v[130:133], v[194:197], 0
	v_mfma_f32_16x16x32_bf16 v[26:29], v[138:141], v[194:197], 0
	v_mfma_f32_16x16x32_bf16 v[18:21], v[130:133], v[202:205], 0
	v_mfma_f32_16x16x32_bf16 v[10:13], v[138:141], v[202:205], 0
	v_mfma_f32_16x16x32_bf16 v[62:65], v[134:137], v[182:185], v[62:65]
	v_mfma_f32_16x16x32_bf16 v[58:61], v[142:145], v[182:185], v[58:61]
	v_mfma_f32_16x16x32_bf16 v[50:53], v[134:137], v[190:193], v[50:53]
	v_mfma_f32_16x16x32_bf16 v[42:45], v[142:145], v[190:193], v[42:45]
	v_mfma_f32_16x16x32_bf16 v[34:37], v[134:137], v[198:201], v[34:37]
	v_mfma_f32_16x16x32_bf16 v[26:29], v[142:145], v[198:201], v[26:29]
	v_mfma_f32_16x16x32_bf16 v[18:21], v[134:137], v[206:209], v[18:21]
	v_mfma_f32_16x16x32_bf16 v[10:13], v[142:145], v[206:209], v[10:13]
	s_setprio 0
	s_setprio 1
	v_mfma_f32_16x16x32_bf16 v[54:57], v[156:159], v[178:181], 0
	v_mfma_f32_16x16x32_bf16 v[46:49], v[164:167], v[178:181], 0
	v_mfma_f32_16x16x32_bf16 v[38:41], v[156:159], v[186:189], 0
	v_mfma_f32_16x16x32_bf16 v[30:33], v[164:167], v[186:189], 0
	v_mfma_f32_16x16x32_bf16 v[22:25], v[156:159], v[194:197], 0
	v_mfma_f32_16x16x32_bf16 v[14:17], v[164:167], v[194:197], 0
	v_mfma_f32_16x16x32_bf16 v[6:9], v[156:159], v[202:205], 0
	v_mfma_f32_16x16x32_bf16 v[2:5], v[164:167], v[202:205], 0
	v_mfma_f32_16x16x32_bf16 v[54:57], v[160:163], v[182:185], v[54:57]
	v_mfma_f32_16x16x32_bf16 v[46:49], v[174:177], v[182:185], v[46:49]
	v_mfma_f32_16x16x32_bf16 v[38:41], v[160:163], v[190:193], v[38:41]
	v_mfma_f32_16x16x32_bf16 v[30:33], v[174:177], v[190:193], v[30:33]
	v_mfma_f32_16x16x32_bf16 v[22:25], v[160:163], v[198:201], v[22:25]
	v_mfma_f32_16x16x32_bf16 v[14:17], v[174:177], v[198:201], v[14:17]
	v_mfma_f32_16x16x32_bf16 v[6:9], v[160:163], v[206:209], v[6:9]
	v_mfma_f32_16x16x32_bf16 v[2:5], v[174:177], v[206:209], v[2:5]
	s_setprio 0
	s_barrier
	s_add_i32 s47, 0, 0x18000
	s_add_i32 s48, 0, 0x1c000
	v_add_u32_e32 v142, s47, v171
	v_add_u32_e32 v174, s48, v171
	ds_read_b128 v[130:133], v142
	ds_read_b128 v[134:137], v142 offset:1024
	ds_read_b128 v[138:141], v142 offset:2048
	ds_read_b128 v[142:145], v142 offset:3072
	ds_read_b128 v[156:159], v174
	ds_read_b128 v[160:163], v174 offset:1024
	ds_read_b128 v[164:167], v174 offset:2048
	ds_read_b128 v[174:177], v174 offset:3072
	s_add_u32 s22, s22, 0x80000
	s_addc_u32 s23, s23, 0
	s_mov_b32 m0, s41
	v_lshl_add_u64 v[224:225], s[22:23], 0, v[150:151]
	ds_read_b128 v[178:181], v173 offset:32768
	ds_read_b128 v[182:185], v173 offset:33792
	ds_read_b128 v[186:189], v173 offset:34816
	ds_read_b128 v[190:193], v173 offset:35840
	ds_read_b128 v[194:197], v173 offset:36864
	ds_read_b128 v[198:201], v173 offset:37888
	ds_read_b128 v[202:205], v173 offset:38912
	ds_read_b128 v[206:209], v173 offset:39936
	global_load_lds_dwordx4 v[224:225], off
	v_lshl_add_u64 v[224:225], s[22:23], 0, v[148:149]
	s_mov_b32 m0, s42
	s_nop 0
	global_load_lds_dwordx4 v[224:225], off
	s_waitcnt vmcnt(8)
	s_waitcnt lgkmcnt(0)
	s_barrier
	s_setprio 1
	s_waitcnt lgkmcnt(0)
	v_mfma_f32_16x16x32_bf16 v[126:129], v[130:133], v[178:181], v[126:129]
	v_mfma_f32_16x16x32_bf16 v[122:125], v[138:141], v[178:181], v[122:125]
	v_mfma_f32_16x16x32_bf16 v[118:121], v[130:133], v[186:189], v[118:121]
	v_mfma_f32_16x16x32_bf16 v[106:109], v[138:141], v[186:189], v[106:109]
	v_mfma_f32_16x16x32_bf16 v[98:101], v[130:133], v[194:197], v[98:101]
	v_mfma_f32_16x16x32_bf16 v[90:93], v[138:141], v[194:197], v[90:93]
	v_mfma_f32_16x16x32_bf16 v[82:85], v[130:133], v[202:205], v[82:85]
	v_mfma_f32_16x16x32_bf16 v[74:77], v[138:141], v[202:205], v[74:77]
	v_mfma_f32_16x16x32_bf16 v[126:129], v[134:137], v[182:185], v[126:129]
	v_mfma_f32_16x16x32_bf16 v[122:125], v[142:145], v[182:185], v[122:125]
	v_mfma_f32_16x16x32_bf16 v[118:121], v[134:137], v[190:193], v[118:121]
	v_mfma_f32_16x16x32_bf16 v[106:109], v[142:145], v[190:193], v[106:109]
	v_mfma_f32_16x16x32_bf16 v[98:101], v[134:137], v[198:201], v[98:101]
	v_mfma_f32_16x16x32_bf16 v[90:93], v[142:145], v[198:201], v[90:93]
	v_mfma_f32_16x16x32_bf16 v[82:85], v[134:137], v[206:209], v[82:85]
	v_mfma_f32_16x16x32_bf16 v[74:77], v[142:145], v[206:209], v[74:77]
	s_setprio 0
	s_setprio 1
	v_mfma_f32_16x16x32_bf16 v[114:117], v[156:159], v[178:181], v[114:117]
	v_mfma_f32_16x16x32_bf16 v[110:113], v[164:167], v[178:181], v[110:113]
	v_mfma_f32_16x16x32_bf16 v[102:105], v[156:159], v[186:189], v[102:105]
	v_mfma_f32_16x16x32_bf16 v[94:97], v[164:167], v[186:189], v[94:97]
	v_mfma_f32_16x16x32_bf16 v[86:89], v[156:159], v[194:197], v[86:89]
	v_mfma_f32_16x16x32_bf16 v[78:81], v[164:167], v[194:197], v[78:81]
	v_mfma_f32_16x16x32_bf16 v[70:73], v[156:159], v[202:205], v[70:73]
	v_mfma_f32_16x16x32_bf16 v[66:69], v[164:167], v[202:205], v[66:69]
	v_mfma_f32_16x16x32_bf16 v[114:117], v[160:163], v[182:185], v[114:117]
	v_mfma_f32_16x16x32_bf16 v[110:113], v[174:177], v[182:185], v[110:113]
	v_mfma_f32_16x16x32_bf16 v[102:105], v[160:163], v[190:193], v[102:105]
	v_mfma_f32_16x16x32_bf16 v[94:97], v[174:177], v[190:193], v[94:97]
	v_mfma_f32_16x16x32_bf16 v[86:89], v[160:163], v[198:201], v[86:89]
	v_mfma_f32_16x16x32_bf16 v[78:81], v[174:177], v[198:201], v[78:81]
	v_mfma_f32_16x16x32_bf16 v[70:73], v[160:163], v[206:209], v[70:73]
	v_mfma_f32_16x16x32_bf16 v[66:69], v[174:177], v[206:209], v[66:69]
	s_setprio 0
	s_barrier
	s_add_i32 s22, s47, s38
	v_lshl_add_u64 v[168:169], v[168:169], 0, s[2:3]
	s_mov_b32 m0, s22
	ds_read_b128 v[178:181], v173 offset:49152
	ds_read_b128 v[182:185], v173 offset:50176
	ds_read_b128 v[186:189], v173 offset:51200
	ds_read_b128 v[190:193], v173 offset:52224
	ds_read_b128 v[194:197], v173 offset:53248
	ds_read_b128 v[198:201], v173 offset:54272
	ds_read_b128 v[202:205], v173 offset:55296
	ds_read_b128 v[206:209], v173 offset:56320
	global_load_lds_dwordx4 v[168:169], off
	s_add_i32 m0, s22, 0x2000
	s_add_u32 s20, s20, 0x20080
	v_lshl_add_u64 v[168:169], v[216:217], 0, s[2:3]
	s_addc_u32 s21, s21, 0
	s_add_i32 s22, s48, s38
	global_load_lds_dwordx4 v[168:169], off
	v_lshl_add_u64 v[168:169], s[20:21], 0, v[0:1]
	s_mov_b32 m0, s22
	s_nop 0
	global_load_lds_dwordx4 v[168:169], off
	v_lshl_add_u64 v[168:169], s[20:21], 0, v[146:147]
	s_add_i32 m0, s22, 0x2000
	s_nop 0
	global_load_lds_dwordx4 v[168:169], off
	v_lshl_add_u64 v[168:169], v[220:221], 0, s[2:3]
	s_mov_b32 m0, s43
	s_nop 0
	global_load_lds_dwordx4 v[168:169], off
	v_lshl_add_u64 v[168:169], v[222:223], 0, s[2:3]
	s_mov_b32 m0, s44
	s_nop 0
	global_load_lds_dwordx4 v[168:169], off
	s_waitcnt vmcnt(8)
	s_waitcnt lgkmcnt(0)
	s_barrier
	s_setprio 1
	s_waitcnt lgkmcnt(0)
	v_mfma_f32_16x16x32_bf16 v[62:65], v[130:133], v[178:181], v[62:65]
	v_mfma_f32_16x16x32_bf16 v[58:61], v[138:141], v[178:181], v[58:61]
	v_mfma_f32_16x16x32_bf16 v[50:53], v[130:133], v[186:189], v[50:53]
	v_mfma_f32_16x16x32_bf16 v[42:45], v[138:141], v[186:189], v[42:45]
	v_mfma_f32_16x16x32_bf16 v[34:37], v[130:133], v[194:197], v[34:37]
	v_mfma_f32_16x16x32_bf16 v[26:29], v[138:141], v[194:197], v[26:29]
	v_mfma_f32_16x16x32_bf16 v[18:21], v[130:133], v[202:205], v[18:21]
	v_mfma_f32_16x16x32_bf16 v[10:13], v[138:141], v[202:205], v[10:13]
	v_mfma_f32_16x16x32_bf16 v[62:65], v[134:137], v[182:185], v[62:65]
	v_mfma_f32_16x16x32_bf16 v[58:61], v[142:145], v[182:185], v[58:61]
	v_mfma_f32_16x16x32_bf16 v[50:53], v[134:137], v[190:193], v[50:53]
	v_mfma_f32_16x16x32_bf16 v[42:45], v[142:145], v[190:193], v[42:45]
	v_mfma_f32_16x16x32_bf16 v[34:37], v[134:137], v[198:201], v[34:37]
	v_mfma_f32_16x16x32_bf16 v[26:29], v[142:145], v[198:201], v[26:29]
	v_mfma_f32_16x16x32_bf16 v[18:21], v[134:137], v[206:209], v[18:21]
	v_mfma_f32_16x16x32_bf16 v[10:13], v[142:145], v[206:209], v[10:13]
	s_setprio 0
	s_setprio 1
	v_mfma_f32_16x16x32_bf16 v[54:57], v[156:159], v[178:181], v[54:57]
	v_mfma_f32_16x16x32_bf16 v[46:49], v[164:167], v[178:181], v[46:49]
	v_mfma_f32_16x16x32_bf16 v[38:41], v[156:159], v[186:189], v[38:41]
	v_mfma_f32_16x16x32_bf16 v[30:33], v[164:167], v[186:189], v[30:33]
	v_mfma_f32_16x16x32_bf16 v[22:25], v[156:159], v[194:197], v[22:25]
	v_mfma_f32_16x16x32_bf16 v[14:17], v[164:167], v[194:197], v[14:17]
	v_mfma_f32_16x16x32_bf16 v[6:9], v[156:159], v[202:205], v[6:9]
	v_mfma_f32_16x16x32_bf16 v[2:5], v[164:167], v[202:205], v[2:5]
	v_mfma_f32_16x16x32_bf16 v[54:57], v[160:163], v[182:185], v[54:57]
	v_mfma_f32_16x16x32_bf16 v[46:49], v[174:177], v[182:185], v[46:49]
	v_mfma_f32_16x16x32_bf16 v[38:41], v[160:163], v[190:193], v[38:41]
	v_mfma_f32_16x16x32_bf16 v[30:33], v[174:177], v[190:193], v[30:33]
	v_mfma_f32_16x16x32_bf16 v[22:25], v[160:163], v[198:201], v[22:25]
	v_mfma_f32_16x16x32_bf16 v[14:17], v[174:177], v[198:201], v[14:17]
	v_mfma_f32_16x16x32_bf16 v[6:9], v[160:163], v[206:209], v[6:9]
	v_mfma_f32_16x16x32_bf16 v[2:5], v[174:177], v[206:209], v[2:5]
	s_setprio 0
	s_barrier
	s_add_i32 s37, s37, 2
	s_add_u32 s18, s18, 0x100
	s_addc_u32 s19, s19, 0
	s_add_u32 s15, s15, 0x100
	s_addc_u32 s36, s36, 0
	s_cmp_gt_u32 s37, 5
	s_cbranch_scc1 .Lpeel_done_3
.LBB0_1201:
	s_add_u32 s20, s18, 0xfff80080
	s_addc_u32 s21, s19, -1
	s_add_i32 s47, 0, 0x10000
	s_cmp_eq_u32 s37, 4
	s_cselect_b32 s23, s11, s21
	s_cselect_b32 s22, s10, s20
	s_cselect_b32 s21, s7, s36
	s_cselect_b32 s20, s9, s15
	s_add_i32 s50, 0, 0x14000
	v_add_u32_e32 v142, s47, v171
	v_add_u32_e32 v168, s50, v171
	ds_read_b128 v[130:133], v142
	ds_read_b128 v[134:137], v142 offset:1024
	ds_read_b128 v[138:141], v142 offset:2048
	ds_read_b128 v[142:145], v142 offset:3072
	ds_read_b128 v[156:159], v168
	ds_read_b128 v[160:163], v168 offset:1024
	ds_read_b128 v[164:167], v168 offset:2048
	ds_read_b128 v[174:177], v168 offset:3072
	v_lshl_add_u64 v[168:169], s[18:19], 0, v[152:153]
	s_add_i32 m0, s17, 0xc000
	ds_read_b128 v[178:181], v173
	ds_read_b128 v[182:185], v173 offset:1024
	ds_read_b128 v[186:189], v173 offset:2048
	ds_read_b128 v[190:193], v173 offset:3072
	ds_read_b128 v[194:197], v173 offset:4096
	ds_read_b128 v[198:201], v173 offset:5120
	ds_read_b128 v[202:205], v173 offset:6144
	ds_read_b128 v[206:209], v173 offset:7168
	global_load_lds_dwordx4 v[168:169], off
	v_lshl_add_u64 v[168:169], s[18:19], 0, v[154:155]
	s_add_i32 m0, s17, 0xe000
	s_nop 0
	global_load_lds_dwordx4 v[168:169], off
	s_waitcnt vmcnt(8)
	s_waitcnt lgkmcnt(0)
	s_barrier
	s_setprio 1
	s_waitcnt lgkmcnt(0)
	v_mfma_f32_16x16x32_bf16 v[126:129], v[130:133], v[178:181], v[126:129]
	v_mfma_f32_16x16x32_bf16 v[122:125], v[138:141], v[178:181], v[122:125]
	v_mfma_f32_16x16x32_bf16 v[118:121], v[130:133], v[186:189], v[118:121]
	v_mfma_f32_16x16x32_bf16 v[106:109], v[138:141], v[186:189], v[106:109]
	v_mfma_f32_16x16x32_bf16 v[98:101], v[130:133], v[194:197], v[98:101]
	v_mfma_f32_16x16x32_bf16 v[90:93], v[138:141], v[194:197], v[90:93]
	v_mfma_f32_16x16x32_bf16 v[82:85], v[130:133], v[202:205], v[82:85]
	v_mfma_f32_16x16x32_bf16 v[74:77], v[138:141], v[202:205], v[74:77]
	v_mfma_f32_16x16x32_bf16 v[126:129], v[134:137], v[182:185], v[126:129]
	v_mfma_f32_16x16x32_bf16 v[122:125], v[142:145], v[182:185], v[122:125]
	v_mfma_f32_16x16x32_bf16 v[118:121], v[134:137], v[190:193], v[118:121]
	v_mfma_f32_16x16x32_bf16 v[106:109], v[142:145], v[190:193], v[106:109]
	v_mfma_f32_16x16x32_bf16 v[98:101], v[134:137], v[198:201], v[98:101]
	v_mfma_f32_16x16x32_bf16 v[90:93], v[142:145], v[198:201], v[90:93]
	v_mfma_f32_16x16x32_bf16 v[82:85], v[134:137], v[206:209], v[82:85]
	v_mfma_f32_16x16x32_bf16 v[74:77], v[142:145], v[206:209], v[74:77]
	s_setprio 0
	s_setprio 1
	v_mfma_f32_16x16x32_bf16 v[114:117], v[156:159], v[178:181], v[114:117]
	v_mfma_f32_16x16x32_bf16 v[110:113], v[164:167], v[178:181], v[110:113]
	v_mfma_f32_16x16x32_bf16 v[102:105], v[156:159], v[186:189], v[102:105]
	v_mfma_f32_16x16x32_bf16 v[94:97], v[164:167], v[186:189], v[94:97]
	v_mfma_f32_16x16x32_bf16 v[86:89], v[156:159], v[194:197], v[86:89]
	v_mfma_f32_16x16x32_bf16 v[78:81], v[164:167], v[194:197], v[78:81]
	v_mfma_f32_16x16x32_bf16 v[70:73], v[156:159], v[202:205], v[70:73]
	v_mfma_f32_16x16x32_bf16 v[66:69], v[164:167], v[202:205], v[66:69]
	v_mfma_f32_16x16x32_bf16 v[114:117], v[160:163], v[182:185], v[114:117]
	v_mfma_f32_16x16x32_bf16 v[110:113], v[174:177], v[182:185], v[110:113]
	v_mfma_f32_16x16x32_bf16 v[102:105], v[160:163], v[190:193], v[102:105]
	v_mfma_f32_16x16x32_bf16 v[94:97], v[174:177], v[190:193], v[94:97]
	v_mfma_f32_16x16x32_bf16 v[86:89], v[160:163], v[198:201], v[86:89]
	v_mfma_f32_16x16x32_bf16 v[78:81], v[174:177], v[198:201], v[78:81]
	v_mfma_f32_16x16x32_bf16 v[70:73], v[160:163], v[206:209], v[70:73]
	v_mfma_f32_16x16x32_bf16 v[66:69], v[174:177], v[206:209], v[66:69]
	s_setprio 0
	s_barrier
	s_add_i32 s47, s47, s38
	v_lshl_add_u64 v[168:169], s[20:21], 0, v[0:1]
	s_mov_b32 m0, s47
	ds_read_b128 v[178:181], v173 offset:16384
	ds_read_b128 v[182:185], v173 offset:17408
	ds_read_b128 v[186:189], v173 offset:18432
	ds_read_b128 v[190:193], v173 offset:19456
	ds_read_b128 v[194:197], v173 offset:20480
	ds_read_b128 v[198:201], v173 offset:21504
	ds_read_b128 v[202:205], v173 offset:22528
	ds_read_b128 v[206:209], v173 offset:23552
	global_load_lds_dwordx4 v[168:169], off
	s_add_i32 m0, s47, 0x2000
	s_add_u32 s48, s20, 0x20000
	v_lshl_add_u64 v[216:217], s[20:21], 0, v[146:147]
	s_addc_u32 s49, s21, 0
	s_add_i32 s47, s50, s38
	global_load_lds_dwordx4 v[216:217], off
	v_lshl_add_u64 v[220:221], s[48:49], 0, v[0:1]
	s_mov_b32 m0, s47
	v_lshl_add_u64 v[222:223], s[22:23], 0, v[148:149]
	global_load_lds_dwordx4 v[220:221], off
	v_lshl_add_u64 v[220:221], s[48:49], 0, v[146:147]
	s_add_i32 m0, s47, 0x2000
	s_nop 0
	global_load_lds_dwordx4 v[220:221], off
	v_lshl_add_u64 v[220:221], s[22:23], 0, v[150:151]
	s_mov_b32 m0, s17
	s_nop 0
	global_load_lds_dwordx4 v[220:221], off
	s_mov_b32 m0, s40
	s_nop 0
	global_load_lds_dwordx4 v[222:223], off
	s_waitcnt vmcnt(8)
	s_waitcnt lgkmcnt(0)
	s_barrier
	s_setprio 1
	s_waitcnt lgkmcnt(0)
	v_mfma_f32_16x16x32_bf16 v[62:65], v[130:133], v[178:181], v[62:65]
	v_mfma_f32_16x16x32_bf16 v[58:61], v[138:141], v[178:181], v[58:61]
	v_mfma_f32_16x16x32_bf16 v[50:53], v[130:133], v[186:189], v[50:53]
	v_mfma_f32_16x16x32_bf16 v[42:45], v[138:141], v[186:189], v[42:45]
	v_mfma_f32_16x16x32_bf16 v[34:37], v[130:133], v[194:197], v[34:37]
	v_mfma_f32_16x16x32_bf16 v[26:29], v[138:141], v[194:197], v[26:29]
	v_mfma_f32_16x16x32_bf16 v[18:21], v[130:133], v[202:205], v[18:21]
	v_mfma_f32_16x16x32_bf16 v[10:13], v[138:141], v[202:205], v[10:13]
	v_mfma_f32_16x16x32_bf16 v[62:65], v[134:137], v[182:185], v[62:65]
	v_mfma_f32_16x16x32_bf16 v[58:61], v[142:145], v[182:185], v[58:61]
	v_mfma_f32_16x16x32_bf16 v[50:53], v[134:137], v[190:193], v[50:53]
	v_mfma_f32_16x16x32_bf16 v[42:45], v[142:145], v[190:193], v[42:45]
	v_mfma_f32_16x16x32_bf16 v[34:37], v[134:137], v[198:201], v[34:37]
	v_mfma_f32_16x16x32_bf16 v[26:29], v[142:145], v[198:201], v[26:29]
	v_mfma_f32_16x16x32_bf16 v[18:21], v[134:137], v[206:209], v[18:21]
	v_mfma_f32_16x16x32_bf16 v[10:13], v[142:145], v[206:209], v[10:13]
	s_setprio 0
	s_setprio 1
	v_mfma_f32_16x16x32_bf16 v[54:57], v[156:159], v[178:181], v[54:57]
	v_mfma_f32_16x16x32_bf16 v[46:49], v[164:167], v[178:181], v[46:49]
	v_mfma_f32_16x16x32_bf16 v[38:41], v[156:159], v[186:189], v[38:41]
	v_mfma_f32_16x16x32_bf16 v[30:33], v[164:167], v[186:189], v[30:33]
	v_mfma_f32_16x16x32_bf16 v[22:25], v[156:159], v[194:197], v[22:25]
	v_mfma_f32_16x16x32_bf16 v[14:17], v[164:167], v[194:197], v[14:17]
	v_mfma_f32_16x16x32_bf16 v[6:9], v[156:159], v[202:205], v[6:9]
	v_mfma_f32_16x16x32_bf16 v[2:5], v[164:167], v[202:205], v[2:5]
	v_mfma_f32_16x16x32_bf16 v[54:57], v[160:163], v[182:185], v[54:57]
	v_mfma_f32_16x16x32_bf16 v[46:49], v[174:177], v[182:185], v[46:49]
	v_mfma_f32_16x16x32_bf16 v[38:41], v[160:163], v[190:193], v[38:41]
	v_mfma_f32_16x16x32_bf16 v[30:33], v[174:177], v[190:193], v[30:33]
	v_mfma_f32_16x16x32_bf16 v[22:25], v[160:163], v[198:201], v[22:25]
	v_mfma_f32_16x16x32_bf16 v[14:17], v[174:177], v[198:201], v[14:17]
	v_mfma_f32_16x16x32_bf16 v[6:9], v[160:163], v[206:209], v[6:9]
	v_mfma_f32_16x16x32_bf16 v[2:5], v[174:177], v[206:209], v[2:5]
	s_setprio 0
	s_barrier
	s_add_i32 s47, 0, 0x18000
	s_add_i32 s48, 0, 0x1c000
	v_add_u32_e32 v142, s47, v171
	v_add_u32_e32 v174, s48, v171
	ds_read_b128 v[130:133], v142
	ds_read_b128 v[134:137], v142 offset:1024
	ds_read_b128 v[138:141], v142 offset:2048
	ds_read_b128 v[142:145], v142 offset:3072
	ds_read_b128 v[156:159], v174
	ds_read_b128 v[160:163], v174 offset:1024
	ds_read_b128 v[164:167], v174 offset:2048
	ds_read_b128 v[174:177], v174 offset:3072
	s_add_u32 s22, s22, 0x80000
	s_addc_u32 s23, s23, 0
	s_mov_b32 m0, s41
	v_lshl_add_u64 v[224:225], s[22:23], 0, v[150:151]
	ds_read_b128 v[178:181], v173 offset:32768
	ds_read_b128 v[182:185], v173 offset:33792
	ds_read_b128 v[186:189], v173 offset:34816
	ds_read_b128 v[190:193], v173 offset:35840
	ds_read_b128 v[194:197], v173 offset:36864
	ds_read_b128 v[198:201], v173 offset:37888
	ds_read_b128 v[202:205], v173 offset:38912
	ds_read_b128 v[206:209], v173 offset:39936
	global_load_lds_dwordx4 v[224:225], off
	v_lshl_add_u64 v[224:225], s[22:23], 0, v[148:149]
	s_mov_b32 m0, s42
	s_nop 0
	global_load_lds_dwordx4 v[224:225], off
	s_waitcnt vmcnt(8)
	s_waitcnt lgkmcnt(0)
	s_barrier
	s_setprio 1
	s_waitcnt lgkmcnt(0)
	v_mfma_f32_16x16x32_bf16 v[126:129], v[130:133], v[178:181], v[126:129]
	v_mfma_f32_16x16x32_bf16 v[122:125], v[138:141], v[178:181], v[122:125]
	v_mfma_f32_16x16x32_bf16 v[118:121], v[130:133], v[186:189], v[118:121]
	v_mfma_f32_16x16x32_bf16 v[106:109], v[138:141], v[186:189], v[106:109]
	v_mfma_f32_16x16x32_bf16 v[98:101], v[130:133], v[194:197], v[98:101]
	v_mfma_f32_16x16x32_bf16 v[90:93], v[138:141], v[194:197], v[90:93]
	v_mfma_f32_16x16x32_bf16 v[82:85], v[130:133], v[202:205], v[82:85]
	v_mfma_f32_16x16x32_bf16 v[74:77], v[138:141], v[202:205], v[74:77]
	v_mfma_f32_16x16x32_bf16 v[126:129], v[134:137], v[182:185], v[126:129]
	v_mfma_f32_16x16x32_bf16 v[122:125], v[142:145], v[182:185], v[122:125]
	v_mfma_f32_16x16x32_bf16 v[118:121], v[134:137], v[190:193], v[118:121]
	v_mfma_f32_16x16x32_bf16 v[106:109], v[142:145], v[190:193], v[106:109]
	v_mfma_f32_16x16x32_bf16 v[98:101], v[134:137], v[198:201], v[98:101]
	v_mfma_f32_16x16x32_bf16 v[90:93], v[142:145], v[198:201], v[90:93]
	v_mfma_f32_16x16x32_bf16 v[82:85], v[134:137], v[206:209], v[82:85]
	v_mfma_f32_16x16x32_bf16 v[74:77], v[142:145], v[206:209], v[74:77]
	s_setprio 0
	s_setprio 1
	v_mfma_f32_16x16x32_bf16 v[114:117], v[156:159], v[178:181], v[114:117]
	v_mfma_f32_16x16x32_bf16 v[110:113], v[164:167], v[178:181], v[110:113]
	v_mfma_f32_16x16x32_bf16 v[102:105], v[156:159], v[186:189], v[102:105]
	v_mfma_f32_16x16x32_bf16 v[94:97], v[164:167], v[186:189], v[94:97]
	v_mfma_f32_16x16x32_bf16 v[86:89], v[156:159], v[194:197], v[86:89]
	v_mfma_f32_16x16x32_bf16 v[78:81], v[164:167], v[194:197], v[78:81]
	v_mfma_f32_16x16x32_bf16 v[70:73], v[156:159], v[202:205], v[70:73]
	v_mfma_f32_16x16x32_bf16 v[66:69], v[164:167], v[202:205], v[66:69]
	v_mfma_f32_16x16x32_bf16 v[114:117], v[160:163], v[182:185], v[114:117]
	v_mfma_f32_16x16x32_bf16 v[110:113], v[174:177], v[182:185], v[110:113]
	v_mfma_f32_16x16x32_bf16 v[102:105], v[160:163], v[190:193], v[102:105]
	v_mfma_f32_16x16x32_bf16 v[94:97], v[174:177], v[190:193], v[94:97]
	v_mfma_f32_16x16x32_bf16 v[86:89], v[160:163], v[198:201], v[86:89]
	v_mfma_f32_16x16x32_bf16 v[78:81], v[174:177], v[198:201], v[78:81]
	v_mfma_f32_16x16x32_bf16 v[70:73], v[160:163], v[206:209], v[70:73]
	v_mfma_f32_16x16x32_bf16 v[66:69], v[174:177], v[206:209], v[66:69]
	s_setprio 0
	s_barrier
	s_add_i32 s22, s47, s38
	v_lshl_add_u64 v[168:169], v[168:169], 0, s[2:3]
	s_mov_b32 m0, s22
	ds_read_b128 v[178:181], v173 offset:49152
	ds_read_b128 v[182:185], v173 offset:50176
	ds_read_b128 v[186:189], v173 offset:51200
	ds_read_b128 v[190:193], v173 offset:52224
	ds_read_b128 v[194:197], v173 offset:53248
	ds_read_b128 v[198:201], v173 offset:54272
	ds_read_b128 v[202:205], v173 offset:55296
	ds_read_b128 v[206:209], v173 offset:56320
	global_load_lds_dwordx4 v[168:169], off
	s_add_i32 m0, s22, 0x2000
	s_add_u32 s20, s20, 0x20080
	v_lshl_add_u64 v[168:169], v[216:217], 0, s[2:3]
	s_addc_u32 s21, s21, 0
	s_add_i32 s22, s48, s38
	global_load_lds_dwordx4 v[168:169], off
	v_lshl_add_u64 v[168:169], s[20:21], 0, v[0:1]
	s_mov_b32 m0, s22
	s_nop 0
	global_load_lds_dwordx4 v[168:169], off
	v_lshl_add_u64 v[168:169], s[20:21], 0, v[146:147]
	s_add_i32 m0, s22, 0x2000
	s_nop 0
	global_load_lds_dwordx4 v[168:169], off
	v_lshl_add_u64 v[168:169], v[220:221], 0, s[2:3]
	s_mov_b32 m0, s43
	s_nop 0
	global_load_lds_dwordx4 v[168:169], off
	v_lshl_add_u64 v[168:169], v[222:223], 0, s[2:3]
	s_mov_b32 m0, s44
	s_nop 0
	global_load_lds_dwordx4 v[168:169], off
	s_waitcnt vmcnt(8)
	s_waitcnt lgkmcnt(0)
	s_barrier
	s_setprio 1
	s_waitcnt lgkmcnt(0)
	v_mfma_f32_16x16x32_bf16 v[62:65], v[130:133], v[178:181], v[62:65]
	v_mfma_f32_16x16x32_bf16 v[58:61], v[138:141], v[178:181], v[58:61]
	v_mfma_f32_16x16x32_bf16 v[50:53], v[130:133], v[186:189], v[50:53]
	v_mfma_f32_16x16x32_bf16 v[42:45], v[138:141], v[186:189], v[42:45]
	v_mfma_f32_16x16x32_bf16 v[34:37], v[130:133], v[194:197], v[34:37]
	v_mfma_f32_16x16x32_bf16 v[26:29], v[138:141], v[194:197], v[26:29]
	v_mfma_f32_16x16x32_bf16 v[18:21], v[130:133], v[202:205], v[18:21]
	v_mfma_f32_16x16x32_bf16 v[10:13], v[138:141], v[202:205], v[10:13]
	v_mfma_f32_16x16x32_bf16 v[62:65], v[134:137], v[182:185], v[62:65]
	v_mfma_f32_16x16x32_bf16 v[58:61], v[142:145], v[182:185], v[58:61]
	v_mfma_f32_16x16x32_bf16 v[50:53], v[134:137], v[190:193], v[50:53]
	v_mfma_f32_16x16x32_bf16 v[42:45], v[142:145], v[190:193], v[42:45]
	v_mfma_f32_16x16x32_bf16 v[34:37], v[134:137], v[198:201], v[34:37]
	v_mfma_f32_16x16x32_bf16 v[26:29], v[142:145], v[198:201], v[26:29]
	v_mfma_f32_16x16x32_bf16 v[18:21], v[134:137], v[206:209], v[18:21]
	v_mfma_f32_16x16x32_bf16 v[10:13], v[142:145], v[206:209], v[10:13]
	s_setprio 0
	s_setprio 1
	v_mfma_f32_16x16x32_bf16 v[54:57], v[156:159], v[178:181], v[54:57]
	v_mfma_f32_16x16x32_bf16 v[46:49], v[164:167], v[178:181], v[46:49]
	v_mfma_f32_16x16x32_bf16 v[38:41], v[156:159], v[186:189], v[38:41]
	v_mfma_f32_16x16x32_bf16 v[30:33], v[164:167], v[186:189], v[30:33]
	v_mfma_f32_16x16x32_bf16 v[22:25], v[156:159], v[194:197], v[22:25]
	v_mfma_f32_16x16x32_bf16 v[14:17], v[164:167], v[194:197], v[14:17]
	v_mfma_f32_16x16x32_bf16 v[6:9], v[156:159], v[202:205], v[6:9]
	v_mfma_f32_16x16x32_bf16 v[2:5], v[164:167], v[202:205], v[2:5]
	v_mfma_f32_16x16x32_bf16 v[54:57], v[160:163], v[182:185], v[54:57]
	v_mfma_f32_16x16x32_bf16 v[46:49], v[174:177], v[182:185], v[46:49]
	v_mfma_f32_16x16x32_bf16 v[38:41], v[160:163], v[190:193], v[38:41]
	v_mfma_f32_16x16x32_bf16 v[30:33], v[174:177], v[190:193], v[30:33]
	v_mfma_f32_16x16x32_bf16 v[22:25], v[160:163], v[198:201], v[22:25]
	v_mfma_f32_16x16x32_bf16 v[14:17], v[174:177], v[198:201], v[14:17]
	v_mfma_f32_16x16x32_bf16 v[6:9], v[160:163], v[206:209], v[6:9]
	v_mfma_f32_16x16x32_bf16 v[2:5], v[174:177], v[206:209], v[2:5]
	s_setprio 0
	s_barrier
	s_add_i32 s37, s37, 2
	s_add_u32 s18, s18, 0x100
	s_addc_u32 s19, s19, 0
	s_add_u32 s15, s15, 0x100
	s_addc_u32 s36, s36, 0
	s_cmp_gt_u32 s37, 5
	s_cbranch_scc0 .LBB0_1201

.LBB0_1564:
	s_ashr_i32 s9, s8, 31
	s_lshl_b64 s[10:11], s[8:9], 20
	v_readlane_b32 s12, v253, 25
	v_readlane_b32 s13, v253, 26
	s_add_u32 s10, s12, s10
	s_addc_u32 s11, s13, s11
	s_and_b64 s[12:13], s[34:35], exec
	s_cselect_b32 s9, s11, s19
	s_cselect_b32 s15, s10, s18
	s_ashr_i32 s7, s6, 31
	s_lshl_b64 s[12:13], s[6:7], 20
	s_add_u32 s12, s37, s12
	s_addc_u32 s13, s38, s13
	s_and_b64 s[22:23], s[34:35], exec
	s_cselect_b32 s7, s13, s21
	s_cselect_b32 s50, s12, s20
	s_add_u32 s18, s18, 0x80080
	s_addc_u32 s19, s19, 0
	s_add_u32 s51, s20, 0x100
	s_addc_u32 s52, s21, 0
	s_mov_b32 s53, -2
	s_add_u32 s20, s18, 0xfff80080
	s_addc_u32 s21, s19, -1
	s_add_i32 s54, 0, 0x10000
	s_cmp_eq_u32 s53, 28
	s_cselect_b32 s23, s9, s21
	s_cselect_b32 s22, s15, s20
	v_add_u32_e32 v158, s54, v160
	s_cselect_b32 s21, s7, s52
	s_cselect_b32 s20, s50, s51
	s_add_i32 s56, 0, 0x14000
	ds_read_b128 v[164:167], v158
	ds_read_b128 v[168:171], v158 offset:1024
	ds_read_b128 v[172:175], v158 offset:2048
	ds_read_b128 v[176:179], v158 offset:3072
	v_add_u32_e32 v158, s56, v160
	ds_read_b128 v[180:183], v158
	ds_read_b128 v[184:187], v158 offset:1024
	ds_read_b128 v[188:191], v158 offset:2048
	ds_read_b128 v[192:195], v158 offset:3072
	v_lshl_add_u64 v[158:159], s[18:19], 0, v[154:155]
	s_add_i32 m0, s17, 0xc000
	ds_read_b128 v[196:199], v162
	ds_read_b128 v[200:203], v162 offset:1024
	ds_read_b128 v[204:207], v162 offset:2048
	ds_read_b128 v[220:223], v162 offset:3072
	ds_read_b128 v[224:227], v162 offset:4096
	ds_read_b128 v[228:231], v162 offset:5120
	ds_read_b128 v[232:235], v162 offset:6144
	ds_read_b128 v[236:239], v162 offset:7168
	global_load_lds_dwordx4 v[158:159], off
	v_lshl_add_u64 v[158:159], s[18:19], 0, v[156:157]
	s_add_i32 m0, s17, 0xe000
	s_nop 0
	global_load_lds_dwordx4 v[158:159], off
	s_waitcnt vmcnt(8)
	s_waitcnt lgkmcnt(0)
	s_barrier
	s_setprio 1
	s_waitcnt lgkmcnt(0)
	v_mfma_f32_16x16x32_bf16 v[122:125], v[164:167], v[196:199], 0
	v_mfma_f32_16x16x32_bf16 v[114:117], v[172:175], v[196:199], 0
	v_mfma_f32_16x16x32_bf16 v[106:109], v[164:167], v[204:207], 0
	v_mfma_f32_16x16x32_bf16 v[98:101], v[172:175], v[204:207], 0
	v_mfma_f32_16x16x32_bf16 v[90:93], v[164:167], v[224:227], 0
	v_mfma_f32_16x16x32_bf16 v[82:85], v[172:175], v[224:227], 0
	v_mfma_f32_16x16x32_bf16 v[74:77], v[164:167], v[232:235], 0
	v_mfma_f32_16x16x32_bf16 v[66:69], v[172:175], v[232:235], 0
	v_mfma_f32_16x16x32_bf16 v[122:125], v[168:171], v[200:203], v[122:125]
	v_mfma_f32_16x16x32_bf16 v[114:117], v[176:179], v[200:203], v[114:117]
	v_mfma_f32_16x16x32_bf16 v[106:109], v[168:171], v[220:223], v[106:109]
	v_mfma_f32_16x16x32_bf16 v[98:101], v[176:179], v[220:223], v[98:101]
	v_mfma_f32_16x16x32_bf16 v[90:93], v[168:171], v[228:231], v[90:93]
	v_mfma_f32_16x16x32_bf16 v[82:85], v[176:179], v[228:231], v[82:85]
	v_mfma_f32_16x16x32_bf16 v[74:77], v[168:171], v[236:239], v[74:77]
	v_mfma_f32_16x16x32_bf16 v[66:69], v[176:179], v[236:239], v[66:69]
	s_setprio 0
	s_setprio 1
	v_mfma_f32_16x16x32_bf16 v[126:129], v[180:183], v[196:199], 0
	v_mfma_f32_16x16x32_bf16 v[118:121], v[188:191], v[196:199], 0
	v_mfma_f32_16x16x32_bf16 v[110:113], v[180:183], v[204:207], 0
	v_mfma_f32_16x16x32_bf16 v[102:105], v[188:191], v[204:207], 0
	v_mfma_f32_16x16x32_bf16 v[94:97], v[180:183], v[224:227], 0
	v_mfma_f32_16x16x32_bf16 v[86:89], v[188:191], v[224:227], 0
	v_mfma_f32_16x16x32_bf16 v[78:81], v[180:183], v[232:235], 0
	v_mfma_f32_16x16x32_bf16 v[70:73], v[188:191], v[232:235], 0
	v_mfma_f32_16x16x32_bf16 v[126:129], v[184:187], v[200:203], v[126:129]
	v_mfma_f32_16x16x32_bf16 v[118:121], v[192:195], v[200:203], v[118:121]
	v_mfma_f32_16x16x32_bf16 v[110:113], v[184:187], v[220:223], v[110:113]
	v_mfma_f32_16x16x32_bf16 v[102:105], v[192:195], v[220:223], v[102:105]
	v_mfma_f32_16x16x32_bf16 v[94:97], v[184:187], v[228:231], v[94:97]
	v_mfma_f32_16x16x32_bf16 v[86:89], v[192:195], v[228:231], v[86:89]
	v_mfma_f32_16x16x32_bf16 v[78:81], v[184:187], v[236:239], v[78:81]
	v_mfma_f32_16x16x32_bf16 v[70:73], v[192:195], v[236:239], v[70:73]
	s_setprio 0
	s_barrier
	s_add_i32 s54, s54, s41
	v_lshl_add_u64 v[158:159], s[20:21], 0, v[0:1]
	s_mov_b32 m0, s54
	ds_read_b128 v[196:199], v162 offset:16384
	ds_read_b128 v[200:203], v162 offset:17408
	ds_read_b128 v[204:207], v162 offset:18432
	ds_read_b128 v[220:223], v162 offset:19456
	ds_read_b128 v[224:227], v162 offset:20480
	ds_read_b128 v[228:231], v162 offset:21504
	ds_read_b128 v[232:235], v162 offset:22528
	ds_read_b128 v[236:239], v162 offset:23552
	global_load_lds_dwordx4 v[158:159], off
	s_add_i32 m0, s54, 0x2000
	s_add_u32 s54, s20, 0x80000
	v_lshl_add_u64 v[208:209], s[20:21], 0, v[130:131]
	s_addc_u32 s55, s21, 0
	s_add_i32 s56, s56, s41
	global_load_lds_dwordx4 v[208:209], off
	v_lshl_add_u64 v[216:217], s[54:55], 0, v[0:1]
	s_mov_b32 m0, s56
	v_lshl_add_u64 v[244:245], s[22:23], 0, v[132:133]
	global_load_lds_dwordx4 v[216:217], off
	v_lshl_add_u64 v[216:217], s[54:55], 0, v[130:131]
	s_add_i32 m0, s56, 0x2000
	s_nop 0
	global_load_lds_dwordx4 v[216:217], off
	v_lshl_add_u64 v[216:217], s[22:23], 0, v[134:135]
	s_mov_b32 m0, s17
	s_nop 0
	global_load_lds_dwordx4 v[216:217], off
	s_mov_b32 m0, s43
	s_nop 0
	global_load_lds_dwordx4 v[244:245], off
	s_waitcnt vmcnt(8)
	s_waitcnt lgkmcnt(0)
	s_barrier
	s_setprio 1
	s_waitcnt lgkmcnt(0)
	v_mfma_f32_16x16x32_bf16 v[58:61], v[164:167], v[196:199], 0
	v_mfma_f32_16x16x32_bf16 v[50:53], v[172:175], v[196:199], 0
	v_mfma_f32_16x16x32_bf16 v[42:45], v[164:167], v[204:207], 0
	v_mfma_f32_16x16x32_bf16 v[34:37], v[172:175], v[204:207], 0
	v_mfma_f32_16x16x32_bf16 v[26:29], v[164:167], v[224:227], 0
	v_mfma_f32_16x16x32_bf16 v[18:21], v[172:175], v[224:227], 0
	v_mfma_f32_16x16x32_bf16 v[10:13], v[164:167], v[232:235], 0
	v_mfma_f32_16x16x32_bf16 v[2:5], v[172:175], v[232:235], 0
	v_mfma_f32_16x16x32_bf16 v[58:61], v[168:171], v[200:203], v[58:61]
	v_mfma_f32_16x16x32_bf16 v[50:53], v[176:179], v[200:203], v[50:53]
	v_mfma_f32_16x16x32_bf16 v[42:45], v[168:171], v[220:223], v[42:45]
	v_mfma_f32_16x16x32_bf16 v[34:37], v[176:179], v[220:223], v[34:37]
	v_mfma_f32_16x16x32_bf16 v[26:29], v[168:171], v[228:231], v[26:29]
	v_mfma_f32_16x16x32_bf16 v[18:21], v[176:179], v[228:231], v[18:21]
	v_mfma_f32_16x16x32_bf16 v[10:13], v[168:171], v[236:239], v[10:13]
	v_mfma_f32_16x16x32_bf16 v[2:5], v[176:179], v[236:239], v[2:5]
	s_setprio 0
	s_setprio 1
	v_mfma_f32_16x16x32_bf16 v[62:65], v[180:183], v[196:199], 0
	v_mfma_f32_16x16x32_bf16 v[54:57], v[188:191], v[196:199], 0
	v_mfma_f32_16x16x32_bf16 v[46:49], v[180:183], v[204:207], 0
	v_mfma_f32_16x16x32_bf16 v[38:41], v[188:191], v[204:207], 0
	v_mfma_f32_16x16x32_bf16 v[30:33], v[180:183], v[224:227], 0
	v_mfma_f32_16x16x32_bf16 v[22:25], v[188:191], v[224:227], 0
	v_mfma_f32_16x16x32_bf16 v[14:17], v[180:183], v[232:235], 0
	v_mfma_f32_16x16x32_bf16 v[6:9], v[188:191], v[232:235], 0
	v_mfma_f32_16x16x32_bf16 v[62:65], v[184:187], v[200:203], v[62:65]
	v_mfma_f32_16x16x32_bf16 v[54:57], v[192:195], v[200:203], v[54:57]
	v_mfma_f32_16x16x32_bf16 v[46:49], v[184:187], v[220:223], v[46:49]
	v_mfma_f32_16x16x32_bf16 v[38:41], v[192:195], v[220:223], v[38:41]
	v_mfma_f32_16x16x32_bf16 v[30:33], v[184:187], v[228:231], v[30:33]
	v_mfma_f32_16x16x32_bf16 v[22:25], v[192:195], v[228:231], v[22:25]
	v_mfma_f32_16x16x32_bf16 v[14:17], v[184:187], v[236:239], v[14:17]
	v_mfma_f32_16x16x32_bf16 v[6:9], v[192:195], v[236:239], v[6:9]
	s_setprio 0
	s_barrier
	s_add_i32 s54, 0, 0x18000
	v_add_u32_e32 v163, s54, v160
	s_add_i32 s55, 0, 0x1c000
	ds_read_b128 v[164:167], v163
	ds_read_b128 v[168:171], v163 offset:1024
	ds_read_b128 v[172:175], v163 offset:2048
	ds_read_b128 v[176:179], v163 offset:3072
	v_add_u32_e32 v163, s55, v160
	ds_read_b128 v[180:183], v163
	ds_read_b128 v[184:187], v163 offset:1024
	ds_read_b128 v[188:191], v163 offset:2048
	ds_read_b128 v[192:195], v163 offset:3072
	s_add_u32 s22, s22, 0x80000
	s_addc_u32 s23, s23, 0
	s_mov_b32 m0, s44
	v_lshl_add_u64 v[246:247], s[22:23], 0, v[134:135]
	ds_read_b128 v[196:199], v162 offset:32768
	ds_read_b128 v[200:203], v162 offset:33792
	ds_read_b128 v[204:207], v162 offset:34816
	ds_read_b128 v[220:223], v162 offset:35840
	ds_read_b128 v[224:227], v162 offset:36864
	ds_read_b128 v[228:231], v162 offset:37888
	ds_read_b128 v[232:235], v162 offset:38912
	ds_read_b128 v[236:239], v162 offset:39936
	global_load_lds_dwordx4 v[246:247], off
	v_lshl_add_u64 v[246:247], s[22:23], 0, v[132:133]
	s_mov_b32 m0, s45
	s_nop 0
	global_load_lds_dwordx4 v[246:247], off
	s_waitcnt vmcnt(8)
	s_waitcnt lgkmcnt(0)
	s_barrier
	s_setprio 1
	s_waitcnt lgkmcnt(0)
	v_mfma_f32_16x16x32_bf16 v[122:125], v[164:167], v[196:199], v[122:125]
	v_mfma_f32_16x16x32_bf16 v[114:117], v[172:175], v[196:199], v[114:117]
	v_mfma_f32_16x16x32_bf16 v[106:109], v[164:167], v[204:207], v[106:109]
	v_mfma_f32_16x16x32_bf16 v[98:101], v[172:175], v[204:207], v[98:101]
	v_mfma_f32_16x16x32_bf16 v[90:93], v[164:167], v[224:227], v[90:93]
	v_mfma_f32_16x16x32_bf16 v[82:85], v[172:175], v[224:227], v[82:85]
	v_mfma_f32_16x16x32_bf16 v[74:77], v[164:167], v[232:235], v[74:77]
	v_mfma_f32_16x16x32_bf16 v[66:69], v[172:175], v[232:235], v[66:69]
	v_mfma_f32_16x16x32_bf16 v[122:125], v[168:171], v[200:203], v[122:125]
	v_mfma_f32_16x16x32_bf16 v[114:117], v[176:179], v[200:203], v[114:117]
	v_mfma_f32_16x16x32_bf16 v[106:109], v[168:171], v[220:223], v[106:109]
	v_mfma_f32_16x16x32_bf16 v[98:101], v[176:179], v[220:223], v[98:101]
	v_mfma_f32_16x16x32_bf16 v[90:93], v[168:171], v[228:231], v[90:93]
	v_mfma_f32_16x16x32_bf16 v[82:85], v[176:179], v[228:231], v[82:85]
	v_mfma_f32_16x16x32_bf16 v[74:77], v[168:171], v[236:239], v[74:77]
	v_mfma_f32_16x16x32_bf16 v[66:69], v[176:179], v[236:239], v[66:69]
	s_setprio 0
	s_setprio 1
	v_mfma_f32_16x16x32_bf16 v[126:129], v[180:183], v[196:199], v[126:129]
	v_mfma_f32_16x16x32_bf16 v[118:121], v[188:191], v[196:199], v[118:121]
	v_mfma_f32_16x16x32_bf16 v[110:113], v[180:183], v[204:207], v[110:113]
	v_mfma_f32_16x16x32_bf16 v[102:105], v[188:191], v[204:207], v[102:105]
	v_mfma_f32_16x16x32_bf16 v[94:97], v[180:183], v[224:227], v[94:97]
	v_mfma_f32_16x16x32_bf16 v[86:89], v[188:191], v[224:227], v[86:89]
	v_mfma_f32_16x16x32_bf16 v[78:81], v[180:183], v[232:235], v[78:81]
	v_mfma_f32_16x16x32_bf16 v[70:73], v[188:191], v[232:235], v[70:73]
	v_mfma_f32_16x16x32_bf16 v[126:129], v[184:187], v[200:203], v[126:129]
	v_mfma_f32_16x16x32_bf16 v[118:121], v[192:195], v[200:203], v[118:121]
	v_mfma_f32_16x16x32_bf16 v[110:113], v[184:187], v[220:223], v[110:113]
	v_mfma_f32_16x16x32_bf16 v[102:105], v[192:195], v[220:223], v[102:105]
	v_mfma_f32_16x16x32_bf16 v[94:97], v[184:187], v[228:231], v[94:97]
	v_mfma_f32_16x16x32_bf16 v[86:89], v[192:195], v[228:231], v[86:89]
	v_mfma_f32_16x16x32_bf16 v[78:81], v[184:187], v[236:239], v[78:81]
	v_mfma_f32_16x16x32_bf16 v[70:73], v[192:195], v[236:239], v[70:73]
	s_setprio 0
	s_barrier
	s_add_i32 s22, s54, s41
	v_lshl_add_u64 v[158:159], v[158:159], 0, s[2:3]
	s_mov_b32 m0, s22
	ds_read_b128 v[196:199], v162 offset:49152
	ds_read_b128 v[200:203], v162 offset:50176
	ds_read_b128 v[204:207], v162 offset:51200
	ds_read_b128 v[220:223], v162 offset:52224
	ds_read_b128 v[224:227], v162 offset:53248
	ds_read_b128 v[228:231], v162 offset:54272
	ds_read_b128 v[232:235], v162 offset:55296
	ds_read_b128 v[236:239], v162 offset:56320
	global_load_lds_dwordx4 v[158:159], off
	s_add_i32 m0, s22, 0x2000
	s_add_u32 s20, s20, 0x80080
	v_lshl_add_u64 v[158:159], v[208:209], 0, s[2:3]
	s_addc_u32 s21, s21, 0
	s_add_i32 s22, s55, s41
	global_load_lds_dwordx4 v[158:159], off
	v_lshl_add_u64 v[158:159], s[20:21], 0, v[0:1]
	s_mov_b32 m0, s22
	s_nop 0
	global_load_lds_dwordx4 v[158:159], off
	v_lshl_add_u64 v[158:159], s[20:21], 0, v[130:131]
	s_add_i32 m0, s22, 0x2000
	s_nop 0
	global_load_lds_dwordx4 v[158:159], off
	v_lshl_add_u64 v[158:159], v[216:217], 0, s[2:3]
	s_mov_b32 m0, s46
	s_nop 0
	global_load_lds_dwordx4 v[158:159], off
	v_lshl_add_u64 v[158:159], v[244:245], 0, s[2:3]
	s_mov_b32 m0, s47
	s_nop 0
	global_load_lds_dwordx4 v[158:159], off
	s_waitcnt vmcnt(8)
	s_waitcnt lgkmcnt(0)
	s_barrier
	s_setprio 1
	s_waitcnt lgkmcnt(0)
	v_mfma_f32_16x16x32_bf16 v[58:61], v[164:167], v[196:199], v[58:61]
	v_mfma_f32_16x16x32_bf16 v[50:53], v[172:175], v[196:199], v[50:53]
	v_mfma_f32_16x16x32_bf16 v[42:45], v[164:167], v[204:207], v[42:45]
	v_mfma_f32_16x16x32_bf16 v[34:37], v[172:175], v[204:207], v[34:37]
	v_mfma_f32_16x16x32_bf16 v[26:29], v[164:167], v[224:227], v[26:29]
	v_mfma_f32_16x16x32_bf16 v[18:21], v[172:175], v[224:227], v[18:21]
	v_mfma_f32_16x16x32_bf16 v[10:13], v[164:167], v[232:235], v[10:13]
	v_mfma_f32_16x16x32_bf16 v[2:5], v[172:175], v[232:235], v[2:5]
	v_mfma_f32_16x16x32_bf16 v[58:61], v[168:171], v[200:203], v[58:61]
	v_mfma_f32_16x16x32_bf16 v[50:53], v[176:179], v[200:203], v[50:53]
	v_mfma_f32_16x16x32_bf16 v[42:45], v[168:171], v[220:223], v[42:45]
	v_mfma_f32_16x16x32_bf16 v[34:37], v[176:179], v[220:223], v[34:37]
	v_mfma_f32_16x16x32_bf16 v[26:29], v[168:171], v[228:231], v[26:29]
	v_mfma_f32_16x16x32_bf16 v[18:21], v[176:179], v[228:231], v[18:21]
	v_mfma_f32_16x16x32_bf16 v[10:13], v[168:171], v[236:239], v[10:13]
	v_mfma_f32_16x16x32_bf16 v[2:5], v[176:179], v[236:239], v[2:5]
	s_setprio 0
	s_setprio 1
	v_mfma_f32_16x16x32_bf16 v[62:65], v[180:183], v[196:199], v[62:65]
	v_mfma_f32_16x16x32_bf16 v[54:57], v[188:191], v[196:199], v[54:57]
	v_mfma_f32_16x16x32_bf16 v[46:49], v[180:183], v[204:207], v[46:49]
	v_mfma_f32_16x16x32_bf16 v[38:41], v[188:191], v[204:207], v[38:41]
	v_mfma_f32_16x16x32_bf16 v[30:33], v[180:183], v[224:227], v[30:33]
	v_mfma_f32_16x16x32_bf16 v[22:25], v[188:191], v[224:227], v[22:25]
	v_mfma_f32_16x16x32_bf16 v[14:17], v[180:183], v[232:235], v[14:17]
	v_mfma_f32_16x16x32_bf16 v[6:9], v[188:191], v[232:235], v[6:9]
	v_mfma_f32_16x16x32_bf16 v[62:65], v[184:187], v[200:203], v[62:65]
	v_mfma_f32_16x16x32_bf16 v[54:57], v[192:195], v[200:203], v[54:57]
	v_mfma_f32_16x16x32_bf16 v[46:49], v[184:187], v[220:223], v[46:49]
	v_mfma_f32_16x16x32_bf16 v[38:41], v[192:195], v[220:223], v[38:41]
	v_mfma_f32_16x16x32_bf16 v[30:33], v[184:187], v[228:231], v[30:33]
	v_mfma_f32_16x16x32_bf16 v[22:25], v[192:195], v[228:231], v[22:25]
	v_mfma_f32_16x16x32_bf16 v[14:17], v[184:187], v[236:239], v[14:17]
	v_mfma_f32_16x16x32_bf16 v[6:9], v[192:195], v[236:239], v[6:9]
	s_setprio 0
	s_barrier
	s_add_i32 s53, s53, 2
	s_add_u32 s18, s18, 0x100
	s_addc_u32 s19, s19, 0
	s_add_u32 s51, s51, 0x100
	s_addc_u32 s52, s52, 0
	s_cmp_gt_u32 s53, 29
	s_cbranch_scc1 .Lpeel_done_4
.LBB0_1565:
	s_add_u32 s20, s18, 0xfff80080
	s_addc_u32 s21, s19, -1
	s_add_i32 s54, 0, 0x10000
	s_cmp_eq_u32 s53, 28
	s_cselect_b32 s23, s9, s21
	s_cselect_b32 s22, s15, s20
	v_add_u32_e32 v158, s54, v160
	s_cselect_b32 s21, s7, s52
	s_cselect_b32 s20, s50, s51
	s_add_i32 s56, 0, 0x14000
	ds_read_b128 v[164:167], v158
	ds_read_b128 v[168:171], v158 offset:1024
	ds_read_b128 v[172:175], v158 offset:2048
	ds_read_b128 v[176:179], v158 offset:3072
	v_add_u32_e32 v158, s56, v160
	ds_read_b128 v[180:183], v158
	ds_read_b128 v[184:187], v158 offset:1024
	ds_read_b128 v[188:191], v158 offset:2048
	ds_read_b128 v[192:195], v158 offset:3072
	v_lshl_add_u64 v[158:159], s[18:19], 0, v[154:155]
	s_add_i32 m0, s17, 0xc000
	ds_read_b128 v[196:199], v162
	ds_read_b128 v[200:203], v162 offset:1024
	ds_read_b128 v[204:207], v162 offset:2048
	ds_read_b128 v[220:223], v162 offset:3072
	ds_read_b128 v[224:227], v162 offset:4096
	ds_read_b128 v[228:231], v162 offset:5120
	ds_read_b128 v[232:235], v162 offset:6144
	ds_read_b128 v[236:239], v162 offset:7168
	global_load_lds_dwordx4 v[158:159], off
	v_lshl_add_u64 v[158:159], s[18:19], 0, v[156:157]
	s_add_i32 m0, s17, 0xe000
	s_nop 0
	global_load_lds_dwordx4 v[158:159], off
	s_waitcnt vmcnt(8)
	s_waitcnt lgkmcnt(0)
	s_barrier
	s_setprio 1
	s_waitcnt lgkmcnt(0)
	v_mfma_f32_16x16x32_bf16 v[122:125], v[164:167], v[196:199], v[122:125]
	v_mfma_f32_16x16x32_bf16 v[114:117], v[172:175], v[196:199], v[114:117]
	v_mfma_f32_16x16x32_bf16 v[106:109], v[164:167], v[204:207], v[106:109]
	v_mfma_f32_16x16x32_bf16 v[98:101], v[172:175], v[204:207], v[98:101]
	v_mfma_f32_16x16x32_bf16 v[90:93], v[164:167], v[224:227], v[90:93]
	v_mfma_f32_16x16x32_bf16 v[82:85], v[172:175], v[224:227], v[82:85]
	v_mfma_f32_16x16x32_bf16 v[74:77], v[164:167], v[232:235], v[74:77]
	v_mfma_f32_16x16x32_bf16 v[66:69], v[172:175], v[232:235], v[66:69]
	v_mfma_f32_16x16x32_bf16 v[122:125], v[168:171], v[200:203], v[122:125]
	v_mfma_f32_16x16x32_bf16 v[114:117], v[176:179], v[200:203], v[114:117]
	v_mfma_f32_16x16x32_bf16 v[106:109], v[168:171], v[220:223], v[106:109]
	v_mfma_f32_16x16x32_bf16 v[98:101], v[176:179], v[220:223], v[98:101]
	v_mfma_f32_16x16x32_bf16 v[90:93], v[168:171], v[228:231], v[90:93]
	v_mfma_f32_16x16x32_bf16 v[82:85], v[176:179], v[228:231], v[82:85]
	v_mfma_f32_16x16x32_bf16 v[74:77], v[168:171], v[236:239], v[74:77]
	v_mfma_f32_16x16x32_bf16 v[66:69], v[176:179], v[236:239], v[66:69]
	s_setprio 0
	s_setprio 1
	v_mfma_f32_16x16x32_bf16 v[126:129], v[180:183], v[196:199], v[126:129]
	v_mfma_f32_16x16x32_bf16 v[118:121], v[188:191], v[196:199], v[118:121]
	v_mfma_f32_16x16x32_bf16 v[110:113], v[180:183], v[204:207], v[110:113]
	v_mfma_f32_16x16x32_bf16 v[102:105], v[188:191], v[204:207], v[102:105]
	v_mfma_f32_16x16x32_bf16 v[94:97], v[180:183], v[224:227], v[94:97]
	v_mfma_f32_16x16x32_bf16 v[86:89], v[188:191], v[224:227], v[86:89]
	v_mfma_f32_16x16x32_bf16 v[78:81], v[180:183], v[232:235], v[78:81]
	v_mfma_f32_16x16x32_bf16 v[70:73], v[188:191], v[232:235], v[70:73]
	v_mfma_f32_16x16x32_bf16 v[126:129], v[184:187], v[200:203], v[126:129]
	v_mfma_f32_16x16x32_bf16 v[118:121], v[192:195], v[200:203], v[118:121]
	v_mfma_f32_16x16x32_bf16 v[110:113], v[184:187], v[220:223], v[110:113]
	v_mfma_f32_16x16x32_bf16 v[102:105], v[192:195], v[220:223], v[102:105]
	v_mfma_f32_16x16x32_bf16 v[94:97], v[184:187], v[228:231], v[94:97]
	v_mfma_f32_16x16x32_bf16 v[86:89], v[192:195], v[228:231], v[86:89]
	v_mfma_f32_16x16x32_bf16 v[78:81], v[184:187], v[236:239], v[78:81]
	v_mfma_f32_16x16x32_bf16 v[70:73], v[192:195], v[236:239], v[70:73]
	s_setprio 0
	s_barrier
	s_add_i32 s54, s54, s41
	v_lshl_add_u64 v[158:159], s[20:21], 0, v[0:1]
	s_mov_b32 m0, s54
	ds_read_b128 v[196:199], v162 offset:16384
	ds_read_b128 v[200:203], v162 offset:17408
	ds_read_b128 v[204:207], v162 offset:18432
	ds_read_b128 v[220:223], v162 offset:19456
	ds_read_b128 v[224:227], v162 offset:20480
	ds_read_b128 v[228:231], v162 offset:21504
	ds_read_b128 v[232:235], v162 offset:22528
	ds_read_b128 v[236:239], v162 offset:23552
	global_load_lds_dwordx4 v[158:159], off
	s_add_i32 m0, s54, 0x2000
	s_add_u32 s54, s20, 0x80000
	v_lshl_add_u64 v[208:209], s[20:21], 0, v[130:131]
	s_addc_u32 s55, s21, 0
	s_add_i32 s56, s56, s41
	global_load_lds_dwordx4 v[208:209], off
	v_lshl_add_u64 v[216:217], s[54:55], 0, v[0:1]
	s_mov_b32 m0, s56
	v_lshl_add_u64 v[244:245], s[22:23], 0, v[132:133]
	global_load_lds_dwordx4 v[216:217], off
	v_lshl_add_u64 v[216:217], s[54:55], 0, v[130:131]
	s_add_i32 m0, s56, 0x2000
	s_nop 0
	global_load_lds_dwordx4 v[216:217], off
	v_lshl_add_u64 v[216:217], s[22:23], 0, v[134:135]
	s_mov_b32 m0, s17
	s_nop 0
	global_load_lds_dwordx4 v[216:217], off
	s_mov_b32 m0, s43
	s_nop 0
	global_load_lds_dwordx4 v[244:245], off
	s_waitcnt vmcnt(8)
	s_waitcnt lgkmcnt(0)
	s_barrier
	s_setprio 1
	s_waitcnt lgkmcnt(0)
	v_mfma_f32_16x16x32_bf16 v[58:61], v[164:167], v[196:199], v[58:61]
	v_mfma_f32_16x16x32_bf16 v[50:53], v[172:175], v[196:199], v[50:53]
	v_mfma_f32_16x16x32_bf16 v[42:45], v[164:167], v[204:207], v[42:45]
	v_mfma_f32_16x16x32_bf16 v[34:37], v[172:175], v[204:207], v[34:37]
	v_mfma_f32_16x16x32_bf16 v[26:29], v[164:167], v[224:227], v[26:29]
	v_mfma_f32_16x16x32_bf16 v[18:21], v[172:175], v[224:227], v[18:21]
	v_mfma_f32_16x16x32_bf16 v[10:13], v[164:167], v[232:235], v[10:13]
	v_mfma_f32_16x16x32_bf16 v[2:5], v[172:175], v[232:235], v[2:5]
	v_mfma_f32_16x16x32_bf16 v[58:61], v[168:171], v[200:203], v[58:61]
	v_mfma_f32_16x16x32_bf16 v[50:53], v[176:179], v[200:203], v[50:53]
	v_mfma_f32_16x16x32_bf16 v[42:45], v[168:171], v[220:223], v[42:45]
	v_mfma_f32_16x16x32_bf16 v[34:37], v[176:179], v[220:223], v[34:37]
	v_mfma_f32_16x16x32_bf16 v[26:29], v[168:171], v[228:231], v[26:29]
	v_mfma_f32_16x16x32_bf16 v[18:21], v[176:179], v[228:231], v[18:21]
	v_mfma_f32_16x16x32_bf16 v[10:13], v[168:171], v[236:239], v[10:13]
	v_mfma_f32_16x16x32_bf16 v[2:5], v[176:179], v[236:239], v[2:5]
	s_setprio 0
	s_setprio 1
	v_mfma_f32_16x16x32_bf16 v[62:65], v[180:183], v[196:199], v[62:65]
	v_mfma_f32_16x16x32_bf16 v[54:57], v[188:191], v[196:199], v[54:57]
	v_mfma_f32_16x16x32_bf16 v[46:49], v[180:183], v[204:207], v[46:49]
	v_mfma_f32_16x16x32_bf16 v[38:41], v[188:191], v[204:207], v[38:41]
	v_mfma_f32_16x16x32_bf16 v[30:33], v[180:183], v[224:227], v[30:33]
	v_mfma_f32_16x16x32_bf16 v[22:25], v[188:191], v[224:227], v[22:25]
	v_mfma_f32_16x16x32_bf16 v[14:17], v[180:183], v[232:235], v[14:17]
	v_mfma_f32_16x16x32_bf16 v[6:9], v[188:191], v[232:235], v[6:9]
	v_mfma_f32_16x16x32_bf16 v[62:65], v[184:187], v[200:203], v[62:65]
	v_mfma_f32_16x16x32_bf16 v[54:57], v[192:195], v[200:203], v[54:57]
	v_mfma_f32_16x16x32_bf16 v[46:49], v[184:187], v[220:223], v[46:49]
	v_mfma_f32_16x16x32_bf16 v[38:41], v[192:195], v[220:223], v[38:41]
	v_mfma_f32_16x16x32_bf16 v[30:33], v[184:187], v[228:231], v[30:33]
	v_mfma_f32_16x16x32_bf16 v[22:25], v[192:195], v[228:231], v[22:25]
	v_mfma_f32_16x16x32_bf16 v[14:17], v[184:187], v[236:239], v[14:17]
	v_mfma_f32_16x16x32_bf16 v[6:9], v[192:195], v[236:239], v[6:9]
	s_setprio 0
	s_barrier
	s_add_i32 s54, 0, 0x18000
	v_add_u32_e32 v163, s54, v160
	s_add_i32 s55, 0, 0x1c000
	ds_read_b128 v[164:167], v163
	ds_read_b128 v[168:171], v163 offset:1024
	ds_read_b128 v[172:175], v163 offset:2048
	ds_read_b128 v[176:179], v163 offset:3072
	v_add_u32_e32 v163, s55, v160
	ds_read_b128 v[180:183], v163
	ds_read_b128 v[184:187], v163 offset:1024
	ds_read_b128 v[188:191], v163 offset:2048
	ds_read_b128 v[192:195], v163 offset:3072
	s_add_u32 s22, s22, 0x80000
	s_addc_u32 s23, s23, 0
	s_mov_b32 m0, s44
	v_lshl_add_u64 v[246:247], s[22:23], 0, v[134:135]
	ds_read_b128 v[196:199], v162 offset:32768
	ds_read_b128 v[200:203], v162 offset:33792
	ds_read_b128 v[204:207], v162 offset:34816
	ds_read_b128 v[220:223], v162 offset:35840
	ds_read_b128 v[224:227], v162 offset:36864
	ds_read_b128 v[228:231], v162 offset:37888
	ds_read_b128 v[232:235], v162 offset:38912
	ds_read_b128 v[236:239], v162 offset:39936
	global_load_lds_dwordx4 v[246:247], off
	v_lshl_add_u64 v[246:247], s[22:23], 0, v[132:133]
	s_mov_b32 m0, s45
	s_nop 0
	global_load_lds_dwordx4 v[246:247], off
	s_waitcnt vmcnt(8)
	s_waitcnt lgkmcnt(0)
	s_barrier
	s_setprio 1
	s_waitcnt lgkmcnt(0)
	v_mfma_f32_16x16x32_bf16 v[122:125], v[164:167], v[196:199], v[122:125]
	v_mfma_f32_16x16x32_bf16 v[114:117], v[172:175], v[196:199], v[114:117]
	v_mfma_f32_16x16x32_bf16 v[106:109], v[164:167], v[204:207], v[106:109]
	v_mfma_f32_16x16x32_bf16 v[98:101], v[172:175], v[204:207], v[98:101]
	v_mfma_f32_16x16x32_bf16 v[90:93], v[164:167], v[224:227], v[90:93]
	v_mfma_f32_16x16x32_bf16 v[82:85], v[172:175], v[224:227], v[82:85]
	v_mfma_f32_16x16x32_bf16 v[74:77], v[164:167], v[232:235], v[74:77]
	v_mfma_f32_16x16x32_bf16 v[66:69], v[172:175], v[232:235], v[66:69]
	v_mfma_f32_16x16x32_bf16 v[122:125], v[168:171], v[200:203], v[122:125]
	v_mfma_f32_16x16x32_bf16 v[114:117], v[176:179], v[200:203], v[114:117]
	v_mfma_f32_16x16x32_bf16 v[106:109], v[168:171], v[220:223], v[106:109]
	v_mfma_f32_16x16x32_bf16 v[98:101], v[176:179], v[220:223], v[98:101]
	v_mfma_f32_16x16x32_bf16 v[90:93], v[168:171], v[228:231], v[90:93]
	v_mfma_f32_16x16x32_bf16 v[82:85], v[176:179], v[228:231], v[82:85]
	v_mfma_f32_16x16x32_bf16 v[74:77], v[168:171], v[236:239], v[74:77]
	v_mfma_f32_16x16x32_bf16 v[66:69], v[176:179], v[236:239], v[66:69]
	s_setprio 0
	s_setprio 1
	v_mfma_f32_16x16x32_bf16 v[126:129], v[180:183], v[196:199], v[126:129]
	v_mfma_f32_16x16x32_bf16 v[118:121], v[188:191], v[196:199], v[118:121]
	v_mfma_f32_16x16x32_bf16 v[110:113], v[180:183], v[204:207], v[110:113]
	v_mfma_f32_16x16x32_bf16 v[102:105], v[188:191], v[204:207], v[102:105]
	v_mfma_f32_16x16x32_bf16 v[94:97], v[180:183], v[224:227], v[94:97]
	v_mfma_f32_16x16x32_bf16 v[86:89], v[188:191], v[224:227], v[86:89]
	v_mfma_f32_16x16x32_bf16 v[78:81], v[180:183], v[232:235], v[78:81]
	v_mfma_f32_16x16x32_bf16 v[70:73], v[188:191], v[232:235], v[70:73]
	v_mfma_f32_16x16x32_bf16 v[126:129], v[184:187], v[200:203], v[126:129]
	v_mfma_f32_16x16x32_bf16 v[118:121], v[192:195], v[200:203], v[118:121]
	v_mfma_f32_16x16x32_bf16 v[110:113], v[184:187], v[220:223], v[110:113]
	v_mfma_f32_16x16x32_bf16 v[102:105], v[192:195], v[220:223], v[102:105]
	v_mfma_f32_16x16x32_bf16 v[94:97], v[184:187], v[228:231], v[94:97]
	v_mfma_f32_16x16x32_bf16 v[86:89], v[192:195], v[228:231], v[86:89]
	v_mfma_f32_16x16x32_bf16 v[78:81], v[184:187], v[236:239], v[78:81]
	v_mfma_f32_16x16x32_bf16 v[70:73], v[192:195], v[236:239], v[70:73]
	s_setprio 0
	s_barrier
	s_add_i32 s22, s54, s41
	v_lshl_add_u64 v[158:159], v[158:159], 0, s[2:3]
	s_mov_b32 m0, s22
	ds_read_b128 v[196:199], v162 offset:49152
	ds_read_b128 v[200:203], v162 offset:50176
	ds_read_b128 v[204:207], v162 offset:51200
	ds_read_b128 v[220:223], v162 offset:52224
	ds_read_b128 v[224:227], v162 offset:53248
	ds_read_b128 v[228:231], v162 offset:54272
	ds_read_b128 v[232:235], v162 offset:55296
	ds_read_b128 v[236:239], v162 offset:56320
	global_load_lds_dwordx4 v[158:159], off
	s_add_i32 m0, s22, 0x2000
	s_add_u32 s20, s20, 0x80080
	v_lshl_add_u64 v[158:159], v[208:209], 0, s[2:3]
	s_addc_u32 s21, s21, 0
	s_add_i32 s22, s55, s41
	global_load_lds_dwordx4 v[158:159], off
	v_lshl_add_u64 v[158:159], s[20:21], 0, v[0:1]
	s_mov_b32 m0, s22
	s_nop 0
	global_load_lds_dwordx4 v[158:159], off
	v_lshl_add_u64 v[158:159], s[20:21], 0, v[130:131]
	s_add_i32 m0, s22, 0x2000
	s_nop 0
	global_load_lds_dwordx4 v[158:159], off
	v_lshl_add_u64 v[158:159], v[216:217], 0, s[2:3]
	s_mov_b32 m0, s46
	s_nop 0
	global_load_lds_dwordx4 v[158:159], off
	v_lshl_add_u64 v[158:159], v[244:245], 0, s[2:3]
	s_mov_b32 m0, s47
	s_nop 0
	global_load_lds_dwordx4 v[158:159], off
	s_waitcnt vmcnt(8)
	s_waitcnt lgkmcnt(0)
	s_barrier
	s_setprio 1
	s_waitcnt lgkmcnt(0)
	v_mfma_f32_16x16x32_bf16 v[58:61], v[164:167], v[196:199], v[58:61]
	v_mfma_f32_16x16x32_bf16 v[50:53], v[172:175], v[196:199], v[50:53]
	v_mfma_f32_16x16x32_bf16 v[42:45], v[164:167], v[204:207], v[42:45]
	v_mfma_f32_16x16x32_bf16 v[34:37], v[172:175], v[204:207], v[34:37]
	v_mfma_f32_16x16x32_bf16 v[26:29], v[164:167], v[224:227], v[26:29]
	v_mfma_f32_16x16x32_bf16 v[18:21], v[172:175], v[224:227], v[18:21]
	v_mfma_f32_16x16x32_bf16 v[10:13], v[164:167], v[232:235], v[10:13]
	v_mfma_f32_16x16x32_bf16 v[2:5], v[172:175], v[232:235], v[2:5]
	v_mfma_f32_16x16x32_bf16 v[58:61], v[168:171], v[200:203], v[58:61]
	v_mfma_f32_16x16x32_bf16 v[50:53], v[176:179], v[200:203], v[50:53]
	v_mfma_f32_16x16x32_bf16 v[42:45], v[168:171], v[220:223], v[42:45]
	v_mfma_f32_16x16x32_bf16 v[34:37], v[176:179], v[220:223], v[34:37]
	v_mfma_f32_16x16x32_bf16 v[26:29], v[168:171], v[228:231], v[26:29]
	v_mfma_f32_16x16x32_bf16 v[18:21], v[176:179], v[228:231], v[18:21]
	v_mfma_f32_16x16x32_bf16 v[10:13], v[168:171], v[236:239], v[10:13]
	v_mfma_f32_16x16x32_bf16 v[2:5], v[176:179], v[236:239], v[2:5]
	s_setprio 0
	s_setprio 1
	v_mfma_f32_16x16x32_bf16 v[62:65], v[180:183], v[196:199], v[62:65]
	v_mfma_f32_16x16x32_bf16 v[54:57], v[188:191], v[196:199], v[54:57]
	v_mfma_f32_16x16x32_bf16 v[46:49], v[180:183], v[204:207], v[46:49]
	v_mfma_f32_16x16x32_bf16 v[38:41], v[188:191], v[204:207], v[38:41]
	v_mfma_f32_16x16x32_bf16 v[30:33], v[180:183], v[224:227], v[30:33]
	v_mfma_f32_16x16x32_bf16 v[22:25], v[188:191], v[224:227], v[22:25]
	v_mfma_f32_16x16x32_bf16 v[14:17], v[180:183], v[232:235], v[14:17]
	v_mfma_f32_16x16x32_bf16 v[6:9], v[188:191], v[232:235], v[6:9]
	v_mfma_f32_16x16x32_bf16 v[62:65], v[184:187], v[200:203], v[62:65]
	v_mfma_f32_16x16x32_bf16 v[54:57], v[192:195], v[200:203], v[54:57]
	v_mfma_f32_16x16x32_bf16 v[46:49], v[184:187], v[220:223], v[46:49]
	v_mfma_f32_16x16x32_bf16 v[38:41], v[192:195], v[220:223], v[38:41]
	v_mfma_f32_16x16x32_bf16 v[30:33], v[184:187], v[228:231], v[30:33]
	v_mfma_f32_16x16x32_bf16 v[22:25], v[192:195], v[228:231], v[22:25]
	v_mfma_f32_16x16x32_bf16 v[14:17], v[184:187], v[236:239], v[14:17]
	v_mfma_f32_16x16x32_bf16 v[6:9], v[192:195], v[236:239], v[6:9]
	s_setprio 0
	s_barrier
	s_add_i32 s53, s53, 2
	s_add_u32 s18, s18, 0x100
	s_addc_u32 s19, s19, 0
	s_add_u32 s51, s51, 0x100
	s_addc_u32 s52, s52, 0
	s_cmp_gt_u32 s53, 29
	s_cbranch_scc0 .LBB0_1565

.LBB0_1843:
	s_add_u32 s11, s14, 0x100
	s_addc_u32 s36, s15, 0
	s_add_u32 s12, s12, 0xc000
	s_addc_u32 s13, s13, 0
	s_mov_b32 s37, -2
	s_add_u32 s14, s12, 0x4000
	s_addc_u32 s15, s13, 0
	s_cmpk_eq_i32 s37, 0x54
	s_cselect_b32 s18, s6, s14
	s_cselect_b32 s19, s7, s15
	s_cselect_b32 s16, s8, s11
	s_cselect_b32 s17, s9, s36
	s_add_u32 s14, s18, 0x8000
	s_addc_u32 s15, s19, 0
	s_add_i32 s38, 0, 0x10000
	v_add_u32_e32 v0, s38, v246
	s_add_i32 s40, 0, 0x14000
	ds_read_b128 v[130:133], v0
	ds_read_b128 v[134:137], v0 offset:1024
	ds_read_b128 v[138:141], v0 offset:2048
	ds_read_b128 v[142:145], v0 offset:3072
	v_add_u32_e32 v0, s40, v246
	ds_read_b128 v[146:149], v0
	ds_read_b128 v[150:153], v0 offset:1024
	ds_read_b128 v[154:157], v0 offset:2048
	ds_read_b128 v[158:161], v0 offset:3072
	v_lshl_add_u64 v[194:195], s[12:13], 0, v[228:229]
	s_add_i32 m0, s47, 0xc000
	ds_read_b128 v[162:165], v247
	ds_read_b128 v[166:169], v247 offset:1024
	ds_read_b128 v[170:173], v247 offset:2048
	ds_read_b128 v[174:177], v247 offset:3072
	ds_read_b128 v[178:181], v247 offset:4096
	ds_read_b128 v[182:185], v247 offset:5120
	ds_read_b128 v[186:189], v247 offset:6144
	ds_read_b128 v[190:193], v247 offset:7168
	global_load_lds_dwordx4 v[194:195], off
	v_lshl_add_u64 v[194:195], s[12:13], 0, v[230:231]
	s_add_i32 m0, s47, 0xe000
	s_nop 0
	global_load_lds_dwordx4 v[194:195], off
	s_waitcnt vmcnt(8)
	s_waitcnt lgkmcnt(0)
	s_barrier
	s_setprio 1
	s_waitcnt lgkmcnt(0)
	v_mfma_f32_16x16x32_bf16 v[126:129], v[130:133], v[162:165], 0
	v_mfma_f32_16x16x32_bf16 v[122:125], v[138:141], v[162:165], 0
	v_mfma_f32_16x16x32_bf16 v[114:117], v[130:133], v[170:173], 0
	v_mfma_f32_16x16x32_bf16 v[106:109], v[138:141], v[170:173], 0
	v_mfma_f32_16x16x32_bf16 v[94:97], v[130:133], v[178:181], 0
	v_mfma_f32_16x16x32_bf16 v[90:93], v[138:141], v[178:181], 0
	v_mfma_f32_16x16x32_bf16 v[86:89], v[130:133], v[186:189], 0
	v_mfma_f32_16x16x32_bf16 v[82:85], v[138:141], v[186:189], 0
	v_mfma_f32_16x16x32_bf16 v[126:129], v[134:137], v[166:169], v[126:129]
	v_mfma_f32_16x16x32_bf16 v[122:125], v[142:145], v[166:169], v[122:125]
	v_mfma_f32_16x16x32_bf16 v[114:117], v[134:137], v[174:177], v[114:117]
	v_mfma_f32_16x16x32_bf16 v[106:109], v[142:145], v[174:177], v[106:109]
	v_mfma_f32_16x16x32_bf16 v[94:97], v[134:137], v[182:185], v[94:97]
	v_mfma_f32_16x16x32_bf16 v[90:93], v[142:145], v[182:185], v[90:93]
	v_mfma_f32_16x16x32_bf16 v[86:89], v[134:137], v[190:193], v[86:89]
	v_mfma_f32_16x16x32_bf16 v[82:85], v[142:145], v[190:193], v[82:85]
	s_setprio 0
	s_setprio 1
	v_mfma_f32_16x16x32_bf16 v[118:121], v[146:149], v[162:165], 0
	v_mfma_f32_16x16x32_bf16 v[110:113], v[154:157], v[162:165], 0
	v_mfma_f32_16x16x32_bf16 v[102:105], v[146:149], v[170:173], 0
	v_mfma_f32_16x16x32_bf16 v[98:101], v[154:157], v[170:173], 0
	v_mfma_f32_16x16x32_bf16 v[78:81], v[146:149], v[178:181], 0
	v_mfma_f32_16x16x32_bf16 v[74:77], v[154:157], v[178:181], 0
	v_mfma_f32_16x16x32_bf16 v[70:73], v[146:149], v[186:189], 0
	v_mfma_f32_16x16x32_bf16 v[66:69], v[154:157], v[186:189], 0
	v_mfma_f32_16x16x32_bf16 v[118:121], v[150:153], v[166:169], v[118:121]
	v_mfma_f32_16x16x32_bf16 v[110:113], v[158:161], v[166:169], v[110:113]
	v_mfma_f32_16x16x32_bf16 v[102:105], v[150:153], v[174:177], v[102:105]
	v_mfma_f32_16x16x32_bf16 v[98:101], v[158:161], v[174:177], v[98:101]
	v_mfma_f32_16x16x32_bf16 v[78:81], v[150:153], v[182:185], v[78:81]
	v_mfma_f32_16x16x32_bf16 v[74:77], v[158:161], v[182:185], v[74:77]
	v_mfma_f32_16x16x32_bf16 v[70:73], v[150:153], v[190:193], v[70:73]
	v_mfma_f32_16x16x32_bf16 v[66:69], v[158:161], v[190:193], v[66:69]
	s_setprio 0
	s_barrier
	s_add_i32 s38, s38, s46
	v_lshl_add_u64 v[194:195], s[16:17], 0, v[222:223]
	s_mov_b32 m0, s38
	ds_read_b128 v[162:165], v247 offset:16384
	ds_read_b128 v[166:169], v247 offset:17408
	ds_read_b128 v[170:173], v247 offset:18432
	ds_read_b128 v[174:177], v247 offset:19456
	ds_read_b128 v[178:181], v247 offset:20480
	ds_read_b128 v[182:185], v247 offset:21504
	ds_read_b128 v[186:189], v247 offset:22528
	ds_read_b128 v[190:193], v247 offset:23552
	global_load_lds_dwordx4 v[194:195], off
	s_add_i32 m0, s38, 0x2000
	s_add_u32 s38, s16, 0x164000
	v_lshl_add_u64 v[196:197], s[16:17], 0, v[226:227]
	s_addc_u32 s39, s17, 0
	s_add_i32 s40, s40, s46
	global_load_lds_dwordx4 v[196:197], off
	v_lshl_add_u64 v[198:199], s[38:39], 0, v[222:223]
	s_mov_b32 m0, s40
	s_nop 0
	global_load_lds_dwordx4 v[198:199], off
	v_lshl_add_u64 v[198:199], s[38:39], 0, v[226:227]
	s_add_i32 m0, s40, 0x2000
	s_nop 0
	global_load_lds_dwordx4 v[198:199], off
	v_lshl_add_u64 v[198:199], s[18:19], 0, v[220:221]
	s_mov_b32 m0, s47
	s_nop 0
	global_load_lds_dwordx4 v[198:199], off
	v_lshl_add_u64 v[198:199], s[18:19], 0, v[224:225]
	s_mov_b32 m0, s74
	s_nop 0
	global_load_lds_dwordx4 v[198:199], off
	s_waitcnt vmcnt(8)
	s_waitcnt lgkmcnt(0)
	s_barrier
	s_setprio 1
	s_waitcnt lgkmcnt(0)
	v_mfma_f32_16x16x32_bf16 v[62:65], v[130:133], v[162:165], 0
	v_mfma_f32_16x16x32_bf16 v[58:61], v[138:141], v[162:165], 0
	v_mfma_f32_16x16x32_bf16 v[54:57], v[130:133], v[170:173], 0
	v_mfma_f32_16x16x32_bf16 v[50:53], v[138:141], v[170:173], 0
	v_mfma_f32_16x16x32_bf16 v[30:33], v[130:133], v[178:181], 0
	v_mfma_f32_16x16x32_bf16 v[26:29], v[138:141], v[178:181], 0
	v_mfma_f32_16x16x32_bf16 v[22:25], v[130:133], v[186:189], 0
	v_mfma_f32_16x16x32_bf16 v[18:21], v[138:141], v[186:189], 0
	v_mfma_f32_16x16x32_bf16 v[62:65], v[134:137], v[166:169], v[62:65]
	v_mfma_f32_16x16x32_bf16 v[58:61], v[142:145], v[166:169], v[58:61]
	v_mfma_f32_16x16x32_bf16 v[54:57], v[134:137], v[174:177], v[54:57]
	v_mfma_f32_16x16x32_bf16 v[50:53], v[142:145], v[174:177], v[50:53]
	v_mfma_f32_16x16x32_bf16 v[30:33], v[134:137], v[182:185], v[30:33]
	v_mfma_f32_16x16x32_bf16 v[26:29], v[142:145], v[182:185], v[26:29]
	v_mfma_f32_16x16x32_bf16 v[22:25], v[134:137], v[190:193], v[22:25]
	v_mfma_f32_16x16x32_bf16 v[18:21], v[142:145], v[190:193], v[18:21]
	s_setprio 0
	s_setprio 1
	v_mfma_f32_16x16x32_bf16 v[46:49], v[146:149], v[162:165], 0
	v_mfma_f32_16x16x32_bf16 v[42:45], v[154:157], v[162:165], 0
	v_mfma_f32_16x16x32_bf16 v[38:41], v[146:149], v[170:173], 0
	v_mfma_f32_16x16x32_bf16 v[34:37], v[154:157], v[170:173], 0
	v_mfma_f32_16x16x32_bf16 v[14:17], v[146:149], v[178:181], 0
	v_mfma_f32_16x16x32_bf16 v[10:13], v[154:157], v[178:181], 0
	v_mfma_f32_16x16x32_bf16 v[6:9], v[146:149], v[186:189], 0
	v_mfma_f32_16x16x32_bf16 v[2:5], v[154:157], v[186:189], 0
	v_mfma_f32_16x16x32_bf16 v[46:49], v[150:153], v[166:169], v[46:49]
	v_mfma_f32_16x16x32_bf16 v[42:45], v[158:161], v[166:169], v[42:45]
	v_mfma_f32_16x16x32_bf16 v[38:41], v[150:153], v[174:177], v[38:41]
	v_mfma_f32_16x16x32_bf16 v[34:37], v[158:161], v[174:177], v[34:37]
	v_mfma_f32_16x16x32_bf16 v[14:17], v[150:153], v[182:185], v[14:17]
	v_mfma_f32_16x16x32_bf16 v[10:13], v[158:161], v[182:185], v[10:13]
	v_mfma_f32_16x16x32_bf16 v[6:9], v[150:153], v[190:193], v[6:9]
	v_mfma_f32_16x16x32_bf16 v[2:5], v[158:161], v[190:193], v[2:5]
	s_setprio 0
	s_barrier
	s_add_i32 s38, 0, 0x18000
	v_add_u32_e32 v0, s38, v246
	s_add_i32 s39, 0, 0x1c000
	ds_read_b128 v[130:133], v0
	ds_read_b128 v[134:137], v0 offset:1024
	ds_read_b128 v[138:141], v0 offset:2048
	ds_read_b128 v[142:145], v0 offset:3072
	v_add_u32_e32 v0, s39, v246
	ds_read_b128 v[146:149], v0
	ds_read_b128 v[150:153], v0 offset:1024
	ds_read_b128 v[154:157], v0 offset:2048
	ds_read_b128 v[158:161], v0 offset:3072
	s_add_u32 s18, s18, 0x4000
	s_addc_u32 s19, s19, 0
	s_mov_b32 m0, s75
	v_lshl_add_u64 v[198:199], s[18:19], 0, v[220:221]
	ds_read_b128 v[162:165], v247 offset:32768
	ds_read_b128 v[166:169], v247 offset:33792
	ds_read_b128 v[170:173], v247 offset:34816
	ds_read_b128 v[174:177], v247 offset:35840
	ds_read_b128 v[178:181], v247 offset:36864
	ds_read_b128 v[182:185], v247 offset:37888
	ds_read_b128 v[186:189], v247 offset:38912
	ds_read_b128 v[190:193], v247 offset:39936
	global_load_lds_dwordx4 v[198:199], off
	v_lshl_add_u64 v[198:199], s[18:19], 0, v[224:225]
	s_mov_b32 m0, s86
	s_nop 0
	global_load_lds_dwordx4 v[198:199], off
	s_waitcnt vmcnt(8)
	s_waitcnt lgkmcnt(0)
	s_barrier
	s_setprio 1
	s_waitcnt lgkmcnt(0)
	v_mfma_f32_16x16x32_bf16 v[126:129], v[130:133], v[162:165], v[126:129]
	v_mfma_f32_16x16x32_bf16 v[122:125], v[138:141], v[162:165], v[122:125]
	v_mfma_f32_16x16x32_bf16 v[114:117], v[130:133], v[170:173], v[114:117]
	v_mfma_f32_16x16x32_bf16 v[106:109], v[138:141], v[170:173], v[106:109]
	v_mfma_f32_16x16x32_bf16 v[94:97], v[130:133], v[178:181], v[94:97]
	v_mfma_f32_16x16x32_bf16 v[90:93], v[138:141], v[178:181], v[90:93]
	v_mfma_f32_16x16x32_bf16 v[86:89], v[130:133], v[186:189], v[86:89]
	v_mfma_f32_16x16x32_bf16 v[82:85], v[138:141], v[186:189], v[82:85]
	v_mfma_f32_16x16x32_bf16 v[126:129], v[134:137], v[166:169], v[126:129]
	v_mfma_f32_16x16x32_bf16 v[122:125], v[142:145], v[166:169], v[122:125]
	v_mfma_f32_16x16x32_bf16 v[114:117], v[134:137], v[174:177], v[114:117]
	v_mfma_f32_16x16x32_bf16 v[106:109], v[142:145], v[174:177], v[106:109]
	v_mfma_f32_16x16x32_bf16 v[94:97], v[134:137], v[182:185], v[94:97]
	v_mfma_f32_16x16x32_bf16 v[90:93], v[142:145], v[182:185], v[90:93]
	v_mfma_f32_16x16x32_bf16 v[86:89], v[134:137], v[190:193], v[86:89]
	v_mfma_f32_16x16x32_bf16 v[82:85], v[142:145], v[190:193], v[82:85]
	s_setprio 0
	s_setprio 1
	v_mfma_f32_16x16x32_bf16 v[118:121], v[146:149], v[162:165], v[118:121]
	v_mfma_f32_16x16x32_bf16 v[110:113], v[154:157], v[162:165], v[110:113]
	v_mfma_f32_16x16x32_bf16 v[102:105], v[146:149], v[170:173], v[102:105]
	v_mfma_f32_16x16x32_bf16 v[98:101], v[154:157], v[170:173], v[98:101]
	v_mfma_f32_16x16x32_bf16 v[78:81], v[146:149], v[178:181], v[78:81]
	v_mfma_f32_16x16x32_bf16 v[74:77], v[154:157], v[178:181], v[74:77]
	v_mfma_f32_16x16x32_bf16 v[70:73], v[146:149], v[186:189], v[70:73]
	v_mfma_f32_16x16x32_bf16 v[66:69], v[154:157], v[186:189], v[66:69]
	v_mfma_f32_16x16x32_bf16 v[118:121], v[150:153], v[166:169], v[118:121]
	v_mfma_f32_16x16x32_bf16 v[110:113], v[158:161], v[166:169], v[110:113]
	v_mfma_f32_16x16x32_bf16 v[102:105], v[150:153], v[174:177], v[102:105]
	v_mfma_f32_16x16x32_bf16 v[98:101], v[158:161], v[174:177], v[98:101]
	v_mfma_f32_16x16x32_bf16 v[78:81], v[150:153], v[182:185], v[78:81]
	v_mfma_f32_16x16x32_bf16 v[74:77], v[158:161], v[182:185], v[74:77]
	v_mfma_f32_16x16x32_bf16 v[70:73], v[150:153], v[190:193], v[70:73]
	v_mfma_f32_16x16x32_bf16 v[66:69], v[158:161], v[190:193], v[66:69]
	s_setprio 0
	s_barrier
	s_add_i32 s18, s38, s46
	v_lshl_add_u64 v[194:195], v[194:195], 0, s[2:3]
	s_mov_b32 m0, s18
	ds_read_b128 v[162:165], v247 offset:49152
	ds_read_b128 v[166:169], v247 offset:50176
	ds_read_b128 v[170:173], v247 offset:51200
	ds_read_b128 v[174:177], v247 offset:52224
	ds_read_b128 v[178:181], v247 offset:53248
	ds_read_b128 v[182:185], v247 offset:54272
	ds_read_b128 v[186:189], v247 offset:55296
	ds_read_b128 v[190:193], v247 offset:56320
	global_load_lds_dwordx4 v[194:195], off
	s_add_i32 m0, s18, 0x2000
	s_add_u32 s16, s16, 0x164080
	v_lshl_add_u64 v[194:195], v[196:197], 0, s[2:3]
	s_addc_u32 s17, s17, 0
	s_add_i32 s18, s39, s46
	global_load_lds_dwordx4 v[194:195], off
	v_lshl_add_u64 v[194:195], s[16:17], 0, v[222:223]
	s_mov_b32 m0, s18
	s_nop 0
	global_load_lds_dwordx4 v[194:195], off
	v_lshl_add_u64 v[194:195], s[16:17], 0, v[226:227]
	s_add_i32 m0, s18, 0x2000
	s_nop 0
	global_load_lds_dwordx4 v[194:195], off
	v_lshl_add_u64 v[194:195], s[14:15], 0, v[220:221]
	s_mov_b32 m0, s50
	s_nop 0
	global_load_lds_dwordx4 v[194:195], off
	v_lshl_add_u64 v[194:195], s[14:15], 0, v[224:225]
	s_mov_b32 m0, s51
	s_nop 0
	global_load_lds_dwordx4 v[194:195], off
	s_waitcnt vmcnt(8)
	s_waitcnt lgkmcnt(0)
	s_barrier
	s_setprio 1
	s_waitcnt lgkmcnt(0)
	v_mfma_f32_16x16x32_bf16 v[62:65], v[130:133], v[162:165], v[62:65]
	v_mfma_f32_16x16x32_bf16 v[58:61], v[138:141], v[162:165], v[58:61]
	v_mfma_f32_16x16x32_bf16 v[54:57], v[130:133], v[170:173], v[54:57]
	v_mfma_f32_16x16x32_bf16 v[50:53], v[138:141], v[170:173], v[50:53]
	v_mfma_f32_16x16x32_bf16 v[30:33], v[130:133], v[178:181], v[30:33]
	v_mfma_f32_16x16x32_bf16 v[26:29], v[138:141], v[178:181], v[26:29]
	v_mfma_f32_16x16x32_bf16 v[22:25], v[130:133], v[186:189], v[22:25]
	v_mfma_f32_16x16x32_bf16 v[18:21], v[138:141], v[186:189], v[18:21]
	v_mfma_f32_16x16x32_bf16 v[62:65], v[134:137], v[166:169], v[62:65]
	v_mfma_f32_16x16x32_bf16 v[58:61], v[142:145], v[166:169], v[58:61]
	v_mfma_f32_16x16x32_bf16 v[54:57], v[134:137], v[174:177], v[54:57]
	v_mfma_f32_16x16x32_bf16 v[50:53], v[142:145], v[174:177], v[50:53]
	v_mfma_f32_16x16x32_bf16 v[30:33], v[134:137], v[182:185], v[30:33]
	v_mfma_f32_16x16x32_bf16 v[26:29], v[142:145], v[182:185], v[26:29]
	v_mfma_f32_16x16x32_bf16 v[22:25], v[134:137], v[190:193], v[22:25]
	v_mfma_f32_16x16x32_bf16 v[18:21], v[142:145], v[190:193], v[18:21]
	s_setprio 0
	s_setprio 1
	v_mfma_f32_16x16x32_bf16 v[46:49], v[146:149], v[162:165], v[46:49]
	v_mfma_f32_16x16x32_bf16 v[42:45], v[154:157], v[162:165], v[42:45]
	v_mfma_f32_16x16x32_bf16 v[38:41], v[146:149], v[170:173], v[38:41]
	v_mfma_f32_16x16x32_bf16 v[34:37], v[154:157], v[170:173], v[34:37]
	v_mfma_f32_16x16x32_bf16 v[14:17], v[146:149], v[178:181], v[14:17]
	v_mfma_f32_16x16x32_bf16 v[10:13], v[154:157], v[178:181], v[10:13]
	v_mfma_f32_16x16x32_bf16 v[6:9], v[146:149], v[186:189], v[6:9]
	v_mfma_f32_16x16x32_bf16 v[2:5], v[154:157], v[186:189], v[2:5]
	v_mfma_f32_16x16x32_bf16 v[46:49], v[150:153], v[166:169], v[46:49]
	v_mfma_f32_16x16x32_bf16 v[42:45], v[158:161], v[166:169], v[42:45]
	v_mfma_f32_16x16x32_bf16 v[38:41], v[150:153], v[174:177], v[38:41]
	v_mfma_f32_16x16x32_bf16 v[34:37], v[158:161], v[174:177], v[34:37]
	v_mfma_f32_16x16x32_bf16 v[14:17], v[150:153], v[182:185], v[14:17]
	v_mfma_f32_16x16x32_bf16 v[10:13], v[158:161], v[182:185], v[10:13]
	v_mfma_f32_16x16x32_bf16 v[6:9], v[150:153], v[190:193], v[6:9]
	v_mfma_f32_16x16x32_bf16 v[2:5], v[158:161], v[190:193], v[2:5]
	s_setprio 0
	s_barrier
	s_add_i32 s37, s37, 2
	s_add_u32 s11, s11, 0x100
	s_addc_u32 s36, s36, 0
	s_add_u32 s12, s12, 0x10000
	s_addc_u32 s13, s13, 0
	s_cmpk_gt_u32 s37, 0x55
	s_cbranch_scc1 .Lpeel_done_5
.LBB0_1844:
	s_add_u32 s14, s12, 0x4000
	s_addc_u32 s15, s13, 0
	s_cmpk_eq_i32 s37, 0x54
	s_cselect_b32 s18, s6, s14
	s_cselect_b32 s19, s7, s15
	s_cselect_b32 s16, s8, s11
	s_cselect_b32 s17, s9, s36
	s_add_u32 s14, s18, 0x8000
	s_addc_u32 s15, s19, 0
	s_add_i32 s38, 0, 0x10000
	v_add_u32_e32 v0, s38, v246
	s_add_i32 s40, 0, 0x14000
	ds_read_b128 v[130:133], v0
	ds_read_b128 v[134:137], v0 offset:1024
	ds_read_b128 v[138:141], v0 offset:2048
	ds_read_b128 v[142:145], v0 offset:3072
	v_add_u32_e32 v0, s40, v246
	ds_read_b128 v[146:149], v0
	ds_read_b128 v[150:153], v0 offset:1024
	ds_read_b128 v[154:157], v0 offset:2048
	ds_read_b128 v[158:161], v0 offset:3072
	v_lshl_add_u64 v[194:195], s[12:13], 0, v[228:229]
	s_add_i32 m0, s47, 0xc000
	ds_read_b128 v[162:165], v247
	ds_read_b128 v[166:169], v247 offset:1024
	ds_read_b128 v[170:173], v247 offset:2048
	ds_read_b128 v[174:177], v247 offset:3072
	ds_read_b128 v[178:181], v247 offset:4096
	ds_read_b128 v[182:185], v247 offset:5120
	ds_read_b128 v[186:189], v247 offset:6144
	ds_read_b128 v[190:193], v247 offset:7168
	global_load_lds_dwordx4 v[194:195], off
	v_lshl_add_u64 v[194:195], s[12:13], 0, v[230:231]
	s_add_i32 m0, s47, 0xe000
	s_nop 0
	global_load_lds_dwordx4 v[194:195], off
	s_waitcnt vmcnt(8)
	s_waitcnt lgkmcnt(0)
	s_barrier
	s_setprio 1
	s_waitcnt lgkmcnt(0)
	v_mfma_f32_16x16x32_bf16 v[126:129], v[130:133], v[162:165], v[126:129]
	v_mfma_f32_16x16x32_bf16 v[122:125], v[138:141], v[162:165], v[122:125]
	v_mfma_f32_16x16x32_bf16 v[114:117], v[130:133], v[170:173], v[114:117]
	v_mfma_f32_16x16x32_bf16 v[106:109], v[138:141], v[170:173], v[106:109]
	v_mfma_f32_16x16x32_bf16 v[94:97], v[130:133], v[178:181], v[94:97]
	v_mfma_f32_16x16x32_bf16 v[90:93], v[138:141], v[178:181], v[90:93]
	v_mfma_f32_16x16x32_bf16 v[86:89], v[130:133], v[186:189], v[86:89]
	v_mfma_f32_16x16x32_bf16 v[82:85], v[138:141], v[186:189], v[82:85]
	v_mfma_f32_16x16x32_bf16 v[126:129], v[134:137], v[166:169], v[126:129]
	v_mfma_f32_16x16x32_bf16 v[122:125], v[142:145], v[166:169], v[122:125]
	v_mfma_f32_16x16x32_bf16 v[114:117], v[134:137], v[174:177], v[114:117]
	v_mfma_f32_16x16x32_bf16 v[106:109], v[142:145], v[174:177], v[106:109]
	v_mfma_f32_16x16x32_bf16 v[94:97], v[134:137], v[182:185], v[94:97]
	v_mfma_f32_16x16x32_bf16 v[90:93], v[142:145], v[182:185], v[90:93]
	v_mfma_f32_16x16x32_bf16 v[86:89], v[134:137], v[190:193], v[86:89]
	v_mfma_f32_16x16x32_bf16 v[82:85], v[142:145], v[190:193], v[82:85]
	s_setprio 0
	s_setprio 1
	v_mfma_f32_16x16x32_bf16 v[118:121], v[146:149], v[162:165], v[118:121]
	v_mfma_f32_16x16x32_bf16 v[110:113], v[154:157], v[162:165], v[110:113]
	v_mfma_f32_16x16x32_bf16 v[102:105], v[146:149], v[170:173], v[102:105]
	v_mfma_f32_16x16x32_bf16 v[98:101], v[154:157], v[170:173], v[98:101]
	v_mfma_f32_16x16x32_bf16 v[78:81], v[146:149], v[178:181], v[78:81]
	v_mfma_f32_16x16x32_bf16 v[74:77], v[154:157], v[178:181], v[74:77]
	v_mfma_f32_16x16x32_bf16 v[70:73], v[146:149], v[186:189], v[70:73]
	v_mfma_f32_16x16x32_bf16 v[66:69], v[154:157], v[186:189], v[66:69]
	v_mfma_f32_16x16x32_bf16 v[118:121], v[150:153], v[166:169], v[118:121]
	v_mfma_f32_16x16x32_bf16 v[110:113], v[158:161], v[166:169], v[110:113]
	v_mfma_f32_16x16x32_bf16 v[102:105], v[150:153], v[174:177], v[102:105]
	v_mfma_f32_16x16x32_bf16 v[98:101], v[158:161], v[174:177], v[98:101]
	v_mfma_f32_16x16x32_bf16 v[78:81], v[150:153], v[182:185], v[78:81]
	v_mfma_f32_16x16x32_bf16 v[74:77], v[158:161], v[182:185], v[74:77]
	v_mfma_f32_16x16x32_bf16 v[70:73], v[150:153], v[190:193], v[70:73]
	v_mfma_f32_16x16x32_bf16 v[66:69], v[158:161], v[190:193], v[66:69]
	s_setprio 0
	s_barrier
	s_add_i32 s38, s38, s46
	v_lshl_add_u64 v[194:195], s[16:17], 0, v[222:223]
	s_mov_b32 m0, s38
	ds_read_b128 v[162:165], v247 offset:16384
	ds_read_b128 v[166:169], v247 offset:17408
	ds_read_b128 v[170:173], v247 offset:18432
	ds_read_b128 v[174:177], v247 offset:19456
	ds_read_b128 v[178:181], v247 offset:20480
	ds_read_b128 v[182:185], v247 offset:21504
	ds_read_b128 v[186:189], v247 offset:22528
	ds_read_b128 v[190:193], v247 offset:23552
	global_load_lds_dwordx4 v[194:195], off
	s_add_i32 m0, s38, 0x2000
	s_add_u32 s38, s16, 0x164000
	v_lshl_add_u64 v[196:197], s[16:17], 0, v[226:227]
	s_addc_u32 s39, s17, 0
	s_add_i32 s40, s40, s46
	global_load_lds_dwordx4 v[196:197], off
	v_lshl_add_u64 v[198:199], s[38:39], 0, v[222:223]
	s_mov_b32 m0, s40
	s_nop 0
	global_load_lds_dwordx4 v[198:199], off
	v_lshl_add_u64 v[198:199], s[38:39], 0, v[226:227]
	s_add_i32 m0, s40, 0x2000
	s_nop 0
	global_load_lds_dwordx4 v[198:199], off
	v_lshl_add_u64 v[198:199], s[18:19], 0, v[220:221]
	s_mov_b32 m0, s47
	s_nop 0
	global_load_lds_dwordx4 v[198:199], off
	v_lshl_add_u64 v[198:199], s[18:19], 0, v[224:225]
	s_mov_b32 m0, s74
	s_nop 0
	global_load_lds_dwordx4 v[198:199], off
	s_waitcnt vmcnt(8)
	s_waitcnt lgkmcnt(0)
	s_barrier
	s_setprio 1
	s_waitcnt lgkmcnt(0)
	v_mfma_f32_16x16x32_bf16 v[62:65], v[130:133], v[162:165], v[62:65]
	v_mfma_f32_16x16x32_bf16 v[58:61], v[138:141], v[162:165], v[58:61]
	v_mfma_f32_16x16x32_bf16 v[54:57], v[130:133], v[170:173], v[54:57]
	v_mfma_f32_16x16x32_bf16 v[50:53], v[138:141], v[170:173], v[50:53]
	v_mfma_f32_16x16x32_bf16 v[30:33], v[130:133], v[178:181], v[30:33]
	v_mfma_f32_16x16x32_bf16 v[26:29], v[138:141], v[178:181], v[26:29]
	v_mfma_f32_16x16x32_bf16 v[22:25], v[130:133], v[186:189], v[22:25]
	v_mfma_f32_16x16x32_bf16 v[18:21], v[138:141], v[186:189], v[18:21]
	v_mfma_f32_16x16x32_bf16 v[62:65], v[134:137], v[166:169], v[62:65]
	v_mfma_f32_16x16x32_bf16 v[58:61], v[142:145], v[166:169], v[58:61]
	v_mfma_f32_16x16x32_bf16 v[54:57], v[134:137], v[174:177], v[54:57]
	v_mfma_f32_16x16x32_bf16 v[50:53], v[142:145], v[174:177], v[50:53]
	v_mfma_f32_16x16x32_bf16 v[30:33], v[134:137], v[182:185], v[30:33]
	v_mfma_f32_16x16x32_bf16 v[26:29], v[142:145], v[182:185], v[26:29]
	v_mfma_f32_16x16x32_bf16 v[22:25], v[134:137], v[190:193], v[22:25]
	v_mfma_f32_16x16x32_bf16 v[18:21], v[142:145], v[190:193], v[18:21]
	s_setprio 0
	s_setprio 1
	v_mfma_f32_16x16x32_bf16 v[46:49], v[146:149], v[162:165], v[46:49]
	v_mfma_f32_16x16x32_bf16 v[42:45], v[154:157], v[162:165], v[42:45]
	v_mfma_f32_16x16x32_bf16 v[38:41], v[146:149], v[170:173], v[38:41]
	v_mfma_f32_16x16x32_bf16 v[34:37], v[154:157], v[170:173], v[34:37]
	v_mfma_f32_16x16x32_bf16 v[14:17], v[146:149], v[178:181], v[14:17]
	v_mfma_f32_16x16x32_bf16 v[10:13], v[154:157], v[178:181], v[10:13]
	v_mfma_f32_16x16x32_bf16 v[6:9], v[146:149], v[186:189], v[6:9]
	v_mfma_f32_16x16x32_bf16 v[2:5], v[154:157], v[186:189], v[2:5]
	v_mfma_f32_16x16x32_bf16 v[46:49], v[150:153], v[166:169], v[46:49]
	v_mfma_f32_16x16x32_bf16 v[42:45], v[158:161], v[166:169], v[42:45]
	v_mfma_f32_16x16x32_bf16 v[38:41], v[150:153], v[174:177], v[38:41]
	v_mfma_f32_16x16x32_bf16 v[34:37], v[158:161], v[174:177], v[34:37]
	v_mfma_f32_16x16x32_bf16 v[14:17], v[150:153], v[182:185], v[14:17]
	v_mfma_f32_16x16x32_bf16 v[10:13], v[158:161], v[182:185], v[10:13]
	v_mfma_f32_16x16x32_bf16 v[6:9], v[150:153], v[190:193], v[6:9]
	v_mfma_f32_16x16x32_bf16 v[2:5], v[158:161], v[190:193], v[2:5]
	s_setprio 0
	s_barrier
	s_add_i32 s38, 0, 0x18000
	v_add_u32_e32 v0, s38, v246
	s_add_i32 s39, 0, 0x1c000
	ds_read_b128 v[130:133], v0
	ds_read_b128 v[134:137], v0 offset:1024
	ds_read_b128 v[138:141], v0 offset:2048
	ds_read_b128 v[142:145], v0 offset:3072
	v_add_u32_e32 v0, s39, v246
	ds_read_b128 v[146:149], v0
	ds_read_b128 v[150:153], v0 offset:1024
	ds_read_b128 v[154:157], v0 offset:2048
	ds_read_b128 v[158:161], v0 offset:3072
	s_add_u32 s18, s18, 0x4000
	s_addc_u32 s19, s19, 0
	s_mov_b32 m0, s75
	v_lshl_add_u64 v[198:199], s[18:19], 0, v[220:221]
	ds_read_b128 v[162:165], v247 offset:32768
	ds_read_b128 v[166:169], v247 offset:33792
	ds_read_b128 v[170:173], v247 offset:34816
	ds_read_b128 v[174:177], v247 offset:35840
	ds_read_b128 v[178:181], v247 offset:36864
	ds_read_b128 v[182:185], v247 offset:37888
	ds_read_b128 v[186:189], v247 offset:38912
	ds_read_b128 v[190:193], v247 offset:39936
	global_load_lds_dwordx4 v[198:199], off
	v_lshl_add_u64 v[198:199], s[18:19], 0, v[224:225]
	s_mov_b32 m0, s86
	s_nop 0
	global_load_lds_dwordx4 v[198:199], off
	s_waitcnt vmcnt(8)
	s_waitcnt lgkmcnt(0)
	s_barrier
	s_setprio 1
	s_waitcnt lgkmcnt(0)
	v_mfma_f32_16x16x32_bf16 v[126:129], v[130:133], v[162:165], v[126:129]
	v_mfma_f32_16x16x32_bf16 v[122:125], v[138:141], v[162:165], v[122:125]
	v_mfma_f32_16x16x32_bf16 v[114:117], v[130:133], v[170:173], v[114:117]
	v_mfma_f32_16x16x32_bf16 v[106:109], v[138:141], v[170:173], v[106:109]
	v_mfma_f32_16x16x32_bf16 v[94:97], v[130:133], v[178:181], v[94:97]
	v_mfma_f32_16x16x32_bf16 v[90:93], v[138:141], v[178:181], v[90:93]
	v_mfma_f32_16x16x32_bf16 v[86:89], v[130:133], v[186:189], v[86:89]
	v_mfma_f32_16x16x32_bf16 v[82:85], v[138:141], v[186:189], v[82:85]
	v_mfma_f32_16x16x32_bf16 v[126:129], v[134:137], v[166:169], v[126:129]
	v_mfma_f32_16x16x32_bf16 v[122:125], v[142:145], v[166:169], v[122:125]
	v_mfma_f32_16x16x32_bf16 v[114:117], v[134:137], v[174:177], v[114:117]
	v_mfma_f32_16x16x32_bf16 v[106:109], v[142:145], v[174:177], v[106:109]
	v_mfma_f32_16x16x32_bf16 v[94:97], v[134:137], v[182:185], v[94:97]
	v_mfma_f32_16x16x32_bf16 v[90:93], v[142:145], v[182:185], v[90:93]
	v_mfma_f32_16x16x32_bf16 v[86:89], v[134:137], v[190:193], v[86:89]
	v_mfma_f32_16x16x32_bf16 v[82:85], v[142:145], v[190:193], v[82:85]
	s_setprio 0
	s_setprio 1
	v_mfma_f32_16x16x32_bf16 v[118:121], v[146:149], v[162:165], v[118:121]
	v_mfma_f32_16x16x32_bf16 v[110:113], v[154:157], v[162:165], v[110:113]
	v_mfma_f32_16x16x32_bf16 v[102:105], v[146:149], v[170:173], v[102:105]
	v_mfma_f32_16x16x32_bf16 v[98:101], v[154:157], v[170:173], v[98:101]
	v_mfma_f32_16x16x32_bf16 v[78:81], v[146:149], v[178:181], v[78:81]
	v_mfma_f32_16x16x32_bf16 v[74:77], v[154:157], v[178:181], v[74:77]
	v_mfma_f32_16x16x32_bf16 v[70:73], v[146:149], v[186:189], v[70:73]
	v_mfma_f32_16x16x32_bf16 v[66:69], v[154:157], v[186:189], v[66:69]
	v_mfma_f32_16x16x32_bf16 v[118:121], v[150:153], v[166:169], v[118:121]
	v_mfma_f32_16x16x32_bf16 v[110:113], v[158:161], v[166:169], v[110:113]
	v_mfma_f32_16x16x32_bf16 v[102:105], v[150:153], v[174:177], v[102:105]
	v_mfma_f32_16x16x32_bf16 v[98:101], v[158:161], v[174:177], v[98:101]
	v_mfma_f32_16x16x32_bf16 v[78:81], v[150:153], v[182:185], v[78:81]
	v_mfma_f32_16x16x32_bf16 v[74:77], v[158:161], v[182:185], v[74:77]
	v_mfma_f32_16x16x32_bf16 v[70:73], v[150:153], v[190:193], v[70:73]
	v_mfma_f32_16x16x32_bf16 v[66:69], v[158:161], v[190:193], v[66:69]
	s_setprio 0
	s_barrier
	s_add_i32 s18, s38, s46
	v_lshl_add_u64 v[194:195], v[194:195], 0, s[2:3]
	s_mov_b32 m0, s18
	ds_read_b128 v[162:165], v247 offset:49152
	ds_read_b128 v[166:169], v247 offset:50176
	ds_read_b128 v[170:173], v247 offset:51200
	ds_read_b128 v[174:177], v247 offset:52224
	ds_read_b128 v[178:181], v247 offset:53248
	ds_read_b128 v[182:185], v247 offset:54272
	ds_read_b128 v[186:189], v247 offset:55296
	ds_read_b128 v[190:193], v247 offset:56320
	global_load_lds_dwordx4 v[194:195], off
	s_add_i32 m0, s18, 0x2000
	s_add_u32 s16, s16, 0x164080
	v_lshl_add_u64 v[194:195], v[196:197], 0, s[2:3]
	s_addc_u32 s17, s17, 0
	s_add_i32 s18, s39, s46
	global_load_lds_dwordx4 v[194:195], off
	v_lshl_add_u64 v[194:195], s[16:17], 0, v[222:223]
	s_mov_b32 m0, s18
	s_nop 0
	global_load_lds_dwordx4 v[194:195], off
	v_lshl_add_u64 v[194:195], s[16:17], 0, v[226:227]
	s_add_i32 m0, s18, 0x2000
	s_nop 0
	global_load_lds_dwordx4 v[194:195], off
	v_lshl_add_u64 v[194:195], s[14:15], 0, v[220:221]
	s_mov_b32 m0, s50
	s_nop 0
	global_load_lds_dwordx4 v[194:195], off
	v_lshl_add_u64 v[194:195], s[14:15], 0, v[224:225]
	s_mov_b32 m0, s51
	s_nop 0
	global_load_lds_dwordx4 v[194:195], off
	s_waitcnt vmcnt(8)
	s_waitcnt lgkmcnt(0)
	s_barrier
	s_setprio 1
	s_waitcnt lgkmcnt(0)
	v_mfma_f32_16x16x32_bf16 v[62:65], v[130:133], v[162:165], v[62:65]
	v_mfma_f32_16x16x32_bf16 v[58:61], v[138:141], v[162:165], v[58:61]
	v_mfma_f32_16x16x32_bf16 v[54:57], v[130:133], v[170:173], v[54:57]
	v_mfma_f32_16x16x32_bf16 v[50:53], v[138:141], v[170:173], v[50:53]
	v_mfma_f32_16x16x32_bf16 v[30:33], v[130:133], v[178:181], v[30:33]
	v_mfma_f32_16x16x32_bf16 v[26:29], v[138:141], v[178:181], v[26:29]
	v_mfma_f32_16x16x32_bf16 v[22:25], v[130:133], v[186:189], v[22:25]
	v_mfma_f32_16x16x32_bf16 v[18:21], v[138:141], v[186:189], v[18:21]
	v_mfma_f32_16x16x32_bf16 v[62:65], v[134:137], v[166:169], v[62:65]
	v_mfma_f32_16x16x32_bf16 v[58:61], v[142:145], v[166:169], v[58:61]
	v_mfma_f32_16x16x32_bf16 v[54:57], v[134:137], v[174:177], v[54:57]
	v_mfma_f32_16x16x32_bf16 v[50:53], v[142:145], v[174:177], v[50:53]
	v_mfma_f32_16x16x32_bf16 v[30:33], v[134:137], v[182:185], v[30:33]
	v_mfma_f32_16x16x32_bf16 v[26:29], v[142:145], v[182:185], v[26:29]
	v_mfma_f32_16x16x32_bf16 v[22:25], v[134:137], v[190:193], v[22:25]
	v_mfma_f32_16x16x32_bf16 v[18:21], v[142:145], v[190:193], v[18:21]
	s_setprio 0
	s_setprio 1
	v_mfma_f32_16x16x32_bf16 v[46:49], v[146:149], v[162:165], v[46:49]
	v_mfma_f32_16x16x32_bf16 v[42:45], v[154:157], v[162:165], v[42:45]
	v_mfma_f32_16x16x32_bf16 v[38:41], v[146:149], v[170:173], v[38:41]
	v_mfma_f32_16x16x32_bf16 v[34:37], v[154:157], v[170:173], v[34:37]
	v_mfma_f32_16x16x32_bf16 v[14:17], v[146:149], v[178:181], v[14:17]
	v_mfma_f32_16x16x32_bf16 v[10:13], v[154:157], v[178:181], v[10:13]
	v_mfma_f32_16x16x32_bf16 v[6:9], v[146:149], v[186:189], v[6:9]
	v_mfma_f32_16x16x32_bf16 v[2:5], v[154:157], v[186:189], v[2:5]
	v_mfma_f32_16x16x32_bf16 v[46:49], v[150:153], v[166:169], v[46:49]
	v_mfma_f32_16x16x32_bf16 v[42:45], v[158:161], v[166:169], v[42:45]
	v_mfma_f32_16x16x32_bf16 v[38:41], v[150:153], v[174:177], v[38:41]
	v_mfma_f32_16x16x32_bf16 v[34:37], v[158:161], v[174:177], v[34:37]
	v_mfma_f32_16x16x32_bf16 v[14:17], v[150:153], v[182:185], v[14:17]
	v_mfma_f32_16x16x32_bf16 v[10:13], v[158:161], v[182:185], v[10:13]
	v_mfma_f32_16x16x32_bf16 v[6:9], v[150:153], v[190:193], v[6:9]
	v_mfma_f32_16x16x32_bf16 v[2:5], v[158:161], v[190:193], v[2:5]
	s_setprio 0
	s_barrier
	s_add_i32 s37, s37, 2
	s_add_u32 s11, s11, 0x100
	s_addc_u32 s36, s36, 0
	s_add_u32 s12, s12, 0x10000
	s_addc_u32 s13, s13, 0
	s_cmpk_gt_u32 s37, 0x55
	s_cbranch_scc0 .LBB0_1844
.Lpeel_done_5:
	s_and_b64 vcc, exec, s[44:45]
	s_cbranch_vccz .LBB0_1847
	s_barrier

.LBB0_2016:
	s_add_u32 s36, s12, 0x100
	s_addc_u32 s37, s13, 0
	s_add_u32 s12, s14, 0xc000
	s_addc_u32 s13, s15, 0
	s_mov_b32 s50, -2
	s_add_u32 s14, s12, 0x4000
	s_addc_u32 s15, s13, 0
	s_cmp_eq_u32 s50, 18
	s_cselect_b32 s18, s8, s14
	s_cselect_b32 s19, s9, s15
	s_cselect_b32 s16, s10, s36
	s_cselect_b32 s17, s11, s37
	s_add_u32 s14, s18, 0x8000
	s_addc_u32 s15, s19, 0
	s_add_i32 s51, 0, 0x10000
	s_add_i32 s54, 0, 0x14000
	v_add_u32_e32 v156, s51, v140
	v_add_u32_e32 v172, s54, v140
	ds_read_b128 v[144:147], v156
	ds_read_b128 v[148:151], v156 offset:1024
	ds_read_b128 v[152:155], v156 offset:2048
	ds_read_b128 v[156:159], v156 offset:3072
	ds_read_b128 v[160:163], v172
	ds_read_b128 v[164:167], v172 offset:1024
	ds_read_b128 v[168:171], v172 offset:2048
	ds_read_b128 v[172:175], v172 offset:3072
	v_lshl_add_u64 v[208:209], s[12:13], 0, v[136:137]
	s_add_i32 m0, s38, 0xc000
	ds_read_b128 v[176:179], v143
	ds_read_b128 v[180:183], v143 offset:1024
	ds_read_b128 v[184:187], v143 offset:2048
	ds_read_b128 v[188:191], v143 offset:3072
	ds_read_b128 v[192:195], v143 offset:4096
	ds_read_b128 v[196:199], v143 offset:5120
	ds_read_b128 v[200:203], v143 offset:6144
	ds_read_b128 v[204:207], v143 offset:7168
	global_load_lds_dwordx4 v[208:209], off
	v_lshl_add_u64 v[208:209], s[12:13], 0, v[138:139]
	s_add_i32 m0, s38, 0xe000
	s_nop 0
	global_load_lds_dwordx4 v[208:209], off
	s_waitcnt vmcnt(8)
	s_waitcnt lgkmcnt(0)
	s_barrier
	s_setprio 1
	s_waitcnt lgkmcnt(0)
	v_mfma_f32_16x16x32_bf16 v[126:129], v[144:147], v[176:179], 0
	v_mfma_f32_16x16x32_bf16 v[122:125], v[152:155], v[176:179], 0
	v_mfma_f32_16x16x32_bf16 v[118:121], v[144:147], v[184:187], 0
	v_mfma_f32_16x16x32_bf16 v[114:117], v[152:155], v[184:187], 0
	v_mfma_f32_16x16x32_bf16 v[102:105], v[144:147], v[192:195], 0
	v_mfma_f32_16x16x32_bf16 v[98:101], v[152:155], v[192:195], 0
	v_mfma_f32_16x16x32_bf16 v[86:89], v[144:147], v[200:203], 0
	v_mfma_f32_16x16x32_bf16 v[82:85], v[152:155], v[200:203], 0
	v_mfma_f32_16x16x32_bf16 v[126:129], v[148:151], v[180:183], v[126:129]
	v_mfma_f32_16x16x32_bf16 v[122:125], v[156:159], v[180:183], v[122:125]
	v_mfma_f32_16x16x32_bf16 v[118:121], v[148:151], v[188:191], v[118:121]
	v_mfma_f32_16x16x32_bf16 v[114:117], v[156:159], v[188:191], v[114:117]
	v_mfma_f32_16x16x32_bf16 v[102:105], v[148:151], v[196:199], v[102:105]
	v_mfma_f32_16x16x32_bf16 v[98:101], v[156:159], v[196:199], v[98:101]
	v_mfma_f32_16x16x32_bf16 v[86:89], v[148:151], v[204:207], v[86:89]
	v_mfma_f32_16x16x32_bf16 v[82:85], v[156:159], v[204:207], v[82:85]
	s_setprio 0
	s_setprio 1
	v_mfma_f32_16x16x32_bf16 v[110:113], v[160:163], v[176:179], 0
	v_mfma_f32_16x16x32_bf16 v[106:109], v[168:171], v[176:179], 0
	v_mfma_f32_16x16x32_bf16 v[94:97], v[160:163], v[184:187], 0
	v_mfma_f32_16x16x32_bf16 v[90:93], v[168:171], v[184:187], 0
	v_mfma_f32_16x16x32_bf16 v[78:81], v[160:163], v[192:195], 0
	v_mfma_f32_16x16x32_bf16 v[74:77], v[168:171], v[192:195], 0
	v_mfma_f32_16x16x32_bf16 v[70:73], v[160:163], v[200:203], 0
	v_mfma_f32_16x16x32_bf16 v[66:69], v[168:171], v[200:203], 0
	v_mfma_f32_16x16x32_bf16 v[110:113], v[164:167], v[180:183], v[110:113]
	v_mfma_f32_16x16x32_bf16 v[106:109], v[172:175], v[180:183], v[106:109]
	v_mfma_f32_16x16x32_bf16 v[94:97], v[164:167], v[188:191], v[94:97]
	v_mfma_f32_16x16x32_bf16 v[90:93], v[172:175], v[188:191], v[90:93]
	v_mfma_f32_16x16x32_bf16 v[78:81], v[164:167], v[196:199], v[78:81]
	v_mfma_f32_16x16x32_bf16 v[74:77], v[172:175], v[196:199], v[74:77]
	v_mfma_f32_16x16x32_bf16 v[70:73], v[164:167], v[204:207], v[70:73]
	v_mfma_f32_16x16x32_bf16 v[66:69], v[172:175], v[204:207], v[66:69]
	s_setprio 0
	s_barrier
	s_add_i32 s51, s51, s24
	v_lshl_add_u64 v[208:209], s[16:17], 0, v[0:1]
	s_mov_b32 m0, s51
	ds_read_b128 v[176:179], v143 offset:16384
	ds_read_b128 v[180:183], v143 offset:17408
	ds_read_b128 v[184:187], v143 offset:18432
	ds_read_b128 v[188:191], v143 offset:19456
	ds_read_b128 v[192:195], v143 offset:20480
	ds_read_b128 v[196:199], v143 offset:21504
	ds_read_b128 v[200:203], v143 offset:22528
	ds_read_b128 v[204:207], v143 offset:23552
	global_load_lds_dwordx4 v[208:209], off
	s_add_i32 m0, s51, 0x2000
	s_add_u32 s52, s16, 0x164000
	v_lshl_add_u64 v[216:217], s[16:17], 0, v[130:131]
	s_addc_u32 s53, s17, 0
	s_add_i32 s51, s54, s24
	global_load_lds_dwordx4 v[216:217], off
	v_lshl_add_u64 v[220:221], s[52:53], 0, v[0:1]
	s_mov_b32 m0, s51
	s_nop 0
	global_load_lds_dwordx4 v[220:221], off
	v_lshl_add_u64 v[220:221], s[52:53], 0, v[130:131]
	s_add_i32 m0, s51, 0x2000
	s_nop 0
	global_load_lds_dwordx4 v[220:221], off
	v_lshl_add_u64 v[220:221], s[18:19], 0, v[134:135]
	s_mov_b32 m0, s38
	s_nop 0
	global_load_lds_dwordx4 v[220:221], off
	v_lshl_add_u64 v[220:221], s[18:19], 0, v[132:133]
	s_mov_b32 m0, s39
	s_nop 0
	global_load_lds_dwordx4 v[220:221], off
	s_waitcnt vmcnt(8)
	s_waitcnt lgkmcnt(0)
	s_barrier
	s_setprio 1
	s_waitcnt lgkmcnt(0)
	v_mfma_f32_16x16x32_bf16 v[62:65], v[144:147], v[176:179], 0
	v_mfma_f32_16x16x32_bf16 v[58:61], v[152:155], v[176:179], 0
	v_mfma_f32_16x16x32_bf16 v[54:57], v[144:147], v[184:187], 0
	v_mfma_f32_16x16x32_bf16 v[50:53], v[152:155], v[184:187], 0
	v_mfma_f32_16x16x32_bf16 v[38:41], v[144:147], v[192:195], 0
	v_mfma_f32_16x16x32_bf16 v[34:37], v[152:155], v[192:195], 0
	v_mfma_f32_16x16x32_bf16 v[22:25], v[144:147], v[200:203], 0
	v_mfma_f32_16x16x32_bf16 v[18:21], v[152:155], v[200:203], 0
	v_mfma_f32_16x16x32_bf16 v[62:65], v[148:151], v[180:183], v[62:65]
	v_mfma_f32_16x16x32_bf16 v[58:61], v[156:159], v[180:183], v[58:61]
	v_mfma_f32_16x16x32_bf16 v[54:57], v[148:151], v[188:191], v[54:57]
	v_mfma_f32_16x16x32_bf16 v[50:53], v[156:159], v[188:191], v[50:53]
	v_mfma_f32_16x16x32_bf16 v[38:41], v[148:151], v[196:199], v[38:41]
	v_mfma_f32_16x16x32_bf16 v[34:37], v[156:159], v[196:199], v[34:37]
	v_mfma_f32_16x16x32_bf16 v[22:25], v[148:151], v[204:207], v[22:25]
	v_mfma_f32_16x16x32_bf16 v[18:21], v[156:159], v[204:207], v[18:21]
	s_setprio 0
	s_setprio 1
	v_mfma_f32_16x16x32_bf16 v[46:49], v[160:163], v[176:179], 0
	v_mfma_f32_16x16x32_bf16 v[42:45], v[168:171], v[176:179], 0
	v_mfma_f32_16x16x32_bf16 v[30:33], v[160:163], v[184:187], 0
	v_mfma_f32_16x16x32_bf16 v[26:29], v[168:171], v[184:187], 0
	v_mfma_f32_16x16x32_bf16 v[14:17], v[160:163], v[192:195], 0
	v_mfma_f32_16x16x32_bf16 v[10:13], v[168:171], v[192:195], 0
	v_mfma_f32_16x16x32_bf16 v[6:9], v[160:163], v[200:203], 0
	v_mfma_f32_16x16x32_bf16 v[2:5], v[168:171], v[200:203], 0
	v_mfma_f32_16x16x32_bf16 v[46:49], v[164:167], v[180:183], v[46:49]
	v_mfma_f32_16x16x32_bf16 v[42:45], v[172:175], v[180:183], v[42:45]
	v_mfma_f32_16x16x32_bf16 v[30:33], v[164:167], v[188:191], v[30:33]
	v_mfma_f32_16x16x32_bf16 v[26:29], v[172:175], v[188:191], v[26:29]
	v_mfma_f32_16x16x32_bf16 v[14:17], v[164:167], v[196:199], v[14:17]
	v_mfma_f32_16x16x32_bf16 v[10:13], v[172:175], v[196:199], v[10:13]
	v_mfma_f32_16x16x32_bf16 v[6:9], v[164:167], v[204:207], v[6:9]
	v_mfma_f32_16x16x32_bf16 v[2:5], v[172:175], v[204:207], v[2:5]
	s_setprio 0
	s_barrier
	s_add_i32 s51, 0, 0x18000
	s_add_i32 s52, 0, 0x1c000
	v_add_u32_e32 v156, s51, v140
	v_add_u32_e32 v172, s52, v140
	ds_read_b128 v[144:147], v156
	ds_read_b128 v[148:151], v156 offset:1024
	ds_read_b128 v[152:155], v156 offset:2048
	ds_read_b128 v[156:159], v156 offset:3072
	ds_read_b128 v[160:163], v172
	ds_read_b128 v[164:167], v172 offset:1024
	ds_read_b128 v[168:171], v172 offset:2048
	ds_read_b128 v[172:175], v172 offset:3072
	s_add_u32 s18, s18, 0x4000
	s_addc_u32 s19, s19, 0
	s_mov_b32 m0, s40
	v_lshl_add_u64 v[220:221], s[18:19], 0, v[134:135]
	ds_read_b128 v[176:179], v143 offset:32768
	ds_read_b128 v[180:183], v143 offset:33792
	ds_read_b128 v[184:187], v143 offset:34816
	ds_read_b128 v[188:191], v143 offset:35840
	ds_read_b128 v[192:195], v143 offset:36864
	ds_read_b128 v[196:199], v143 offset:37888
	ds_read_b128 v[200:203], v143 offset:38912
	ds_read_b128 v[204:207], v143 offset:39936
	global_load_lds_dwordx4 v[220:221], off
	v_lshl_add_u64 v[220:221], s[18:19], 0, v[132:133]
	s_mov_b32 m0, s41
	s_nop 0
	global_load_lds_dwordx4 v[220:221], off
	s_waitcnt vmcnt(8)
	s_waitcnt lgkmcnt(0)
	s_barrier
	s_setprio 1
	s_waitcnt lgkmcnt(0)
	v_mfma_f32_16x16x32_bf16 v[126:129], v[144:147], v[176:179], v[126:129]
	v_mfma_f32_16x16x32_bf16 v[122:125], v[152:155], v[176:179], v[122:125]
	v_mfma_f32_16x16x32_bf16 v[118:121], v[144:147], v[184:187], v[118:121]
	v_mfma_f32_16x16x32_bf16 v[114:117], v[152:155], v[184:187], v[114:117]
	v_mfma_f32_16x16x32_bf16 v[102:105], v[144:147], v[192:195], v[102:105]
	v_mfma_f32_16x16x32_bf16 v[98:101], v[152:155], v[192:195], v[98:101]
	v_mfma_f32_16x16x32_bf16 v[86:89], v[144:147], v[200:203], v[86:89]
	v_mfma_f32_16x16x32_bf16 v[82:85], v[152:155], v[200:203], v[82:85]
	v_mfma_f32_16x16x32_bf16 v[126:129], v[148:151], v[180:183], v[126:129]
	v_mfma_f32_16x16x32_bf16 v[122:125], v[156:159], v[180:183], v[122:125]
	v_mfma_f32_16x16x32_bf16 v[118:121], v[148:151], v[188:191], v[118:121]
	v_mfma_f32_16x16x32_bf16 v[114:117], v[156:159], v[188:191], v[114:117]
	v_mfma_f32_16x16x32_bf16 v[102:105], v[148:151], v[196:199], v[102:105]
	v_mfma_f32_16x16x32_bf16 v[98:101], v[156:159], v[196:199], v[98:101]
	v_mfma_f32_16x16x32_bf16 v[86:89], v[148:151], v[204:207], v[86:89]
	v_mfma_f32_16x16x32_bf16 v[82:85], v[156:159], v[204:207], v[82:85]
	s_setprio 0
	s_setprio 1
	v_mfma_f32_16x16x32_bf16 v[110:113], v[160:163], v[176:179], v[110:113]
	v_mfma_f32_16x16x32_bf16 v[106:109], v[168:171], v[176:179], v[106:109]
	v_mfma_f32_16x16x32_bf16 v[94:97], v[160:163], v[184:187], v[94:97]
	v_mfma_f32_16x16x32_bf16 v[90:93], v[168:171], v[184:187], v[90:93]
	v_mfma_f32_16x16x32_bf16 v[78:81], v[160:163], v[192:195], v[78:81]
	v_mfma_f32_16x16x32_bf16 v[74:77], v[168:171], v[192:195], v[74:77]
	v_mfma_f32_16x16x32_bf16 v[70:73], v[160:163], v[200:203], v[70:73]
	v_mfma_f32_16x16x32_bf16 v[66:69], v[168:171], v[200:203], v[66:69]
	v_mfma_f32_16x16x32_bf16 v[110:113], v[164:167], v[180:183], v[110:113]
	v_mfma_f32_16x16x32_bf16 v[106:109], v[172:175], v[180:183], v[106:109]
	v_mfma_f32_16x16x32_bf16 v[94:97], v[164:167], v[188:191], v[94:97]
	v_mfma_f32_16x16x32_bf16 v[90:93], v[172:175], v[188:191], v[90:93]
	v_mfma_f32_16x16x32_bf16 v[78:81], v[164:167], v[196:199], v[78:81]
	v_mfma_f32_16x16x32_bf16 v[74:77], v[172:175], v[196:199], v[74:77]
	v_mfma_f32_16x16x32_bf16 v[70:73], v[164:167], v[204:207], v[70:73]
	v_mfma_f32_16x16x32_bf16 v[66:69], v[172:175], v[204:207], v[66:69]
	s_setprio 0
	s_barrier
	s_add_i32 s18, s51, s24
	v_lshl_add_u64 v[208:209], v[208:209], 0, s[2:3]
	s_mov_b32 m0, s18
	ds_read_b128 v[176:179], v143 offset:49152
	ds_read_b128 v[180:183], v143 offset:50176
	ds_read_b128 v[184:187], v143 offset:51200
	ds_read_b128 v[188:191], v143 offset:52224
	ds_read_b128 v[192:195], v143 offset:53248
	ds_read_b128 v[196:199], v143 offset:54272
	ds_read_b128 v[200:203], v143 offset:55296
	ds_read_b128 v[204:207], v143 offset:56320
	global_load_lds_dwordx4 v[208:209], off
	s_add_i32 m0, s18, 0x2000
	s_add_u32 s16, s16, 0x164080
	v_lshl_add_u64 v[208:209], v[216:217], 0, s[2:3]
	s_addc_u32 s17, s17, 0
	s_add_i32 s18, s52, s24
	global_load_lds_dwordx4 v[208:209], off
	v_lshl_add_u64 v[208:209], s[16:17], 0, v[0:1]
	s_mov_b32 m0, s18
	s_nop 0
	global_load_lds_dwordx4 v[208:209], off
	v_lshl_add_u64 v[208:209], s[16:17], 0, v[130:131]
	s_add_i32 m0, s18, 0x2000
	s_nop 0
	global_load_lds_dwordx4 v[208:209], off
	v_lshl_add_u64 v[208:209], s[14:15], 0, v[134:135]
	s_mov_b32 m0, s42
	s_nop 0
	global_load_lds_dwordx4 v[208:209], off
	v_lshl_add_u64 v[208:209], s[14:15], 0, v[132:133]
	s_mov_b32 m0, s43
	s_nop 0
	global_load_lds_dwordx4 v[208:209], off
	s_waitcnt vmcnt(8)
	s_waitcnt lgkmcnt(0)
	s_barrier
	s_setprio 1
	s_waitcnt lgkmcnt(0)
	v_mfma_f32_16x16x32_bf16 v[62:65], v[144:147], v[176:179], v[62:65]
	v_mfma_f32_16x16x32_bf16 v[58:61], v[152:155], v[176:179], v[58:61]
	v_mfma_f32_16x16x32_bf16 v[54:57], v[144:147], v[184:187], v[54:57]
	v_mfma_f32_16x16x32_bf16 v[50:53], v[152:155], v[184:187], v[50:53]
	v_mfma_f32_16x16x32_bf16 v[38:41], v[144:147], v[192:195], v[38:41]
	v_mfma_f32_16x16x32_bf16 v[34:37], v[152:155], v[192:195], v[34:37]
	v_mfma_f32_16x16x32_bf16 v[22:25], v[144:147], v[200:203], v[22:25]
	v_mfma_f32_16x16x32_bf16 v[18:21], v[152:155], v[200:203], v[18:21]
	v_mfma_f32_16x16x32_bf16 v[62:65], v[148:151], v[180:183], v[62:65]
	v_mfma_f32_16x16x32_bf16 v[58:61], v[156:159], v[180:183], v[58:61]
	v_mfma_f32_16x16x32_bf16 v[54:57], v[148:151], v[188:191], v[54:57]
	v_mfma_f32_16x16x32_bf16 v[50:53], v[156:159], v[188:191], v[50:53]
	v_mfma_f32_16x16x32_bf16 v[38:41], v[148:151], v[196:199], v[38:41]
	v_mfma_f32_16x16x32_bf16 v[34:37], v[156:159], v[196:199], v[34:37]
	v_mfma_f32_16x16x32_bf16 v[22:25], v[148:151], v[204:207], v[22:25]
	v_mfma_f32_16x16x32_bf16 v[18:21], v[156:159], v[204:207], v[18:21]
	s_setprio 0
	s_setprio 1
	v_mfma_f32_16x16x32_bf16 v[46:49], v[160:163], v[176:179], v[46:49]
	v_mfma_f32_16x16x32_bf16 v[42:45], v[168:171], v[176:179], v[42:45]
	v_mfma_f32_16x16x32_bf16 v[30:33], v[160:163], v[184:187], v[30:33]
	v_mfma_f32_16x16x32_bf16 v[26:29], v[168:171], v[184:187], v[26:29]
	v_mfma_f32_16x16x32_bf16 v[14:17], v[160:163], v[192:195], v[14:17]
	v_mfma_f32_16x16x32_bf16 v[10:13], v[168:171], v[192:195], v[10:13]
	v_mfma_f32_16x16x32_bf16 v[6:9], v[160:163], v[200:203], v[6:9]
	v_mfma_f32_16x16x32_bf16 v[2:5], v[168:171], v[200:203], v[2:5]
	v_mfma_f32_16x16x32_bf16 v[46:49], v[164:167], v[180:183], v[46:49]
	v_mfma_f32_16x16x32_bf16 v[42:45], v[172:175], v[180:183], v[42:45]
	v_mfma_f32_16x16x32_bf16 v[30:33], v[164:167], v[188:191], v[30:33]
	v_mfma_f32_16x16x32_bf16 v[26:29], v[172:175], v[188:191], v[26:29]
	v_mfma_f32_16x16x32_bf16 v[14:17], v[164:167], v[196:199], v[14:17]
	v_mfma_f32_16x16x32_bf16 v[10:13], v[172:175], v[196:199], v[10:13]
	v_mfma_f32_16x16x32_bf16 v[6:9], v[164:167], v[204:207], v[6:9]
	v_mfma_f32_16x16x32_bf16 v[2:5], v[172:175], v[204:207], v[2:5]
	s_setprio 0
	s_barrier
	s_add_i32 s50, s50, 2
	s_add_u32 s36, s36, 0x100
	s_addc_u32 s37, s37, 0
	s_add_u32 s12, s12, 0x10000
	s_addc_u32 s13, s13, 0
	s_cmp_gt_u32 s50, 19
	s_cbranch_scc1 .Lpeel_done_6
.LBB0_2017:
	s_add_u32 s14, s12, 0x4000
	s_addc_u32 s15, s13, 0
	s_cmp_eq_u32 s50, 18
	s_cselect_b32 s18, s8, s14
	s_cselect_b32 s19, s9, s15
	s_cselect_b32 s16, s10, s36
	s_cselect_b32 s17, s11, s37
	s_add_u32 s14, s18, 0x8000
	s_addc_u32 s15, s19, 0
	s_add_i32 s51, 0, 0x10000
	s_add_i32 s54, 0, 0x14000
	v_add_u32_e32 v156, s51, v140
	v_add_u32_e32 v172, s54, v140
	ds_read_b128 v[144:147], v156
	ds_read_b128 v[148:151], v156 offset:1024
	ds_read_b128 v[152:155], v156 offset:2048
	ds_read_b128 v[156:159], v156 offset:3072
	ds_read_b128 v[160:163], v172
	ds_read_b128 v[164:167], v172 offset:1024
	ds_read_b128 v[168:171], v172 offset:2048
	ds_read_b128 v[172:175], v172 offset:3072
	v_lshl_add_u64 v[208:209], s[12:13], 0, v[136:137]
	s_add_i32 m0, s38, 0xc000
	ds_read_b128 v[176:179], v143
	ds_read_b128 v[180:183], v143 offset:1024
	ds_read_b128 v[184:187], v143 offset:2048
	ds_read_b128 v[188:191], v143 offset:3072
	ds_read_b128 v[192:195], v143 offset:4096
	ds_read_b128 v[196:199], v143 offset:5120
	ds_read_b128 v[200:203], v143 offset:6144
	ds_read_b128 v[204:207], v143 offset:7168
	global_load_lds_dwordx4 v[208:209], off
	v_lshl_add_u64 v[208:209], s[12:13], 0, v[138:139]
	s_add_i32 m0, s38, 0xe000
	s_nop 0
	global_load_lds_dwordx4 v[208:209], off
	s_waitcnt vmcnt(8)
	s_waitcnt lgkmcnt(0)
	s_barrier
	s_setprio 1
	s_waitcnt lgkmcnt(0)
	v_mfma_f32_16x16x32_bf16 v[126:129], v[144:147], v[176:179], v[126:129]
	v_mfma_f32_16x16x32_bf16 v[122:125], v[152:155], v[176:179], v[122:125]
	v_mfma_f32_16x16x32_bf16 v[118:121], v[144:147], v[184:187], v[118:121]
	v_mfma_f32_16x16x32_bf16 v[114:117], v[152:155], v[184:187], v[114:117]
	v_mfma_f32_16x16x32_bf16 v[102:105], v[144:147], v[192:195], v[102:105]
	v_mfma_f32_16x16x32_bf16 v[98:101], v[152:155], v[192:195], v[98:101]
	v_mfma_f32_16x16x32_bf16 v[86:89], v[144:147], v[200:203], v[86:89]
	v_mfma_f32_16x16x32_bf16 v[82:85], v[152:155], v[200:203], v[82:85]
	v_mfma_f32_16x16x32_bf16 v[126:129], v[148:151], v[180:183], v[126:129]
	v_mfma_f32_16x16x32_bf16 v[122:125], v[156:159], v[180:183], v[122:125]
	v_mfma_f32_16x16x32_bf16 v[118:121], v[148:151], v[188:191], v[118:121]
	v_mfma_f32_16x16x32_bf16 v[114:117], v[156:159], v[188:191], v[114:117]
	v_mfma_f32_16x16x32_bf16 v[102:105], v[148:151], v[196:199], v[102:105]
	v_mfma_f32_16x16x32_bf16 v[98:101], v[156:159], v[196:199], v[98:101]
	v_mfma_f32_16x16x32_bf16 v[86:89], v[148:151], v[204:207], v[86:89]
	v_mfma_f32_16x16x32_bf16 v[82:85], v[156:159], v[204:207], v[82:85]
	s_setprio 0
	s_setprio 1
	v_mfma_f32_16x16x32_bf16 v[110:113], v[160:163], v[176:179], v[110:113]
	v_mfma_f32_16x16x32_bf16 v[106:109], v[168:171], v[176:179], v[106:109]
	v_mfma_f32_16x16x32_bf16 v[94:97], v[160:163], v[184:187], v[94:97]
	v_mfma_f32_16x16x32_bf16 v[90:93], v[168:171], v[184:187], v[90:93]
	v_mfma_f32_16x16x32_bf16 v[78:81], v[160:163], v[192:195], v[78:81]
	v_mfma_f32_16x16x32_bf16 v[74:77], v[168:171], v[192:195], v[74:77]
	v_mfma_f32_16x16x32_bf16 v[70:73], v[160:163], v[200:203], v[70:73]
	v_mfma_f32_16x16x32_bf16 v[66:69], v[168:171], v[200:203], v[66:69]
	v_mfma_f32_16x16x32_bf16 v[110:113], v[164:167], v[180:183], v[110:113]
	v_mfma_f32_16x16x32_bf16 v[106:109], v[172:175], v[180:183], v[106:109]
	v_mfma_f32_16x16x32_bf16 v[94:97], v[164:167], v[188:191], v[94:97]
	v_mfma_f32_16x16x32_bf16 v[90:93], v[172:175], v[188:191], v[90:93]
	v_mfma_f32_16x16x32_bf16 v[78:81], v[164:167], v[196:199], v[78:81]
	v_mfma_f32_16x16x32_bf16 v[74:77], v[172:175], v[196:199], v[74:77]
	v_mfma_f32_16x16x32_bf16 v[70:73], v[164:167], v[204:207], v[70:73]
	v_mfma_f32_16x16x32_bf16 v[66:69], v[172:175], v[204:207], v[66:69]
	s_setprio 0
	s_barrier
	s_add_i32 s51, s51, s24
	v_lshl_add_u64 v[208:209], s[16:17], 0, v[0:1]
	s_mov_b32 m0, s51
	ds_read_b128 v[176:179], v143 offset:16384
	ds_read_b128 v[180:183], v143 offset:17408
	ds_read_b128 v[184:187], v143 offset:18432
	ds_read_b128 v[188:191], v143 offset:19456
	ds_read_b128 v[192:195], v143 offset:20480
	ds_read_b128 v[196:199], v143 offset:21504
	ds_read_b128 v[200:203], v143 offset:22528
	ds_read_b128 v[204:207], v143 offset:23552
	global_load_lds_dwordx4 v[208:209], off
	s_add_i32 m0, s51, 0x2000
	s_add_u32 s52, s16, 0x164000
	v_lshl_add_u64 v[216:217], s[16:17], 0, v[130:131]
	s_addc_u32 s53, s17, 0
	s_add_i32 s51, s54, s24
	global_load_lds_dwordx4 v[216:217], off
	v_lshl_add_u64 v[220:221], s[52:53], 0, v[0:1]
	s_mov_b32 m0, s51
	s_nop 0
	global_load_lds_dwordx4 v[220:221], off
	v_lshl_add_u64 v[220:221], s[52:53], 0, v[130:131]
	s_add_i32 m0, s51, 0x2000
	s_nop 0
	global_load_lds_dwordx4 v[220:221], off
	v_lshl_add_u64 v[220:221], s[18:19], 0, v[134:135]
	s_mov_b32 m0, s38
	s_nop 0
	global_load_lds_dwordx4 v[220:221], off
	v_lshl_add_u64 v[220:221], s[18:19], 0, v[132:133]
	s_mov_b32 m0, s39
	s_nop 0
	global_load_lds_dwordx4 v[220:221], off
	s_waitcnt vmcnt(8)
	s_waitcnt lgkmcnt(0)
	s_barrier
	s_setprio 1
	s_waitcnt lgkmcnt(0)
	v_mfma_f32_16x16x32_bf16 v[62:65], v[144:147], v[176:179], v[62:65]
	v_mfma_f32_16x16x32_bf16 v[58:61], v[152:155], v[176:179], v[58:61]
	v_mfma_f32_16x16x32_bf16 v[54:57], v[144:147], v[184:187], v[54:57]
	v_mfma_f32_16x16x32_bf16 v[50:53], v[152:155], v[184:187], v[50:53]
	v_mfma_f32_16x16x32_bf16 v[38:41], v[144:147], v[192:195], v[38:41]
	v_mfma_f32_16x16x32_bf16 v[34:37], v[152:155], v[192:195], v[34:37]
	v_mfma_f32_16x16x32_bf16 v[22:25], v[144:147], v[200:203], v[22:25]
	v_mfma_f32_16x16x32_bf16 v[18:21], v[152:155], v[200:203], v[18:21]
	v_mfma_f32_16x16x32_bf16 v[62:65], v[148:151], v[180:183], v[62:65]
	v_mfma_f32_16x16x32_bf16 v[58:61], v[156:159], v[180:183], v[58:61]
	v_mfma_f32_16x16x32_bf16 v[54:57], v[148:151], v[188:191], v[54:57]
	v_mfma_f32_16x16x32_bf16 v[50:53], v[156:159], v[188:191], v[50:53]
	v_mfma_f32_16x16x32_bf16 v[38:41], v[148:151], v[196:199], v[38:41]
	v_mfma_f32_16x16x32_bf16 v[34:37], v[156:159], v[196:199], v[34:37]
	v_mfma_f32_16x16x32_bf16 v[22:25], v[148:151], v[204:207], v[22:25]
	v_mfma_f32_16x16x32_bf16 v[18:21], v[156:159], v[204:207], v[18:21]
	s_setprio 0
	s_setprio 1
	v_mfma_f32_16x16x32_bf16 v[46:49], v[160:163], v[176:179], v[46:49]
	v_mfma_f32_16x16x32_bf16 v[42:45], v[168:171], v[176:179], v[42:45]
	v_mfma_f32_16x16x32_bf16 v[30:33], v[160:163], v[184:187], v[30:33]
	v_mfma_f32_16x16x32_bf16 v[26:29], v[168:171], v[184:187], v[26:29]
	v_mfma_f32_16x16x32_bf16 v[14:17], v[160:163], v[192:195], v[14:17]
	v_mfma_f32_16x16x32_bf16 v[10:13], v[168:171], v[192:195], v[10:13]
	v_mfma_f32_16x16x32_bf16 v[6:9], v[160:163], v[200:203], v[6:9]
	v_mfma_f32_16x16x32_bf16 v[2:5], v[168:171], v[200:203], v[2:5]
	v_mfma_f32_16x16x32_bf16 v[46:49], v[164:167], v[180:183], v[46:49]
	v_mfma_f32_16x16x32_bf16 v[42:45], v[172:175], v[180:183], v[42:45]
	v_mfma_f32_16x16x32_bf16 v[30:33], v[164:167], v[188:191], v[30:33]
	v_mfma_f32_16x16x32_bf16 v[26:29], v[172:175], v[188:191], v[26:29]
	v_mfma_f32_16x16x32_bf16 v[14:17], v[164:167], v[196:199], v[14:17]
	v_mfma_f32_16x16x32_bf16 v[10:13], v[172:175], v[196:199], v[10:13]
	v_mfma_f32_16x16x32_bf16 v[6:9], v[164:167], v[204:207], v[6:9]
	v_mfma_f32_16x16x32_bf16 v[2:5], v[172:175], v[204:207], v[2:5]
	s_setprio 0
	s_barrier
	s_add_i32 s51, 0, 0x18000
	s_add_i32 s52, 0, 0x1c000
	v_add_u32_e32 v156, s51, v140
	v_add_u32_e32 v172, s52, v140
	ds_read_b128 v[144:147], v156
	ds_read_b128 v[148:151], v156 offset:1024
	ds_read_b128 v[152:155], v156 offset:2048
	ds_read_b128 v[156:159], v156 offset:3072
	ds_read_b128 v[160:163], v172
	ds_read_b128 v[164:167], v172 offset:1024
	ds_read_b128 v[168:171], v172 offset:2048
	ds_read_b128 v[172:175], v172 offset:3072
	s_add_u32 s18, s18, 0x4000
	s_addc_u32 s19, s19, 0
	s_mov_b32 m0, s40
	v_lshl_add_u64 v[220:221], s[18:19], 0, v[134:135]
	ds_read_b128 v[176:179], v143 offset:32768
	ds_read_b128 v[180:183], v143 offset:33792
	ds_read_b128 v[184:187], v143 offset:34816
	ds_read_b128 v[188:191], v143 offset:35840
	ds_read_b128 v[192:195], v143 offset:36864
	ds_read_b128 v[196:199], v143 offset:37888
	ds_read_b128 v[200:203], v143 offset:38912
	ds_read_b128 v[204:207], v143 offset:39936
	global_load_lds_dwordx4 v[220:221], off
	v_lshl_add_u64 v[220:221], s[18:19], 0, v[132:133]
	s_mov_b32 m0, s41
	s_nop 0
	global_load_lds_dwordx4 v[220:221], off
	s_waitcnt vmcnt(8)
	s_waitcnt lgkmcnt(0)
	s_barrier
	s_setprio 1
	s_waitcnt lgkmcnt(0)
	v_mfma_f32_16x16x32_bf16 v[126:129], v[144:147], v[176:179], v[126:129]
	v_mfma_f32_16x16x32_bf16 v[122:125], v[152:155], v[176:179], v[122:125]
	v_mfma_f32_16x16x32_bf16 v[118:121], v[144:147], v[184:187], v[118:121]
	v_mfma_f32_16x16x32_bf16 v[114:117], v[152:155], v[184:187], v[114:117]
	v_mfma_f32_16x16x32_bf16 v[102:105], v[144:147], v[192:195], v[102:105]
	v_mfma_f32_16x16x32_bf16 v[98:101], v[152:155], v[192:195], v[98:101]
	v_mfma_f32_16x16x32_bf16 v[86:89], v[144:147], v[200:203], v[86:89]
	v_mfma_f32_16x16x32_bf16 v[82:85], v[152:155], v[200:203], v[82:85]
	v_mfma_f32_16x16x32_bf16 v[126:129], v[148:151], v[180:183], v[126:129]
	v_mfma_f32_16x16x32_bf16 v[122:125], v[156:159], v[180:183], v[122:125]
	v_mfma_f32_16x16x32_bf16 v[118:121], v[148:151], v[188:191], v[118:121]
	v_mfma_f32_16x16x32_bf16 v[114:117], v[156:159], v[188:191], v[114:117]
	v_mfma_f32_16x16x32_bf16 v[102:105], v[148:151], v[196:199], v[102:105]
	v_mfma_f32_16x16x32_bf16 v[98:101], v[156:159], v[196:199], v[98:101]
	v_mfma_f32_16x16x32_bf16 v[86:89], v[148:151], v[204:207], v[86:89]
	v_mfma_f32_16x16x32_bf16 v[82:85], v[156:159], v[204:207], v[82:85]
	s_setprio 0
	s_setprio 1
	v_mfma_f32_16x16x32_bf16 v[110:113], v[160:163], v[176:179], v[110:113]
	v_mfma_f32_16x16x32_bf16 v[106:109], v[168:171], v[176:179], v[106:109]
	v_mfma_f32_16x16x32_bf16 v[94:97], v[160:163], v[184:187], v[94:97]
	v_mfma_f32_16x16x32_bf16 v[90:93], v[168:171], v[184:187], v[90:93]
	v_mfma_f32_16x16x32_bf16 v[78:81], v[160:163], v[192:195], v[78:81]
	v_mfma_f32_16x16x32_bf16 v[74:77], v[168:171], v[192:195], v[74:77]
	v_mfma_f32_16x16x32_bf16 v[70:73], v[160:163], v[200:203], v[70:73]
	v_mfma_f32_16x16x32_bf16 v[66:69], v[168:171], v[200:203], v[66:69]
	v_mfma_f32_16x16x32_bf16 v[110:113], v[164:167], v[180:183], v[110:113]
	v_mfma_f32_16x16x32_bf16 v[106:109], v[172:175], v[180:183], v[106:109]
	v_mfma_f32_16x16x32_bf16 v[94:97], v[164:167], v[188:191], v[94:97]
	v_mfma_f32_16x16x32_bf16 v[90:93], v[172:175], v[188:191], v[90:93]
	v_mfma_f32_16x16x32_bf16 v[78:81], v[164:167], v[196:199], v[78:81]
	v_mfma_f32_16x16x32_bf16 v[74:77], v[172:175], v[196:199], v[74:77]
	v_mfma_f32_16x16x32_bf16 v[70:73], v[164:167], v[204:207], v[70:73]
	v_mfma_f32_16x16x32_bf16 v[66:69], v[172:175], v[204:207], v[66:69]
	s_setprio 0
	s_barrier
	s_add_i32 s18, s51, s24
	v_lshl_add_u64 v[208:209], v[208:209], 0, s[2:3]
	s_mov_b32 m0, s18
	ds_read_b128 v[176:179], v143 offset:49152
	ds_read_b128 v[180:183], v143 offset:50176
	ds_read_b128 v[184:187], v143 offset:51200
	ds_read_b128 v[188:191], v143 offset:52224
	ds_read_b128 v[192:195], v143 offset:53248
	ds_read_b128 v[196:199], v143 offset:54272
	ds_read_b128 v[200:203], v143 offset:55296
	ds_read_b128 v[204:207], v143 offset:56320
	global_load_lds_dwordx4 v[208:209], off
	s_add_i32 m0, s18, 0x2000
	s_add_u32 s16, s16, 0x164080
	v_lshl_add_u64 v[208:209], v[216:217], 0, s[2:3]
	s_addc_u32 s17, s17, 0
	s_add_i32 s18, s52, s24
	global_load_lds_dwordx4 v[208:209], off
	v_lshl_add_u64 v[208:209], s[16:17], 0, v[0:1]
	s_mov_b32 m0, s18
	s_nop 0
	global_load_lds_dwordx4 v[208:209], off
	v_lshl_add_u64 v[208:209], s[16:17], 0, v[130:131]
	s_add_i32 m0, s18, 0x2000
	s_nop 0
	global_load_lds_dwordx4 v[208:209], off
	v_lshl_add_u64 v[208:209], s[14:15], 0, v[134:135]
	s_mov_b32 m0, s42
	s_nop 0
	global_load_lds_dwordx4 v[208:209], off
	v_lshl_add_u64 v[208:209], s[14:15], 0, v[132:133]
	s_mov_b32 m0, s43
	s_nop 0
	global_load_lds_dwordx4 v[208:209], off
	s_waitcnt vmcnt(8)
	s_waitcnt lgkmcnt(0)
	s_barrier
	s_setprio 1
	s_waitcnt lgkmcnt(0)
	v_mfma_f32_16x16x32_bf16 v[62:65], v[144:147], v[176:179], v[62:65]
	v_mfma_f32_16x16x32_bf16 v[58:61], v[152:155], v[176:179], v[58:61]
	v_mfma_f32_16x16x32_bf16 v[54:57], v[144:147], v[184:187], v[54:57]
	v_mfma_f32_16x16x32_bf16 v[50:53], v[152:155], v[184:187], v[50:53]
	v_mfma_f32_16x16x32_bf16 v[38:41], v[144:147], v[192:195], v[38:41]
	v_mfma_f32_16x16x32_bf16 v[34:37], v[152:155], v[192:195], v[34:37]
	v_mfma_f32_16x16x32_bf16 v[22:25], v[144:147], v[200:203], v[22:25]
	v_mfma_f32_16x16x32_bf16 v[18:21], v[152:155], v[200:203], v[18:21]
	v_mfma_f32_16x16x32_bf16 v[62:65], v[148:151], v[180:183], v[62:65]
	v_mfma_f32_16x16x32_bf16 v[58:61], v[156:159], v[180:183], v[58:61]
	v_mfma_f32_16x16x32_bf16 v[54:57], v[148:151], v[188:191], v[54:57]
	v_mfma_f32_16x16x32_bf16 v[50:53], v[156:159], v[188:191], v[50:53]
	v_mfma_f32_16x16x32_bf16 v[38:41], v[148:151], v[196:199], v[38:41]
	v_mfma_f32_16x16x32_bf16 v[34:37], v[156:159], v[196:199], v[34:37]
	v_mfma_f32_16x16x32_bf16 v[22:25], v[148:151], v[204:207], v[22:25]
	v_mfma_f32_16x16x32_bf16 v[18:21], v[156:159], v[204:207], v[18:21]
	s_setprio 0
	s_setprio 1
	v_mfma_f32_16x16x32_bf16 v[46:49], v[160:163], v[176:179], v[46:49]
	v_mfma_f32_16x16x32_bf16 v[42:45], v[168:171], v[176:179], v[42:45]
	v_mfma_f32_16x16x32_bf16 v[30:33], v[160:163], v[184:187], v[30:33]
	v_mfma_f32_16x16x32_bf16 v[26:29], v[168:171], v[184:187], v[26:29]
	v_mfma_f32_16x16x32_bf16 v[14:17], v[160:163], v[192:195], v[14:17]
	v_mfma_f32_16x16x32_bf16 v[10:13], v[168:171], v[192:195], v[10:13]
	v_mfma_f32_16x16x32_bf16 v[6:9], v[160:163], v[200:203], v[6:9]
	v_mfma_f32_16x16x32_bf16 v[2:5], v[168:171], v[200:203], v[2:5]
	v_mfma_f32_16x16x32_bf16 v[46:49], v[164:167], v[180:183], v[46:49]
	v_mfma_f32_16x16x32_bf16 v[42:45], v[172:175], v[180:183], v[42:45]
	v_mfma_f32_16x16x32_bf16 v[30:33], v[164:167], v[188:191], v[30:33]
	v_mfma_f32_16x16x32_bf16 v[26:29], v[172:175], v[188:191], v[26:29]
	v_mfma_f32_16x16x32_bf16 v[14:17], v[164:167], v[196:199], v[14:17]
	v_mfma_f32_16x16x32_bf16 v[10:13], v[172:175], v[196:199], v[10:13]
	v_mfma_f32_16x16x32_bf16 v[6:9], v[164:167], v[204:207], v[6:9]
	v_mfma_f32_16x16x32_bf16 v[2:5], v[172:175], v[204:207], v[2:5]
	s_setprio 0
	s_barrier
	s_add_i32 s50, s50, 2
	s_add_u32 s36, s36, 0x100
	s_addc_u32 s37, s37, 0
	s_add_u32 s12, s12, 0x10000
	s_addc_u32 s13, s13, 0
	s_cmp_gt_u32 s50, 19
	s_cbranch_scc0 .LBB0_2017
